# flash loops: K reads first, next-tile LDS-DMA issued after with SALU-computed bases; max-tree collapse; GEMM DMA spread; tile-boundary waits relaxed
# speedup vs baseline: 1.1455x; 1.0266x over previous
; __device__ __forceinline__ f32x4 zero4() { return (f32x4){0.f, 0.f, 0.f, 0.f}; }
; template <class Epi>
; __device__ __forceinline__ void gemm_tile(const bf16_t* __restrict__ A, const bf16_t* __restrict__ Bt, int K, int row0, int col0, const Epi& epi, char* smem,
;                                           bool prefetched, bool nvalid, int nrow0, int ncol0) {
;     ...
; #pragma unroll
;     for (int m = 0; m < 4; ++m)
; #pragma unroll
;         for (int n = 0; n < 4; ++n) acc[m][n] = zero4();
;     int soffA[4], soffB[4];
; #pragma unroll
;     for (int i = 0; i < 4; ++i) {
;         const int row = (w + 4 * i) * 8 + (lane >> 3), cp = lane & 7;
;         soffA[i] = row * K + (cp ^ ((row >> 1) & 7)) * 8;
;         soffB[i] = row * K + (cp ^ (((row >> 1) & 1) | (((row >> 3) & 1) << 1) | (((row >> 4) & 1) << 2))) * 8;
;     }
;     const bf16_t* pA = A + (size_t)row0 * K;
;     const bf16_t* pB = Bt + (size_t)col0 * K;
;     ...
;     int offA[4][2], offB[4][2];
; #pragma unroll
;     for (int m = 0; m < 4; ++m)
; #pragma unroll
;         for (int ks = 0; ks < 2; ++ks) { const int cx = ((ks * 4 + fq) ^ ((fr >> 1) & 7)) * 16;
;             offA[m][ks] = (wr * 64 + m * 16 + fr) * 128 + cx;
;             offB[m][ks] = TILE_B + (wc * 64 + (m >> 1) * 32 + 8 * (fr >> 2) + 4 * (m & 1) + (fr & 3)) * 128 + cx; }
;     if (prefetched) {
;         if (Epi::STAGED) asm volatile("s_waitcnt vmcnt(8)" ::: "memory");
;         else asm volatile("s_waitcnt vmcnt(0)" ::: "memory");
;     } else {
;         GLDS_STAGE(0, pA, pB, 0);
;         asm volatile("s_waitcnt vmcnt(0)" ::: "memory");
;     }
;     __syncthreads();
;     const int nk = K >> 6;
;     for (int kt = 0; kt < nk; ++kt) {
;         const int cur = kt & 1;
;         if (kt + 1 < nk) GLDS_STAGE(cur ^ 1, pA, pB, kt + 1);
.LBB0_153:
	v_mov_b32_e32 v0, 0
	v_lshl_add_u64 v[64:65], v[106:107], 0, s[0:1]
	v_lshl_add_u64 v[66:67], v[108:109], 0, s[0:1]
	v_lshl_add_u64 v[68:69], v[110:111], 0, s[0:1]
	v_lshl_add_u64 v[70:71], v[118:119], 0, s[0:1]
	v_lshl_add_u64 v[72:73], v[120:121], 0, s[8:9]
	v_lshl_add_u64 v[74:75], v[122:123], 0, s[8:9]
	v_lshl_add_u64 v[76:77], v[124:125], 0, s[8:9]
	v_lshl_add_u64 v[78:79], v[126:127], 0, s[8:9]
	s_mov_b32 s5, 0
	s_mov_b64 s[0:1], 0
	v_mov_b32_e32 v1, v0
	v_mov_b32_e32 v2, v0
	v_mov_b32_e32 v3, v0
	v_mov_b32_e32 v4, v0
	v_mov_b32_e32 v5, v0
	v_mov_b32_e32 v6, v0
	v_mov_b32_e32 v7, v0
	v_mov_b32_e32 v8, v0
	v_mov_b32_e32 v9, v0
	v_mov_b32_e32 v10, v0
	v_mov_b32_e32 v11, v0
	v_mov_b32_e32 v12, v0
	v_mov_b32_e32 v13, v0
	v_mov_b32_e32 v14, v0
	v_mov_b32_e32 v15, v0
	v_mov_b32_e32 v16, v0
	v_mov_b32_e32 v17, v0
	v_mov_b32_e32 v18, v0
	v_mov_b32_e32 v19, v0
	v_mov_b32_e32 v20, v0
	v_mov_b32_e32 v21, v0
	v_mov_b32_e32 v22, v0
	v_mov_b32_e32 v23, v0
	v_mov_b32_e32 v24, v0
	v_mov_b32_e32 v25, v0
	v_mov_b32_e32 v26, v0
	v_mov_b32_e32 v27, v0
	s_waitcnt vmcnt(0)
	v_mov_b32_e32 v28, v0
	v_mov_b32_e32 v29, v0
	v_mov_b32_e32 v30, v0
	v_mov_b32_e32 v31, v0
	v_mov_b32_e32 v32, v0
	v_mov_b32_e32 v33, v0
	v_mov_b32_e32 v34, v0
	v_mov_b32_e32 v35, v0
	v_mov_b32_e32 v36, v0
	v_mov_b32_e32 v37, v0
	v_mov_b32_e32 v38, v0
	v_mov_b32_e32 v39, v0
	v_mov_b32_e32 v40, v0
	v_mov_b32_e32 v41, v0
	v_mov_b32_e32 v42, v0
	v_mov_b32_e32 v43, v0
	v_mov_b32_e32 v44, v0
	v_mov_b32_e32 v45, v0
	v_mov_b32_e32 v46, v0
	v_mov_b32_e32 v47, v0
	v_mov_b32_e32 v48, v0
	v_mov_b32_e32 v49, v0
	v_mov_b32_e32 v50, v0
	v_mov_b32_e32 v51, v0
	v_mov_b32_e32 v52, v0
	v_mov_b32_e32 v53, v0
	v_mov_b32_e32 v54, v0
	v_mov_b32_e32 v55, v0
	v_mov_b32_e32 v56, v0
	v_mov_b32_e32 v57, v0
	v_mov_b32_e32 v58, v0
	v_mov_b32_e32 v59, v0
	v_mov_b32_e32 v60, v0
	v_mov_b32_e32 v61, v0
	v_mov_b32_e32 v62, v0
	v_mov_b32_e32 v63, v0
	s_waitcnt lgkmcnt(0)
	s_barrier
.LBB0_154:
	v_readfirstlane_b32 s98, v64
	v_readfirstlane_b32 s99, v65
	v_readfirstlane_b32 s10, v66
	v_readfirstlane_b32 s100, v72
	v_readfirstlane_b32 s101, v73
	v_readfirstlane_b32 s13, v149
	s_nop 3
	s_sub_u32 s14, s10, s98
	s_and_b32 s98, s98, 0xffffff80
	s_and_b32 s100, s100, 0xffffff80
	s_nop 1
	v_subrev_u32_e32 v254, s98, v64
	v_subrev_u32_e32 v255, s100, v72
	s_add_i32 s12, s13, 0x8000
	s_mov_b32 m0, s12
	s_nop 0
	global_load_lds_dwordx4 v254, s[98:99]
	s_add_i32 m0, s12, 0x1000
	s_add_u32 s10, s98, s14
	s_addc_u32 s11, s99, 0
	global_load_lds_dwordx4 v254, s[10:11]
	s_add_i32 m0, s12, 0x2000
	s_add_u32 s10, s10, s14
	s_addc_u32 s11, s11, 0
	global_load_lds_dwordx4 v254, s[10:11]
	ds_read_b128 v[182:185], v139
	ds_read_b128 v[64:67], v142 offset:16384
	ds_read_b128 v[68:71], v142 offset:16896
	ds_read_b128 v[72:75], v142 offset:20480
	ds_read_b128 v[76:79], v142 offset:20992
	ds_read_b128 v[186:189], v139 offset:2048
	ds_read_b128 v[246:249], v139 offset:4096
	ds_read_b128 v[250:253], v139 offset:6144
; __device__ __forceinline__ f32x4 mfma16(bf16x8 a, bf16x8 b, f32x4 c) { return __builtin_amdgcn_mfma_f32_16x16x32_bf16(a, b, c, 0, 0, 0); }
; template <class Epi>
; __device__ __forceinline__ void gemm_tile(const bf16_t* __restrict__ A, const bf16_t* __restrict__ Bt, int K, int row0, int col0, const Epi& epi, char* smem,
;                                           bool prefetched, bool nvalid, int nrow0, int ncol0) {
;     ...
;     for (int kt = 0; kt < nk; ++kt) {
;         const int cur = kt & 1;
;         if (kt + 1 < nk) GLDS_STAGE(cur ^ 1, pA, pB, kt + 1);
;         const char* cb = smem + cur * 2 * TILE_B;
; #pragma unroll
;         for (int ks = 0; ks < 2; ++ks) {
;             bf16x8 a[4], b[4];
; #pragma unroll
;             for (int m = 0; m < 4; ++m) a[m] = *(const bf16x8*)(cb + offA[m][ks]);
; #pragma unroll
;             for (int n = 0; n < 4; ++n) b[n] = *(const bf16x8*)(cb + offB[n][ks]);
; #pragma unroll
;             for (int m = 0; m < 4; ++m)
; #pragma unroll
;                 for (int n = 0; n < 4; ++n) acc[m][n] = mfma16(b[n], a[m], acc[m][n]);
;         }
;         asm volatile("s_waitcnt vmcnt(0)" ::: "memory");
;         __syncthreads();
.Lgk_loop_154:
	s_and_b32 s8, s5, 0x8000
	s_xor_b32 s9, s8, 0x8000
	v_or_b32_e32 v173, s8, v141
	v_add_u32_e32 v190, s8, v140
	s_waitcnt lgkmcnt(6)
	v_mfma_f32_16x16x32_bf16 v[0:3], v[64:67], v[182:185], v[0:3]
	ds_read_b128 v[80:83], v173 offset:16384
	s_add_i32 m0, s12, 0x3000
	s_add_u32 s10, s10, s14
	s_addc_u32 s11, s11, 0
	s_waitcnt lgkmcnt(6)
	v_mfma_f32_16x16x32_bf16 v[4:7], v[68:71], v[182:185], v[4:7]
	global_load_lds_dwordx4 v254, s[10:11]
	s_add_u32 s98, s98, 0x80
	s_addc_u32 s99, s99, 0
	ds_read_b128 v[128:131], v173 offset:16896
	s_waitcnt lgkmcnt(6)
	v_mfma_f32_16x16x32_bf16 v[8:11], v[72:75], v[182:185], v[8:11]
	ds_read_b128 v[174:177], v173 offset:20480
	s_waitcnt lgkmcnt(6)
	v_mfma_f32_16x16x32_bf16 v[12:15], v[76:79], v[182:185], v[12:15]
	ds_read_b128 v[178:181], v173 offset:20992
	ds_read_b128 v[182:185], v190
	s_add_i32 m0, s12, 0x4000
	s_nop 0
	s_waitcnt lgkmcnt(7)
	v_mfma_f32_16x16x32_bf16 v[16:19], v[64:67], v[186:189], v[16:19]
	global_load_lds_dwordx4 v255, s[100:101]
	v_mfma_f32_16x16x32_bf16 v[20:23], v[68:71], v[186:189], v[20:23]
	v_mfma_f32_16x16x32_bf16 v[24:27], v[72:75], v[186:189], v[24:27]
	s_add_i32 m0, s12, 0x5000
	s_add_u32 s10, s100, s14
	s_addc_u32 s11, s101, 0
	v_mfma_f32_16x16x32_bf16 v[28:31], v[76:79], v[186:189], v[28:31]
	global_load_lds_dwordx4 v255, s[10:11]
	ds_read_b128 v[186:189], v190 offset:2048
	s_waitcnt lgkmcnt(7)
	v_mfma_f32_16x16x32_bf16 v[32:35], v[64:67], v[246:249], v[32:35]
	v_mfma_f32_16x16x32_bf16 v[36:39], v[68:71], v[246:249], v[36:39]
	s_add_i32 m0, s12, 0x6000
	s_add_u32 s10, s10, s14
	s_addc_u32 s11, s11, 0
	v_mfma_f32_16x16x32_bf16 v[40:43], v[72:75], v[246:249], v[40:43]
	global_load_lds_dwordx4 v255, s[10:11]
	v_mfma_f32_16x16x32_bf16 v[44:47], v[76:79], v[246:249], v[44:47]
	ds_read_b128 v[246:249], v190 offset:4096
	s_waitcnt lgkmcnt(7)
	v_mfma_f32_16x16x32_bf16 v[48:51], v[64:67], v[250:253], v[48:51]
	s_add_i32 m0, s12, 0x7000
	s_add_u32 s10, s10, s14
	s_addc_u32 s11, s11, 0
	v_mfma_f32_16x16x32_bf16 v[52:55], v[68:71], v[250:253], v[52:55]
	global_load_lds_dwordx4 v255, s[10:11]
	s_add_u32 s100, s100, 0x80
	s_addc_u32 s101, s101, 0
	v_mfma_f32_16x16x32_bf16 v[56:59], v[72:75], v[250:253], v[56:59]
	v_mfma_f32_16x16x32_bf16 v[60:63], v[76:79], v[250:253], v[60:63]
	ds_read_b128 v[250:253], v190 offset:6144
	s_waitcnt lgkmcnt(3)
	v_mfma_f32_16x16x32_bf16 v[0:3], v[80:83], v[182:185], v[0:3]
	v_mfma_f32_16x16x32_bf16 v[4:7], v[128:131], v[182:185], v[4:7]
	v_mfma_f32_16x16x32_bf16 v[8:11], v[174:177], v[182:185], v[8:11]
	v_mfma_f32_16x16x32_bf16 v[12:15], v[178:181], v[182:185], v[12:15]
	s_waitcnt lgkmcnt(2)
	v_mfma_f32_16x16x32_bf16 v[16:19], v[80:83], v[186:189], v[16:19]
	v_mfma_f32_16x16x32_bf16 v[20:23], v[128:131], v[186:189], v[20:23]
	v_mfma_f32_16x16x32_bf16 v[24:27], v[174:177], v[186:189], v[24:27]
	v_mfma_f32_16x16x32_bf16 v[28:31], v[178:181], v[186:189], v[28:31]
	s_waitcnt vmcnt(0)
	s_waitcnt lgkmcnt(0)
	s_barrier
	s_add_i32 s5, s5, 0x8000
	s_cmp_eq_u32 s5, 0x78000
	s_cbranch_scc1 .Lgk_tail_154
	v_or_b32_e32 v173, s9, v142
	v_add_u32_e32 v190, s9, v139
	s_add_i32 s12, s8, s13
	ds_read_b128 v[182:185], v190
	ds_read_b128 v[64:67], v173 offset:16384
	s_mov_b32 m0, s12
	s_nop 0
	v_mfma_f32_16x16x32_bf16 v[32:35], v[80:83], v[246:249], v[32:35]
	global_load_lds_dwordx4 v254, s[98:99]
	ds_read_b128 v[68:71], v173 offset:16896
	v_mfma_f32_16x16x32_bf16 v[36:39], v[128:131], v[246:249], v[36:39]
	ds_read_b128 v[72:75], v173 offset:20480
	v_mfma_f32_16x16x32_bf16 v[40:43], v[174:177], v[246:249], v[40:43]
	ds_read_b128 v[76:79], v173 offset:20992
	s_add_i32 m0, s12, 0x1000
	s_add_u32 s10, s98, s14
	s_addc_u32 s11, s99, 0
	v_mfma_f32_16x16x32_bf16 v[44:47], v[178:181], v[246:249], v[44:47]
	global_load_lds_dwordx4 v254, s[10:11]
	ds_read_b128 v[186:189], v190 offset:2048
	ds_read_b128 v[246:249], v190 offset:4096
	v_mfma_f32_16x16x32_bf16 v[48:51], v[80:83], v[250:253], v[48:51]
	v_mfma_f32_16x16x32_bf16 v[52:55], v[128:131], v[250:253], v[52:55]
	s_add_i32 m0, s12, 0x2000
	s_add_u32 s10, s10, s14
	s_addc_u32 s11, s11, 0
	v_mfma_f32_16x16x32_bf16 v[56:59], v[174:177], v[250:253], v[56:59]
	global_load_lds_dwordx4 v254, s[10:11]
	v_mfma_f32_16x16x32_bf16 v[60:63], v[178:181], v[250:253], v[60:63]
	ds_read_b128 v[250:253], v190 offset:6144
	s_branch .Lgk_loop_154

; __device__ __forceinline__ u32x4 pack8(f32x4 a, f32x4 b) { u32x4 r; r.x = cvt_pk_bf16(a[0], a[1]); r.y = cvt_pk_bf16(a[2], a[3]); r.z = cvt_pk_bf16(b[0], b[1]); r.w = cvt_pk_bf16(b[2], b[3]); return r; }
; template <class Epi>
; __device__ __forceinline__ void gemm_tile(const bf16_t* __restrict__ A, const bf16_t* __restrict__ Bt, int K, int row0, int col0, const Epi& epi, char* smem,
;                                           bool prefetched, bool nvalid, int nrow0, int ncol0) {
;     ...
;     if constexpr (Epi::STAGED) {
;         bf16_t* st = (bf16_t*)(smem + 2 * TILE_B);
;         epi.to_lds(acc, st, row0, col0, wr, wc, fr, fq);
;         __syncthreads();
;         bf16_t* gbase; size_t gstride;
;         epi.dest(row0, col0, gbase, gstride);
;         const int r0 = tid >> 4, ch = (tid & 15) * 8;
; #pragma unroll
;         for (int it = 0; it < 8; ++it) { const int r = it * 16 + r0; __builtin_nontemporal_store(*(const u32x4*)(st + r * 136 + ch), (u32x4*)(gbase + (size_t)r * gstride + ch)); }
;     __device__ __forceinline__ void to_lds(f32x4 (&acc)[4][4], bf16_t* st, int row0, int col0, int wr, int wc, int fr, int fq) const {
; #pragma unroll
;         for (int m = 0; m < 4; ++m)
; #pragma unroll
;             for (int pp = 0; pp < 2; ++pp)
;                 *(u32x4*)(st + (wr * 64 + m * 16 + fr) * 136 + wc * 64 + pp * 32 + 8 * fq) = pack8(acc[m][2 * pp], acc[m][2 * pp + 1]);
.LBB0_191:
	s_ashr_i32 s6, s0, 12
	s_ashr_i32 s7, s6, 31
	s_lshl_b64 s[6:7], s[6:7], 22
	s_lshl_b64 s[2:3], s[2:3], 13
	v_readlane_b32 s1, v245, 57
	s_add_u32 s1, s1, s6
	v_readlane_b32 s6, v245, 58
	s_addc_u32 s6, s6, s7
	s_add_u32 s1, s1, s2
	v_cvt_pk_bf16_f32 v56, v56, v57
	v_cvt_pk_bf16_f32 v57, v58, v59
	v_cvt_pk_bf16_f32 v58, v60, v61
	v_cvt_pk_bf16_f32 v59, v62, v63
	v_cvt_pk_bf16_f32 v48, v48, v49
	v_cvt_pk_bf16_f32 v49, v50, v51
	v_cvt_pk_bf16_f32 v50, v52, v53
	v_cvt_pk_bf16_f32 v51, v54, v55
	v_cvt_pk_bf16_f32 v44, v44, v45
	v_cvt_pk_bf16_f32 v45, v46, v47
	v_cvt_pk_bf16_f32 v46, v40, v41
	v_cvt_pk_bf16_f32 v47, v42, v43
	v_cvt_pk_bf16_f32 v36, v36, v37
	v_cvt_pk_bf16_f32 v37, v38, v39
	v_cvt_pk_bf16_f32 v38, v32, v33
	v_cvt_pk_bf16_f32 v39, v34, v35
	v_cvt_pk_bf16_f32 v28, v28, v29
	v_cvt_pk_bf16_f32 v29, v30, v31
	v_cvt_pk_bf16_f32 v30, v24, v25
	v_cvt_pk_bf16_f32 v31, v26, v27
	v_cvt_pk_bf16_f32 v20, v20, v21
	v_cvt_pk_bf16_f32 v21, v22, v23
	v_cvt_pk_bf16_f32 v22, v16, v17
	v_cvt_pk_bf16_f32 v23, v18, v19
	v_cvt_pk_bf16_f32 v4, v4, v5
	v_cvt_pk_bf16_f32 v5, v6, v7
	v_cvt_pk_bf16_f32 v6, v8, v9
	v_cvt_pk_bf16_f32 v7, v10, v11
	v_cvt_pk_bf16_f32 v0, v0, v1
	v_cvt_pk_bf16_f32 v1, v2, v3
	v_cvt_pk_bf16_f32 v2, v12, v13
	v_cvt_pk_bf16_f32 v3, v14, v15
	s_addc_u32 s2, s6, s3
	s_and_b32 s0, s0, 0xf80
	ds_write_b128 v145, v[56:59] offset:32768
	ds_write_b128 v145, v[48:51] offset:32832
	ds_write_b128 v145, v[44:47] offset:37120
	ds_write_b128 v145, v[36:39] offset:37184
	ds_write_b128 v145, v[28:31] offset:41472
	ds_write_b128 v145, v[20:23] offset:41536
	ds_write_b128 v145, v[4:7] offset:45824
	ds_write_b128 v145, v[0:3] offset:45888
	s_waitcnt lgkmcnt(0)
	s_barrier
	s_lshl_b32 s0, s0, 1
	ds_read_b128 v[0:3], v162 offset:32768
	ds_read_b128 v[4:7], v162 offset:37120
	s_add_u32 s0, s1, s0
	s_addc_u32 s1, s2, 0
	v_lshl_add_u64 v[12:13], s[0:1], 0, v[72:73]
	v_lshl_add_u64 v[8:9], v[74:75], 1, v[12:13]
	s_waitcnt lgkmcnt(1)
	global_store_dwordx4 v[8:9], v[0:3], off nt
	ds_read_b128 v[0:3], v162 offset:41472
	v_lshl_add_u64 v[8:9], v[76:77], 1, v[12:13]
	s_waitcnt lgkmcnt(1)
	global_store_dwordx4 v[8:9], v[4:7], off nt
	ds_read_b128 v[4:7], v162 offset:45824
	v_lshl_add_u64 v[8:9], v[78:79], 1, v[12:13]
	s_waitcnt lgkmcnt(1)
	global_store_dwordx4 v[8:9], v[0:3], off nt
	ds_read_b128 v[0:3], v162 offset:50176
	v_lshl_add_u64 v[8:9], v[80:81], 1, v[12:13]
	s_waitcnt lgkmcnt(1)
	global_store_dwordx4 v[8:9], v[4:7], off nt
	v_lshl_add_u64 v[8:9], v[82:83], 1, v[12:13]
	ds_read_b128 v[4:7], v162 offset:54528
	s_waitcnt lgkmcnt(1)
	global_store_dwordx4 v[8:9], v[0:3], off nt
	ds_read_b128 v[0:3], v162 offset:58880
	ds_read_b128 v[8:11], v162 offset:63232
	v_lshl_add_u64 v[14:15], v[84:85], 1, v[12:13]
	s_waitcnt lgkmcnt(2)
	global_store_dwordx4 v[14:15], v[4:7], off nt
	s_andn2_b64 vcc, exec, s[4:5]
	s_mov_b64 s[8:9], -1
	v_lshl_add_u64 v[4:5], v[86:87], 1, v[12:13]
	s_waitcnt lgkmcnt(1)
	global_store_dwordx4 v[4:5], v[0:3], off nt
	s_nop 1
	v_lshl_add_u64 v[0:1], v[88:89], 1, v[12:13]
	s_waitcnt lgkmcnt(0)
	global_store_dwordx4 v[0:1], v[8:11], off nt
	s_cbranch_vccz .LBB0_200

; __device__ __forceinline__ f32x4 zero4() { return (f32x4){0.f, 0.f, 0.f, 0.f}; }
; template <class Epi>
; __device__ __forceinline__ void gemm_tile(const bf16_t* __restrict__ A, const bf16_t* __restrict__ Bt, int K, int row0, int col0, const Epi& epi, char* smem,
;                                           bool prefetched, bool nvalid, int nrow0, int ncol0) {
;     ...
;     f32x4 acc[4][4];
; #pragma unroll
;     for (int m = 0; m < 4; ++m)
; #pragma unroll
;         for (int n = 0; n < 4; ++n) acc[m][n] = zero4();
;     ...
;     __syncthreads();
;     const int nk = K >> 6;
;     for (int kt = 0; kt < nk; ++kt) {
;         const int cur = kt & 1;
;         if (kt + 1 < nk) GLDS_STAGE(cur ^ 1, pA, pB, kt + 1);
;         const char* cb = smem + cur * 2 * TILE_B;
; #pragma unroll
;         for (int ks = 0; ks < 2; ++ks) {
;             bf16x8 a[4], b[4];
; #pragma unroll
;             for (int m = 0; m < 4; ++m) a[m] = *(const bf16x8*)(cb + offA[m][ks]);
; #pragma unroll
;             for (int n = 0; n < 4; ++n) b[n] = *(const bf16x8*)(cb + offB[n][ks]);
.LBB0_196:
	v_mov_b32_e32 v0, 0
	v_lshl_add_u64 v[106:107], v[90:91], 0, s[4:5]
	v_lshl_add_u64 v[108:109], v[92:93], 0, s[4:5]
	v_lshl_add_u64 v[110:111], v[94:95], 0, s[4:5]
	v_lshl_add_u64 v[118:119], v[96:97], 0, s[4:5]
	v_lshl_add_u64 v[120:121], v[98:99], 0, s[6:7]
	v_lshl_add_u64 v[122:123], v[100:101], 0, s[6:7]
	v_lshl_add_u64 v[124:125], v[102:103], 0, s[6:7]
	v_lshl_add_u64 v[126:127], v[104:105], 0, s[6:7]
	s_mov_b32 s1, 0
	s_mov_b64 s[4:5], 0
	v_mov_b32_e32 v1, v0
	v_mov_b32_e32 v2, v0
	v_mov_b32_e32 v3, v0
	v_mov_b32_e32 v4, v0
	v_mov_b32_e32 v5, v0
	v_mov_b32_e32 v6, v0
	v_mov_b32_e32 v7, v0
	v_mov_b32_e32 v8, v0
	v_mov_b32_e32 v9, v0
	v_mov_b32_e32 v10, v0
	v_mov_b32_e32 v11, v0
	v_mov_b32_e32 v12, v0
	v_mov_b32_e32 v13, v0
	v_mov_b32_e32 v14, v0
	v_mov_b32_e32 v15, v0
	v_mov_b32_e32 v16, v0
	v_mov_b32_e32 v17, v0
	v_mov_b32_e32 v18, v0
	v_mov_b32_e32 v19, v0
	v_mov_b32_e32 v20, v0
	v_mov_b32_e32 v21, v0
	v_mov_b32_e32 v22, v0
	v_mov_b32_e32 v23, v0
	v_mov_b32_e32 v24, v0
	v_mov_b32_e32 v25, v0
	v_mov_b32_e32 v26, v0
	v_mov_b32_e32 v27, v0
	v_mov_b32_e32 v28, v0
	v_mov_b32_e32 v29, v0
	v_mov_b32_e32 v30, v0
	v_mov_b32_e32 v31, v0
	v_mov_b32_e32 v32, v0
	v_mov_b32_e32 v33, v0
	v_mov_b32_e32 v34, v0
	v_mov_b32_e32 v35, v0
	v_mov_b32_e32 v36, v0
	v_mov_b32_e32 v37, v0
	v_mov_b32_e32 v38, v0
	v_mov_b32_e32 v39, v0
	v_mov_b32_e32 v40, v0
	v_mov_b32_e32 v41, v0
	v_mov_b32_e32 v42, v0
	v_mov_b32_e32 v43, v0
	v_mov_b32_e32 v44, v0
	v_mov_b32_e32 v45, v0
	v_mov_b32_e32 v46, v0
	v_mov_b32_e32 v47, v0
	v_mov_b32_e32 v48, v0
	v_mov_b32_e32 v49, v0
	v_mov_b32_e32 v50, v0
	v_mov_b32_e32 v51, v0
	v_mov_b32_e32 v52, v0
	v_mov_b32_e32 v53, v0
	v_mov_b32_e32 v54, v0
	v_mov_b32_e32 v55, v0
	v_mov_b32_e32 v56, v0
	v_mov_b32_e32 v57, v0
	v_mov_b32_e32 v58, v0
	v_mov_b32_e32 v59, v0
	v_mov_b32_e32 v60, v0
	v_mov_b32_e32 v61, v0
	v_mov_b32_e32 v62, v0
	v_mov_b32_e32 v63, v0
	s_waitcnt lgkmcnt(0)
	s_barrier
.LBB0_197:
	v_readfirstlane_b32 s98, v106
	v_readfirstlane_b32 s99, v107
	v_readfirstlane_b32 s8, v108
	v_readfirstlane_b32 s100, v120
	v_readfirstlane_b32 s101, v121
	v_readfirstlane_b32 s11, v149
	s_nop 3
	s_sub_u32 s15, s8, s98
	s_and_b32 s98, s98, 0xffffff80
	s_and_b32 s100, s100, 0xffffff80
	s_nop 1
	v_subrev_u32_e32 v254, s98, v106
	v_subrev_u32_e32 v255, s100, v120
	s_add_i32 s10, s11, 0x8000
	s_mov_b32 m0, s10
	s_nop 0
	global_load_lds_dwordx4 v254, s[98:99]
	s_add_i32 m0, s10, 0x1000
	s_add_u32 s8, s98, s15
	s_addc_u32 s9, s99, 0
	global_load_lds_dwordx4 v254, s[8:9]
	s_add_i32 m0, s10, 0x2000
	s_add_u32 s8, s8, s15
	s_addc_u32 s9, s9, 0
	global_load_lds_dwordx4 v254, s[8:9]
	ds_read_b128 v[188:191], v117
	ds_read_b128 v[106:109], v130 offset:16384
	ds_read_b128 v[118:121], v130 offset:16896
	ds_read_b128 v[122:125], v130 offset:20480
	ds_read_b128 v[168:171], v130 offset:20992
	ds_read_b128 v[192:195], v117 offset:2048
	ds_read_b128 v[196:199], v117 offset:4096
	ds_read_b128 v[246:249], v117 offset:6144
; __device__ __forceinline__ f32x4 mfma16(bf16x8 a, bf16x8 b, f32x4 c) { return __builtin_amdgcn_mfma_f32_16x16x32_bf16(a, b, c, 0, 0, 0); }
; template <class Epi>
; __device__ __forceinline__ void gemm_tile(const bf16_t* __restrict__ A, const bf16_t* __restrict__ Bt, int K, int row0, int col0, const Epi& epi, char* smem,
;                                           bool prefetched, bool nvalid, int nrow0, int ncol0) {
;     ...
;     for (int kt = 0; kt < nk; ++kt) {
;         const int cur = kt & 1;
;         if (kt + 1 < nk) GLDS_STAGE(cur ^ 1, pA, pB, kt + 1);
;         const char* cb = smem + cur * 2 * TILE_B;
; #pragma unroll
;         for (int ks = 0; ks < 2; ++ks) {
;             bf16x8 a[4], b[4];
; #pragma unroll
;             for (int m = 0; m < 4; ++m) a[m] = *(const bf16x8*)(cb + offA[m][ks]);
; #pragma unroll
;             for (int n = 0; n < 4; ++n) b[n] = *(const bf16x8*)(cb + offB[n][ks]);
; #pragma unroll
;             for (int m = 0; m < 4; ++m)
; #pragma unroll
;                 for (int n = 0; n < 4; ++n) acc[m][n] = mfma16(b[n], a[m], acc[m][n]);
;         }
;         asm volatile("s_waitcnt vmcnt(0)" ::: "memory");
;         __syncthreads();
.Lgk_loop_197:
	s_and_b32 s6, s1, 0x8000
	s_xor_b32 s7, s6, 0x8000
	v_or_b32_e32 v167, s6, v129
	v_add_u32_e32 v250, s6, v128
	s_waitcnt lgkmcnt(6)
	v_mfma_f32_16x16x32_bf16 v[0:3], v[106:109], v[188:191], v[0:3]
	ds_read_b128 v[172:175], v167 offset:16384
	s_add_i32 m0, s10, 0x3000
	s_add_u32 s8, s8, s15
	s_addc_u32 s9, s9, 0
	s_waitcnt lgkmcnt(6)
	v_mfma_f32_16x16x32_bf16 v[4:7], v[118:121], v[188:191], v[4:7]
	global_load_lds_dwordx4 v254, s[8:9]
	s_add_u32 s98, s98, 0x80
	s_addc_u32 s99, s99, 0
	ds_read_b128 v[176:179], v167 offset:16896
	s_waitcnt lgkmcnt(6)
	v_mfma_f32_16x16x32_bf16 v[8:11], v[122:125], v[188:191], v[8:11]
	ds_read_b128 v[180:183], v167 offset:20480
	s_waitcnt lgkmcnt(6)
	v_mfma_f32_16x16x32_bf16 v[12:15], v[168:171], v[188:191], v[12:15]
	ds_read_b128 v[184:187], v167 offset:20992
	ds_read_b128 v[188:191], v250
	s_add_i32 m0, s10, 0x4000
	s_nop 0
	s_waitcnt lgkmcnt(7)
	v_mfma_f32_16x16x32_bf16 v[16:19], v[106:109], v[192:195], v[16:19]
	global_load_lds_dwordx4 v255, s[100:101]
	v_mfma_f32_16x16x32_bf16 v[20:23], v[118:121], v[192:195], v[20:23]
	v_mfma_f32_16x16x32_bf16 v[24:27], v[122:125], v[192:195], v[24:27]
	s_add_i32 m0, s10, 0x5000
	s_add_u32 s8, s100, s15
	s_addc_u32 s9, s101, 0
	v_mfma_f32_16x16x32_bf16 v[28:31], v[168:171], v[192:195], v[28:31]
	global_load_lds_dwordx4 v255, s[8:9]
	ds_read_b128 v[192:195], v250 offset:2048
	s_waitcnt lgkmcnt(7)
	v_mfma_f32_16x16x32_bf16 v[32:35], v[106:109], v[196:199], v[32:35]
	v_mfma_f32_16x16x32_bf16 v[36:39], v[118:121], v[196:199], v[36:39]
	s_add_i32 m0, s10, 0x6000
	s_add_u32 s8, s8, s15
	s_addc_u32 s9, s9, 0
	v_mfma_f32_16x16x32_bf16 v[40:43], v[122:125], v[196:199], v[40:43]
	global_load_lds_dwordx4 v255, s[8:9]
	v_mfma_f32_16x16x32_bf16 v[44:47], v[168:171], v[196:199], v[44:47]
	ds_read_b128 v[196:199], v250 offset:4096
	s_waitcnt lgkmcnt(7)
	v_mfma_f32_16x16x32_bf16 v[48:51], v[106:109], v[246:249], v[48:51]
	s_add_i32 m0, s10, 0x7000
	s_add_u32 s8, s8, s15
	s_addc_u32 s9, s9, 0
	v_mfma_f32_16x16x32_bf16 v[52:55], v[118:121], v[246:249], v[52:55]
	global_load_lds_dwordx4 v255, s[8:9]
	s_add_u32 s100, s100, 0x80
	s_addc_u32 s101, s101, 0
	v_mfma_f32_16x16x32_bf16 v[56:59], v[122:125], v[246:249], v[56:59]
	v_mfma_f32_16x16x32_bf16 v[60:63], v[168:171], v[246:249], v[60:63]
	ds_read_b128 v[246:249], v250 offset:6144
	s_waitcnt lgkmcnt(3)
	v_mfma_f32_16x16x32_bf16 v[0:3], v[172:175], v[188:191], v[0:3]
	v_mfma_f32_16x16x32_bf16 v[4:7], v[176:179], v[188:191], v[4:7]
	v_mfma_f32_16x16x32_bf16 v[8:11], v[180:183], v[188:191], v[8:11]
	v_mfma_f32_16x16x32_bf16 v[12:15], v[184:187], v[188:191], v[12:15]
	s_waitcnt lgkmcnt(2)
	v_mfma_f32_16x16x32_bf16 v[16:19], v[172:175], v[192:195], v[16:19]
	v_mfma_f32_16x16x32_bf16 v[20:23], v[176:179], v[192:195], v[20:23]
	v_mfma_f32_16x16x32_bf16 v[24:27], v[180:183], v[192:195], v[24:27]
	v_mfma_f32_16x16x32_bf16 v[28:31], v[184:187], v[192:195], v[28:31]
	s_waitcnt vmcnt(0)
	s_waitcnt lgkmcnt(0)
	s_barrier
	s_add_i32 s1, s1, 0x8000
	s_cmp_eq_u32 s1, 0x78000
	s_cbranch_scc1 .Lgk_tail_197
	v_or_b32_e32 v167, s7, v130
	v_add_u32_e32 v250, s7, v117
	s_add_i32 s10, s6, s11
	ds_read_b128 v[188:191], v250
	ds_read_b128 v[106:109], v167 offset:16384
	s_mov_b32 m0, s10
	s_nop 0
	v_mfma_f32_16x16x32_bf16 v[32:35], v[172:175], v[196:199], v[32:35]
	global_load_lds_dwordx4 v254, s[98:99]
	ds_read_b128 v[118:121], v167 offset:16896
	v_mfma_f32_16x16x32_bf16 v[36:39], v[176:179], v[196:199], v[36:39]
	ds_read_b128 v[122:125], v167 offset:20480
	v_mfma_f32_16x16x32_bf16 v[40:43], v[180:183], v[196:199], v[40:43]
	ds_read_b128 v[168:171], v167 offset:20992
	s_add_i32 m0, s10, 0x1000
	s_add_u32 s8, s98, s15
	s_addc_u32 s9, s99, 0
	v_mfma_f32_16x16x32_bf16 v[44:47], v[184:187], v[196:199], v[44:47]
	global_load_lds_dwordx4 v254, s[8:9]
	ds_read_b128 v[192:195], v250 offset:2048
	ds_read_b128 v[196:199], v250 offset:4096
	v_mfma_f32_16x16x32_bf16 v[48:51], v[172:175], v[246:249], v[48:51]
	v_mfma_f32_16x16x32_bf16 v[52:55], v[176:179], v[246:249], v[52:55]
	s_add_i32 m0, s10, 0x2000
	s_add_u32 s8, s8, s15
	s_addc_u32 s9, s9, 0
	v_mfma_f32_16x16x32_bf16 v[56:59], v[180:183], v[246:249], v[56:59]
	global_load_lds_dwordx4 v254, s[8:9]
	v_mfma_f32_16x16x32_bf16 v[60:63], v[184:187], v[246:249], v[60:63]
	ds_read_b128 v[246:249], v250 offset:6144
	s_branch .Lgk_loop_197

; __device__ __forceinline__ f32x4 zero4() { return (f32x4){0.f, 0.f, 0.f, 0.f}; }
; template <int KW, int VD, bool SEL> ...
;     ...
;     int koff[NKI], voff[NVI];
; #pragma unroll
;     for (int i = 0; i < NKI; ++i) {
;         const int row = (w + 4 * i) * KRPI + lane / KCPR, cp = lane % KCPR;
;         const int f = (KW == 64) ? (((row >> 1) & 1) | (((row >> 3) & 1) << 1) | (((row >> 4) & 1) << 2)) : ((row & 3) | (((row >> 3) & 3) << 2));
;         koff[i] = row * ldk + (cp ^ f) * 8;
;     }
; #pragma unroll
;     for (int i = 0; i < NVI; ++i) {
;         const int row = (w + 4 * i) * 8 + (lane >> 3), cp = lane & 7;
;         voff[i] = row * S + (cp ^ ((row >> 1) & 7)) * 8;
;     }
;     ...
;     int j = __ffsll((long long)tiles) - 1; tiles &= tiles - 1;
;     FL_ISSUE(0, j);
;     asm volatile("s_waitcnt vmcnt(0)" ::: "memory");
;     __syncthreads();
; __device__ __forceinline__ void nsa_tile(const Params& p, int qb, int bg, char* smem) {
;     ...
;     u64 ormask = 0;
; #pragma unroll 4
;     for (int i = 0; i < 32; ++i) ormask |= selmask[i];
;     ormask = ((u64)__builtin_amdgcn_readfirstlane((unsigned)(ormask >> 32)) << 32) | (u64)__builtin_amdgcn_readfirstlane((unsigned)ormask);
;     const u64 selm[2] = {~0ull, ~0ull};
;     const int cur0 = t0 >> 6;
;     float* park = part;
;     __syncthreads();
; #pragma unroll
;     for (int qt = 0; qt < 2; ++qt)
; #pragma unroll
;         for (int dt = 0; dt < 4; ++dt)
;             ((f32x4*)park)[(qt * 4 + dt) * 256 + tid] = outacc[qt][dt];
;     {
;         f32x4 O[2][4];
; #pragma unroll
;         for (int qt = 0; qt < 2; ++qt)
; #pragma unroll
;             for (int dt = 0; dt < 4; ++dt) O[qt][dt] = zero4();
;         float mr[2] = {-1e30f, -1e30f}, lr[2] = {0.f, 0.f};
;         const int lo[2] = {-1, -1};
;         flash_branch<64, 64, true>(ormask, projA + (size_t)b * S * LDA + 1536 + g * 64, LDA, projVT + ((size_t)b * 512 + g * 64) * S, 0,
;                                    qf, O, mr, lr, tpos, selm, lo, t0, -1, smem);
.LBB0_366:
	s_add_i32 s1, s0, 0x11000
	s_add_i32 s2, s0, 0x11010
	v_mov_b32_e32 v3, s1
	v_mov_b32_e32 v58, s2
	ds_read_b128 v[54:57], v3
	ds_read_b128 v[58:61], v58
	s_add_i32 s0, s0, 32
	s_cmpk_eq_i32 s0, 0x100
	s_waitcnt lgkmcnt(1)
	v_or_b32_e32 v3, v54, v52
	v_or_b32_e32 v52, v55, v53
	v_or_b32_e32 v3, v56, v3
	v_or_b32_e32 v52, v57, v52
	s_waitcnt lgkmcnt(0)
	v_or_b32_e32 v3, v58, v3
	v_or_b32_e32 v53, v59, v52
	v_or_b32_e32 v52, v60, v3
	v_or_b32_e32 v53, v61, v53
	s_cbranch_scc0 .LBB0_366
	v_readlane_b32 s16, v244, 17
	v_readfirstlane_b32 s1, v53
	v_readfirstlane_b32 s0, v52
	v_readlane_b32 s17, v244, 18
	s_mov_b32 s2, s17
	s_mov_b32 s3, s1
	s_bfe_i64 s[0:1], s[0:1], 0x200000
	v_readlane_b32 s8, v244, 13
	s_or_b64 s[0:1], s[0:1], s[2:3]
	s_mul_i32 s2, s8, 0x1100000
	v_readlane_b32 s4, v245, 55
	v_readlane_b32 s5, v245, 56
	s_add_u32 s2, s4, s2
	s_addc_u32 s3, s5, 0
	v_readlane_b32 s5, v244, 12
	s_lshl_b32 s4, s5, 7
	s_add_u32 s6, s2, s4
	s_addc_u32 s7, s3, 0
	s_lshl_b32 s2, s8, 22
	s_lshl_b32 s3, s5, 19
	v_readlane_b32 s4, v245, 57
	s_add_u32 s2, s4, s2
	v_readlane_b32 s4, v245, 58
	s_addc_u32 s4, s4, 0
	s_add_u32 s8, s2, s3
	v_lshlrev_b32_e32 v122, 4, v76
	s_addc_u32 s9, s4, 0
	v_readlane_b32 s52, v244, 3
	v_pk_mul_f32 v[38:39], v[0:1], v[38:39] op_sel_hi:[0,1]
	v_pk_mul_f32 v[36:37], v[0:1], v[36:37] op_sel_hi:[0,1]
	v_pk_mul_f32 v[46:47], v[2:3], v[46:47] op_sel_hi:[0,1]
	v_pk_mul_f32 v[44:45], v[2:3], v[44:45] op_sel_hi:[0,1]
	v_pk_mul_f32 v[34:35], v[0:1], v[34:35] op_sel_hi:[0,1]
	v_pk_mul_f32 v[32:33], v[0:1], v[32:33] op_sel_hi:[0,1]
	v_pk_mul_f32 v[26:27], v[0:1], v[26:27] op_sel_hi:[0,1]
	v_pk_mul_f32 v[24:25], v[0:1], v[24:25] op_sel_hi:[0,1]
	v_pk_mul_f32 v[22:23], v[0:1], v[22:23] op_sel_hi:[0,1]
	v_pk_mul_f32 v[20:21], v[0:1], v[20:21] op_sel_hi:[0,1]
	v_add_u32_e32 v121, 0x9000, v122
	v_mov_b32_e32 v0, v114
	s_cmp_lg_u64 s[0:1], 0
	v_readlane_b32 s53, v244, 4
	v_readlane_b32 s54, v244, 5
	v_readlane_b32 s55, v244, 6
	v_readlane_b32 s56, v244, 7
	v_readlane_b32 s57, v244, 8
	v_readlane_b32 s58, v244, 9
	v_readlane_b32 s59, v244, 10
	s_mov_b64 s[18:19], 0x1000
	s_mov_b32 s20, 0xf149f2ca
	v_readlane_b32 s21, v244, 16
	v_pk_mul_f32 v[50:51], v[2:3], v[50:51] op_sel_hi:[0,1]
	v_pk_mul_f32 v[48:49], v[2:3], v[48:49] op_sel_hi:[0,1]
	v_pk_mul_f32 v[42:43], v[2:3], v[42:43] op_sel_hi:[0,1]
	v_pk_mul_f32 v[40:41], v[2:3], v[40:41] op_sel_hi:[0,1]
	v_pk_mul_f32 v[30:31], v[2:3], v[30:31] op_sel_hi:[0,1]
	v_pk_mul_f32 v[28:29], v[2:3], v[28:29] op_sel_hi:[0,1]
	s_barrier
	ds_write_b128 v122, v[44:47] offset:36864
	ds_write_b128 v122, v[48:51] offset:40960
	ds_write_b128 v122, v[40:43] offset:45056
	ds_write_b128 v122, v[28:31] offset:49152
	ds_write_b128 v122, v[32:35] offset:53248
	ds_write_b128 v122, v[36:39] offset:57344
	ds_write_b128 v122, v[24:27] offset:61440
	ds_write_b128 v121, v[20:23] offset:28672
	s_cbranch_scc0 .LBB0_387
	v_ashrrev_i32_e32 v2, 6, v0
	v_bfe_u32 v3, v0, 3, 3
	v_bfe_u32 v21, v0, 4, 1
	v_lshlrev_b32_e32 v22, 1, v2
	v_lshl_or_b32 v3, v2, 3, v3
	v_and_b32_e32 v20, 7, v0
	v_and_or_b32 v21, v22, 2, v21
	v_and_b32_e32 v22, 4, v22
	s_movk_i32 s2, 0x880
	v_bitop3_b32 v20, v21, v20, v22 bitop3:0x36
	v_mul_lo_u32 v21, v3, s2
	s_ff1_i32_b64 s4, s[0:1]
	s_add_u32 s2, s0, -1
	v_lshl_or_b32 v96, v20, 3, v21
	v_lshlrev_b32_e32 v20, 12, v3
	v_lshrrev_b32_e32 v3, 1, v3
	s_addc_u32 s3, s1, -1
	s_mul_i32 s5, s4, 0x44000
	v_xor_b32_e32 v3, v3, v0
	s_add_u32 s10, s6, s5
	v_lshlrev_b32_e32 v3, 3, v3
	v_lshlrev_b32_e32 v123, 10, v2
	s_addc_u32 s11, s7, 0
	v_ashrrev_i32_e32 v97, 31, v96
	v_add_u32_e32 v98, 0x11000, v96
	v_and_or_b32 v100, v3, 56, v20
	v_lshl_add_u64 v[2:3], v[96:97], 1, s[10:11]
	s_mov_b64 s[14:15], 0xc00
	v_readfirstlane_b32 s12, v123
	v_lshl_add_u64 v[2:3], v[2:3], 0, s[14:15]
	s_mov_b32 m0, s12
	v_ashrrev_i32_e32 v99, 31, v98
	v_add_u32_e32 v20, 0x1000, v123
	s_lshl_b32 s5, s4, 7
	global_load_lds_dwordx4 v[2:3], off
	v_lshl_add_u64 v[2:3], v[98:99], 1, s[10:11]
	v_readfirstlane_b32 s10, v20
	s_mov_b32 m0, s10
	s_add_u32 s10, s8, s5
	v_add_u32_e32 v20, 0x2000, v123
	v_add_u32_e32 v102, 0x20000, v100
	v_lshl_add_u64 v[2:3], v[2:3], 0, s[14:15]
	s_addc_u32 s11, s9, 0
	v_ashrrev_i32_e32 v101, 31, v100
	v_readfirstlane_b32 s5, v20
	v_add_u32_e32 v20, 0x3000, v123
	global_load_lds_dwordx4 v[2:3], off
	v_lshl_add_u64 v[2:3], v[100:101], 1, s[10:11]
	s_mov_b32 m0, s5
	v_ashrrev_i32_e32 v103, 31, v102
	v_readfirstlane_b32 s5, v20
	global_load_lds_dwordx4 v[2:3], off
	v_lshl_add_u64 v[2:3], v[102:103], 1, s[10:11]
	s_mov_b32 m0, s5
	v_lshrrev_b32_e32 v20, 1, v0
	global_load_lds_dwordx4 v[2:3], off
	v_bfe_u32 v2, v0, 4, 2
	v_and_b32_e32 v3, 15, v0
	v_bfe_u32 v21, v0, 1, 3
	v_lshlrev_b32_e32 v22, 1, v0
	v_and_b32_e32 v0, 3, v0
	v_bitop3_b32 v20, v2, v20, 7 bitop3:0x78
	s_waitcnt vmcnt(0)
	v_lshl_or_b32 v124, v3, 3, v108
	v_and_or_b32 v0, v22, 24, v0
	v_lshlrev_b32_e32 v125, 4, v20
	v_bitop3_b32 v20, v2, v21, 4 bitop3:0x36
	v_lshlrev_b32_e32 v127, 3, v2
	v_lshlrev_b32_e32 v128, 7, v3
	v_mov_b32_e32 v2, v1
	v_mov_b32_e32 v3, v1
	v_lshlrev_b32_e32 v126, 4, v20
	v_lshlrev_b32_e32 v129, 7, v0
	v_mov_b32_e32 v0, v1
	v_mov_b64_e32 v[22:23], v[2:3]
	v_mov_b64_e32 v[26:27], v[2:3]
	v_mov_b64_e32 v[30:31], v[2:3]
	v_mov_b64_e32 v[34:35], v[2:3]
	v_mov_b64_e32 v[38:39], v[2:3]
	v_mov_b64_e32 v[42:43], v[2:3]
	v_mov_b64_e32 v[46:47], v[2:3]
	v_mov_b64_e32 v[50:51], v[2:3]
	s_and_b64 s[2:3], s[2:3], s[0:1]
	s_mov_b32 s10, 0
	v_mov_b32_e32 v130, 0xf149f2ca
	v_mov_b32_e32 v104, 0
	v_mov_b64_e32 v[20:21], v[0:1]
	v_mov_b64_e32 v[24:25], v[0:1]
	v_mov_b64_e32 v[28:29], v[0:1]
	v_mov_b64_e32 v[32:33], v[0:1]
	v_mov_b64_e32 v[36:37], v[0:1]
	v_mov_b64_e32 v[40:41], v[0:1]
	v_mov_b64_e32 v[44:45], v[0:1]
	v_mov_b64_e32 v[48:49], v[0:1]
	v_mov_b32_e32 v105, 0
	v_mov_b32_e32 v0, 0xf149f2ca
	s_mov_b32 s16, 0xefa18f08
	v_lshlrev_b32_e32 v246, 1, v96
	v_lshlrev_b32_e32 v247, 1, v98
	v_lshlrev_b32_e32 v248, 1, v100
	v_lshlrev_b32_e32 v249, 1, v102
	s_waitcnt vmcnt(0) lgkmcnt(0)
	s_barrier
	s_cmp_lg_u64 s[2:3], 0
	s_cbranch_scc1 .LBB0_371
	s_branch .LBB0_370

; template <int KW, int VD, bool SEL> ...
;     ...
;     while (true) {
;         int jn = -1;
;         if (tiles) { jn = __ffsll((long long)tiles) - 1; tiles &= tiles - 1; FL_ISSUE(cur ^ 1, jn); }
.LBB0_371:
	s_add_u32 s0, s2, -1
	s_addc_u32 s1, s3, -1
	s_lshl_b32 s12, s10, 14
	s_ff1_i32_b64 s11, s[2:3]
	s_and_b64 s[2:3], s[0:1], s[2:3]
	s_branch .LBB0_373

; __device__ __forceinline__ f32x4 mfma16(bf16x8 a, bf16x8 b, f32x4 c) { return __builtin_amdgcn_mfma_f32_16x16x32_bf16(a, b, c, 0, 0, 0); }
; template <int KW, int VD, bool SEL> ...
;     ...
;         if (tiles) { jn = __ffsll((long long)tiles) - 1; tiles &= tiles - 1; FL_ISSUE(cur ^ 1, jn); }
;         const char* sK = smem + cur * BUFB;
;         const char* sV = smem + cur * BUFB + KB;
;         f32x4 s[2][4];
;         const float mref0 = (mrow[0] < -1e29f) ? 0.f : mrow[0], mref1 = (mrow[1] < -1e29f) ? 0.f : mrow[1];
;         const float ci0 = (SEL && !((((const u64*)(smem + 69632))[fr] >> j) & 1ull)) ? -1e30f : -mref0;
;         const float ci1 = (SEL && !((((const u64*)(smem + 69632))[16 + fr] >> j) & 1ull)) ? -1e30f : -mref1;
;         const f32x4 cinit0 = (f32x4){ci0, ci0, ci0, ci0}, cinit1 = (f32x4){ci1, ci1, ci1, ci1};
; #pragma unroll
;         for (int tt = 0; tt < 4; ++tt) {
;             const int kr = 32 * (tt >> 1) + (fr >> 2) * 8 + (tt & 1) * 4 + (fr & 3);
;             const bf16x8 kf0 = *(const bf16x8*)(sK + kr * KROWB + (((kcol >> 3) + fq) ^ kswz) * 16);
;             const bf16x8 kf1 = *(const bf16x8*)(sK + kr * KROWB + (((kcol >> 3) + 4 + fq) ^ kswz) * 16);
;             s[0][tt] = mfma16(kf0, qf[0][0], cinit0);
;             s[1][tt] = mfma16(kf0, qf[1][0], cinit1);
;             s[0][tt] = mfma16(kf1, qf[0][1], s[0][tt]);
;             s[1][tt] = mfma16(kf1, qf[1][1], s[1][tt]);
;         }
.LBB0_373:
	v_add_u32_e32 v72, s12, v129
	ds_read2_b64 v[52:55], v124 offset1:16
	v_add_u32_e32 v141, v72, v125
	ds_read_b128 v[56:59], v141
	s_cmp_lt_i32 s11, 0
	s_cbranch_scc1 .Lfh_sel_nodma
	v_readfirstlane_b32 s13, v123
	s_mul_i32 s14, s11, 0x44000
	s_add_u32 s14, s6, s14
	s_addc_u32 s15, s7, 0
	s_add_u32 s14, s14, 0xc00
	s_addc_u32 s15, s15, 0
	s_lshl_b32 s5, s11, 7
	s_add_u32 s22, s8, s5
	s_addc_u32 s23, s9, 0
	s_xor_b32 s5, s12, 0x4000
	s_add_i32 s5, s5, s13
	s_mov_b32 m0, s5
	s_nop 0
	global_load_lds_dwordx4 v246, s[14:15]
	s_add_i32 m0, s5, 0x1000
	s_nop 0
	global_load_lds_dwordx4 v247, s[14:15]
	s_add_i32 m0, s5, 0x2000
	s_nop 0
	global_load_lds_dwordx4 v248, s[22:23]
	s_add_i32 m0, s5, 0x3000
	s_nop 0
	global_load_lds_dwordx4 v249, s[22:23]
.Lfh_sel_nodma:
	s_lshl_b64 s[0:1], 1, s4
	v_cmp_ngt_f32_e32 vcc, s16, v130
	s_waitcnt lgkmcnt(0)
	v_and_b32_e32 v107, s1, v53
	v_and_b32_e32 v106, s0, v52
	v_and_b32_e32 v3, s1, v55
	v_and_b32_e32 v2, s0, v54
	ds_read_b128 v[52:55], v141 offset:512
	v_cndmask_b32_e32 v171, 0, v130, vcc
	v_cmp_ngt_f32_e32 vcc, s16, v0
	v_add_u32_e32 v166, v72, v126
	ds_read_b128 v[72:75], v166
	ds_read_b128 v[76:79], v166 offset:512
	v_cndmask_b32_e32 v131, 0, v0, vcc
	v_cmp_ne_u64_e32 vcc, 0, v[106:107]
	s_lshl_b32 s13, s4, 6
	s_or_b32 s0, s13, 63
	v_cndmask_b32_e64 v64, v85, -v171, vcc
	v_mov_b32_e32 v65, v64
	v_mov_b32_e32 v66, v64
	v_mov_b32_e32 v67, v64
	v_cmp_ne_u64_e32 vcc, 0, v[2:3]
	s_cmp_le_u32 s0, s21
	v_mfma_f32_16x16x32_bf16 v[60:63], v[56:59], v[4:7], v[64:67]
	v_cndmask_b32_e64 v68, v85, -v131, vcc
	v_mov_b32_e32 v69, v68
	v_mov_b32_e32 v70, v68
	v_mov_b32_e32 v71, v68
	s_waitcnt lgkmcnt(1)
	v_mfma_f32_16x16x32_bf16 v[80:83], v[72:75], v[8:11], v[60:63]
	s_cselect_b64 s[4:5], -1, 0
	s_cmp_gt_u32 s0, s21
	s_mov_b64 s[0:1], -1
	v_mfma_f32_16x16x32_bf16 v[56:59], v[56:59], v[12:15], v[68:71]
	v_mfma_f32_16x16x32_bf16 v[60:63], v[52:55], v[4:7], v[64:67]
	v_mfma_f32_16x16x32_bf16 v[52:55], v[52:55], v[12:15], v[68:71]
	v_mfma_f32_16x16x32_bf16 v[56:59], v[72:75], v[16:19], v[56:59]
	s_waitcnt lgkmcnt(0)
	v_mfma_f32_16x16x32_bf16 v[72:75], v[76:79], v[8:11], v[60:63]
	v_mfma_f32_16x16x32_bf16 v[60:63], v[76:79], v[16:19], v[52:55]
	s_nop 3
	ds_read_b128 v[52:55], v141 offset:4096
	ds_read_b128 v[142:145], v141 offset:4608
	ds_read_b128 v[162:165], v166 offset:4096
	ds_read_b128 v[166:169], v166 offset:4608
	s_waitcnt lgkmcnt(3)
	v_mfma_f32_16x16x32_bf16 v[76:79], v[52:55], v[4:7], v[64:67]
	v_mfma_f32_16x16x32_bf16 v[52:55], v[52:55], v[12:15], v[68:71]
	s_waitcnt lgkmcnt(2)
	v_mfma_f32_16x16x32_bf16 v[64:67], v[142:145], v[4:7], v[64:67]
	v_mfma_f32_16x16x32_bf16 v[142:145], v[142:145], v[12:15], v[68:71]
	s_waitcnt lgkmcnt(1)
	v_mfma_f32_16x16x32_bf16 v[76:79], v[162:165], v[8:11], v[76:79]
	v_mfma_f32_16x16x32_bf16 v[52:55], v[162:165], v[16:19], v[52:55]
	s_waitcnt lgkmcnt(0)
	v_mfma_f32_16x16x32_bf16 v[68:71], v[166:169], v[8:11], v[64:67]
	v_mfma_f32_16x16x32_bf16 v[64:67], v[166:169], v[16:19], v[142:145]
	s_cbranch_scc1 .LBB0_375
	s_mov_b64 s[0:1], 0

; template <int KW, int VD, bool SEL> ...
;     ...
;             float mx = fmaxf(fmaxf(s[qt][0][0], s[qt][0][1]), fmaxf(s[qt][0][2], s[qt][0][3]));
; #pragma unroll
;             for (int tt = 1; tt < 4; ++tt) mx = fmaxf(mx, fmaxf(fmaxf(s[qt][tt][0], s[qt][tt][1]), fmaxf(s[qt][tt][2], s[qt][tt][3])));
;             const float mref = qt ? mref1 : mref0;
;             if (__builtin_amdgcn_ballot_w64(mx > (mrow[qt] - mref) + 8.0f) != 0ull) {
;                 mx = fmaxf(mx, __shfl_xor(mx, 16));
;                 mx = fmaxf(mx, __shfl_xor(mx, 32));
;                 const float mnew = fmaxf(mrow[qt], mx + mref);
;                 const float alpha = __builtin_amdgcn_exp2f(mrow[qt] - mnew);
;                 const float delta = ((mnew < -1e29f) ? 0.f : mnew) - mref;
;                 lrow[qt] *= alpha;
;                 mrow[qt] = mnew;
; #pragma unroll
;                 for (int dt = 0; dt < VD / 16; ++dt) O[qt][dt] = O[qt][dt] * alpha;
; #pragma unroll
;                 for (int tt = 0; tt < 4; ++tt)
; #pragma unroll
;                     for (int jj = 0; jj < 4; ++jj) s[qt][tt][jj] -= delta;
;             }
.LBB0_377:
	v_max3_f32 v106, v68, v69, v70
	v_max3_f32 v107, v71, v72, v73
	v_max3_f32 v106, v106, v74, v75
	v_max3_f32 v107, v107, v76, v77
	v_max3_f32 v106, v106, v78, v79
	v_max3_f32 v107, v107, v80, v81
	v_max3_f32 v106, v106, v82, v83
	v_max_f32_e32 v106, v106, v107
	v_sub_f32_e32 v107, v130, v171
	v_add_f32_e32 v107, 0x41000000, v107
	v_cmp_gt_f32_e32 vcc, v106, v107
	s_cbranch_vccz .LBB0_379
	ds_bpermute_b32 v107, v119, v106
	v_max_f32_e32 v106, v106, v106
	v_max_f32_e32 v172, v130, v130
	s_waitcnt lgkmcnt(0)
	v_max_f32_e32 v107, v107, v107
	v_max_f32_e32 v106, v106, v107
	ds_bpermute_b32 v107, v118, v106
	s_waitcnt lgkmcnt(0)
	v_max_f32_e32 v107, v107, v107
	v_max_f32_e32 v106, v106, v107
	v_add_f32_e32 v106, v171, v106
	v_max_f32_e32 v107, v172, v106
	v_sub_f32_e32 v106, v130, v107
	v_exp_f32_e32 v106, v106
	v_cmp_ngt_f32_e32 vcc, s16, v107
	v_mul_f32_e32 v105, v105, v106
	s_nop 0
	v_cndmask_b32_e32 v130, 0, v107, vcc
	v_pk_mul_f32 v[50:51], v[50:51], v[106:107] op_sel_hi:[1,0]
	v_pk_mul_f32 v[48:49], v[48:49], v[106:107] op_sel_hi:[1,0]
	v_pk_mul_f32 v[46:47], v[46:47], v[106:107] op_sel_hi:[1,0]
	v_pk_mul_f32 v[44:45], v[44:45], v[106:107] op_sel_hi:[1,0]
	v_pk_mul_f32 v[42:43], v[42:43], v[106:107] op_sel_hi:[1,0]
	v_pk_mul_f32 v[40:41], v[40:41], v[106:107] op_sel_hi:[1,0]
	v_pk_mul_f32 v[38:39], v[38:39], v[106:107] op_sel_hi:[1,0]
	v_pk_mul_f32 v[36:37], v[36:37], v[106:107] op_sel_hi:[1,0]
	v_sub_f32_e32 v106, v130, v171
	v_pk_add_f32 v[80:81], v[80:81], v[106:107] op_sel_hi:[1,0] neg_lo:[0,1] neg_hi:[0,1]
	v_pk_add_f32 v[82:83], v[82:83], v[106:107] op_sel_hi:[1,0] neg_lo:[0,1] neg_hi:[0,1]
	v_pk_add_f32 v[72:73], v[72:73], v[106:107] op_sel_hi:[1,0] neg_lo:[0,1] neg_hi:[0,1]
	v_pk_add_f32 v[74:75], v[74:75], v[106:107] op_sel_hi:[1,0] neg_lo:[0,1] neg_hi:[0,1]
	v_pk_add_f32 v[76:77], v[76:77], v[106:107] op_sel_hi:[1,0] neg_lo:[0,1] neg_hi:[0,1]
	v_pk_add_f32 v[78:79], v[78:79], v[106:107] op_sel_hi:[1,0] neg_lo:[0,1] neg_hi:[0,1]
	v_pk_add_f32 v[68:69], v[68:69], v[106:107] op_sel_hi:[1,0] neg_lo:[0,1] neg_hi:[0,1]
	v_pk_add_f32 v[70:71], v[70:71], v[106:107] op_sel_hi:[1,0] neg_lo:[0,1] neg_hi:[0,1]
	v_mov_b32_e32 v130, v107

; template <int KW, int VD, bool SEL> ...
;     ...
;             float mx = fmaxf(fmaxf(s[qt][0][0], s[qt][0][1]), fmaxf(s[qt][0][2], s[qt][0][3]));
; #pragma unroll
;             for (int tt = 1; tt < 4; ++tt) mx = fmaxf(mx, fmaxf(fmaxf(s[qt][tt][0], s[qt][tt][1]), fmaxf(s[qt][tt][2], s[qt][tt][3])));
;             const float mref = qt ? mref1 : mref0;
;             if (__builtin_amdgcn_ballot_w64(mx > (mrow[qt] - mref) + 8.0f) != 0ull) {
;                 mx = fmaxf(mx, __shfl_xor(mx, 16));
;                 mx = fmaxf(mx, __shfl_xor(mx, 32));
;                 const float mnew = fmaxf(mrow[qt], mx + mref);
;                 const float alpha = __builtin_amdgcn_exp2f(mrow[qt] - mnew);
;                 const float delta = ((mnew < -1e29f) ? 0.f : mnew) - mref;
;                 lrow[qt] *= alpha;
;                 mrow[qt] = mnew;
; #pragma unroll
;                 for (int dt = 0; dt < VD / 16; ++dt) O[qt][dt] = O[qt][dt] * alpha;
; #pragma unroll
;                 for (int tt = 0; tt < 4; ++tt)
; #pragma unroll
;                     for (int jj = 0; jj < 4; ++jj) s[qt][tt][jj] -= delta;
;             }
.LBB0_383:
	v_max3_f32 v2, v52, v53, v54
	v_max3_f32 v3, v55, v56, v57
	v_max3_f32 v2, v2, v58, v59
	v_max3_f32 v3, v3, v60, v61
	v_max3_f32 v2, v2, v62, v63
	v_max3_f32 v3, v3, v64, v65
	v_max3_f32 v2, v2, v66, v67
	v_max_f32_e32 v2, v2, v3
	v_sub_f32_e32 v3, v0, v131
	v_add_f32_e32 v3, 0x41000000, v3
	v_cmp_gt_f32_e32 vcc, v2, v3
	s_cbranch_vccz .LBB0_385
	ds_bpermute_b32 v3, v119, v2
	v_max_f32_e32 v2, v2, v2
	v_max_f32_e32 v106, v0, v0
	s_waitcnt lgkmcnt(0)
	v_max_f32_e32 v3, v3, v3
	v_max_f32_e32 v2, v2, v3
	ds_bpermute_b32 v3, v118, v2
	s_waitcnt lgkmcnt(0)
	v_max_f32_e32 v3, v3, v3
	v_max_f32_e32 v2, v2, v3
	v_add_f32_e32 v2, v131, v2
	v_max_f32_e32 v2, v106, v2
	v_sub_f32_e32 v0, v0, v2
	v_exp_f32_e32 v0, v0
	v_cmp_ngt_f32_e32 vcc, s16, v2
	v_mul_f32_e32 v104, v104, v0
	s_nop 0
	v_cndmask_b32_e32 v3, 0, v2, vcc
	v_pk_mul_f32 v[34:35], v[34:35], v[0:1] op_sel_hi:[1,0]
	v_pk_mul_f32 v[32:33], v[32:33], v[0:1] op_sel_hi:[1,0]
	v_pk_mul_f32 v[30:31], v[30:31], v[0:1] op_sel_hi:[1,0]
	v_pk_mul_f32 v[28:29], v[28:29], v[0:1] op_sel_hi:[1,0]
	v_pk_mul_f32 v[26:27], v[26:27], v[0:1] op_sel_hi:[1,0]
	v_pk_mul_f32 v[24:25], v[24:25], v[0:1] op_sel_hi:[1,0]
	v_pk_mul_f32 v[22:23], v[22:23], v[0:1] op_sel_hi:[1,0]
	v_pk_mul_f32 v[20:21], v[20:21], v[0:1] op_sel_hi:[1,0]
	v_sub_f32_e32 v0, v3, v131
	v_pk_add_f32 v[56:57], v[56:57], v[0:1] op_sel_hi:[1,0] neg_lo:[0,1] neg_hi:[0,1]
	v_pk_add_f32 v[58:59], v[58:59], v[0:1] op_sel_hi:[1,0] neg_lo:[0,1] neg_hi:[0,1]
	v_pk_add_f32 v[60:61], v[60:61], v[0:1] op_sel_hi:[1,0] neg_lo:[0,1] neg_hi:[0,1]
	v_pk_add_f32 v[62:63], v[62:63], v[0:1] op_sel_hi:[1,0] neg_lo:[0,1] neg_hi:[0,1]
	v_pk_add_f32 v[52:53], v[52:53], v[0:1] op_sel_hi:[1,0] neg_lo:[0,1] neg_hi:[0,1]
	v_pk_add_f32 v[54:55], v[54:55], v[0:1] op_sel_hi:[1,0] neg_lo:[0,1] neg_hi:[0,1]
	v_pk_add_f32 v[64:65], v[64:65], v[0:1] op_sel_hi:[1,0] neg_lo:[0,1] neg_hi:[0,1]
	v_pk_add_f32 v[66:67], v[66:67], v[0:1] op_sel_hi:[1,0] neg_lo:[0,1] neg_hi:[0,1]
	v_mov_b32_e32 v0, v2

; __device__ __forceinline__ f32x4 zero4() { return (f32x4){0.f, 0.f, 0.f, 0.f}; }
; #define NSA_GATE(qt, br) sigmoidf_(glog[qt][br])
; template <int KW, int VD, bool SEL> ...
;     ...
;     int koff[NKI], voff[NVI];
; #pragma unroll
;     for (int i = 0; i < NKI; ++i) {
;         const int row = (w + 4 * i) * KRPI + lane / KCPR, cp = lane % KCPR;
;         const int f = (KW == 64) ? (((row >> 1) & 1) | (((row >> 3) & 1) << 1) | (((row >> 4) & 1) << 2)) : ((row & 3) | (((row >> 3) & 3) << 2));
;         koff[i] = row * ldk + (cp ^ f) * 8;
;     }
; #pragma unroll
;     for (int i = 0; i < NVI; ++i) {
;         const int row = (w + 4 * i) * 8 + (lane >> 3), cp = lane & 7;
;         voff[i] = row * S + (cp ^ ((row >> 1) & 7)) * 8;
;     }
;     ...
;     int j = __ffsll((long long)tiles) - 1; tiles &= tiles - 1;
;     FL_ISSUE(0, j);
;     asm volatile("s_waitcnt vmcnt(0)" ::: "memory");
;     __syncthreads();
; __device__ __forceinline__ void nsa_tile(const Params& p, int qb, int bg, char* smem) {
;     ...
;         for (int qt = 0; qt < 2; ++qt) {
;             const float sc = NSA_GATE(qt, 1) / lr[qt];
; #pragma unroll
;             for (int dt = 0; dt < 4; ++dt) ((f32x4*)park)[(qt * 4 + dt) * 256 + tid] = ((f32x4*)park)[(qt * 4 + dt) * 256 + tid] + O[qt][dt] * sc;
;         }
;     }
;     {
;         f32x4 O[2][4];
; #pragma unroll
;         for (int qt = 0; qt < 2; ++qt)
; #pragma unroll
;             for (int dt = 0; dt < 4; ++dt) O[qt][dt] = zero4();
;         float mr[2] = {-1e30f, -1e30f}, lr[2] = {0.f, 0.f};
;         const int lo[2] = {tpos[0] - 512, tpos[1] - 512};
;         const u64 ones[2] = {~0ull, ~0ull};
;         int jlo = t0 - 511; jlo = jlo < 0 ? 0 : (jlo >> 6);
;         const u64 upto = (cur0 == 63) ? ~0ull : ((1ull << (cur0 + 1)) - 1ull);
;         const u64 tiles = upto & ~((1ull << jlo) - 1ull);
;         flash_branch<64, 64, false>(tiles, projA + (size_t)b * S * LDA + 1792 + g * 64, LDA, projVT + ((size_t)b * 512 + 256 + g * 64) * S, 0,
;                                     qf, O, mr, lr, tpos, ones, lo, t0, t0 + 31 - 512, smem);
.LBB0_388:
	v_and_b32_e32 v0, 0xffff0000, v120
	v_mul_f32_e32 v0, 0xbfb8aa3b, v0
	v_exp_f32_e32 v0, v0
	v_lshlrev_b32_e32 v60, 16, v111
	ds_read_b128 v[52:55], v122 offset:36864
	ds_read_b128 v[56:59], v122 offset:40960
	v_readlane_b32 s3, v244, 15
	v_add_f32_e32 v0, 1.0, v0
	v_rcp_f32_e32 v0, v0
	s_lshr_b32 s2, s3, 1
	v_div_scale_f32 v61, s[0:1], v3, v3, v0
	v_rcp_f32_e32 v62, v61
	v_div_scale_f32 v63, vcc, v0, v3, v0
	v_fma_f32 v64, -v61, v62, 1.0
	v_fmac_f32_e32 v62, v64, v62
	v_mul_f32_e32 v64, v63, v62
	v_fma_f32 v65, -v61, v64, v63
	v_fmac_f32_e32 v64, v65, v62
	v_fma_f32 v61, -v61, v64, v63
	v_div_fmas_f32 v61, v61, v62, v64
	v_div_fixup_f32 v0, v61, v3, v0
	v_mul_f32_e32 v3, 0xbfb8aa3b, v60
	v_exp_f32_e32 v3, v3
	s_waitcnt lgkmcnt(1)
	v_pk_fma_f32 v[50:51], v[50:51], v[0:1], v[54:55] op_sel_hi:[1,0,1]
	v_pk_fma_f32 v[48:49], v[48:49], v[0:1], v[52:53] op_sel_hi:[1,0,1]
	ds_write_b128 v122, v[48:51] offset:36864
	ds_read_b128 v[48:51], v122 offset:45056
	v_add_f32_e32 v3, 1.0, v3
	v_rcp_f32_e32 v3, v3
	s_waitcnt lgkmcnt(2)
	v_pk_fma_f32 v[46:47], v[46:47], v[0:1], v[58:59] op_sel_hi:[1,0,1]
	v_pk_fma_f32 v[44:45], v[44:45], v[0:1], v[56:57] op_sel_hi:[1,0,1]
	ds_write_b128 v122, v[44:47] offset:40960
	ds_read_b128 v[44:47], v122 offset:49152
	s_waitcnt lgkmcnt(2)
	v_pk_fma_f32 v[42:43], v[42:43], v[0:1], v[50:51] op_sel_hi:[1,0,1]
	v_pk_fma_f32 v[40:41], v[40:41], v[0:1], v[48:49] op_sel_hi:[1,0,1]
	ds_write_b128 v122, v[40:43] offset:45056
	v_div_scale_f32 v40, s[0:1], v2, v2, v3
	v_rcp_f32_e32 v41, v40
	s_waitcnt lgkmcnt(1)
	v_pk_fma_f32 v[38:39], v[38:39], v[0:1], v[46:47] op_sel_hi:[1,0,1]
	v_pk_fma_f32 v[36:37], v[36:37], v[0:1], v[44:45] op_sel_hi:[1,0,1]
	ds_write_b128 v122, v[36:39] offset:49152
	v_fma_f32 v0, -v40, v41, 1.0
	v_fmac_f32_e32 v41, v0, v41
	v_div_scale_f32 v0, vcc, v3, v2, v3
	v_mul_f32_e32 v42, v0, v41
	v_fma_f32 v36, -v40, v42, v0
	v_fmac_f32_e32 v42, v36, v41
	ds_read_b128 v[36:39], v122 offset:53248
	v_fma_f32 v0, -v40, v42, v0
	s_add_i32 s0, s21, 0xfffffe01
	v_div_fmas_f32 v0, v0, v41, v42
	s_ashr_i32 s0, s0, 6
	v_div_fixup_f32 v0, v0, v2, v3
	s_cmp_gt_u32 s3, 15
	s_waitcnt lgkmcnt(0)
	v_pk_fma_f32 v[34:35], v[34:35], v[0:1], v[38:39] op_sel_hi:[1,0,1]
	v_pk_fma_f32 v[32:33], v[32:33], v[0:1], v[36:37] op_sel_hi:[1,0,1]
	s_cselect_b32 s3, s0, 0
	s_add_i32 s0, s2, 1
	ds_read_b128 v[40:43], v122 offset:57344
	ds_read_b128 v[36:39], v121 offset:28672
	ds_write_b128 v122, v[32:35] offset:53248
	ds_read_b128 v[32:35], v122 offset:61440
	s_lshl_b64 s[0:1], -1, s0
	s_not_b64 s[0:1], s[0:1]
	s_cmp_lg_u32 s2, 63
	s_cselect_b32 s1, s1, -1
	s_cselect_b32 s0, s0, -1
	s_lshl_b64 s[2:3], -1, s3
	s_and_b64 s[0:1], s[2:3], s[0:1]
	s_waitcnt lgkmcnt(3)
	v_pk_fma_f32 v[30:31], v[30:31], v[0:1], v[42:43] op_sel_hi:[1,0,1]
	v_pk_fma_f32 v[28:29], v[28:29], v[0:1], v[40:41] op_sel_hi:[1,0,1]
	s_waitcnt lgkmcnt(0)
	v_pk_fma_f32 v[26:27], v[26:27], v[0:1], v[34:35] op_sel_hi:[1,0,1]
	v_pk_fma_f32 v[24:25], v[24:25], v[0:1], v[32:33] op_sel_hi:[1,0,1]
	v_pk_fma_f32 v[22:23], v[22:23], v[0:1], v[38:39] op_sel_hi:[1,0,1]
	v_pk_fma_f32 v[20:21], v[20:21], v[0:1], v[36:37] op_sel_hi:[1,0,1]
	v_mov_b32_e32 v0, v114
	s_cmp_eq_u64 s[0:1], 0
	ds_write_b128 v122, v[28:31] offset:57344
	ds_write_b128 v122, v[24:27] offset:61440
	ds_write_b128 v121, v[20:23] offset:28672
	s_cbranch_scc1 .LBB0_337
	v_ashrrev_i32_e32 v2, 6, v0
	s_add_u32 s8, s8, 0x200000
	v_bfe_u32 v3, v0, 3, 3
	v_bfe_u32 v21, v0, 4, 1
	v_lshlrev_b32_e32 v22, 1, v2
	s_addc_u32 s9, s9, 0
	s_add_i32 s10, s21, 0xfffffe1f
	v_lshl_or_b32 v3, v2, 3, v3
	v_and_b32_e32 v20, 7, v0
	v_and_or_b32 v21, v22, 2, v21
	v_and_b32_e32 v22, 4, v22
	s_movk_i32 s2, 0x880
	v_bitop3_b32 v20, v21, v20, v22 bitop3:0x36
	v_mul_lo_u32 v21, v3, s2
	s_ff1_i32_b64 s4, s[0:1]
	s_add_u32 s2, s0, -1
	v_lshl_or_b32 v96, v20, 3, v21
	v_lshlrev_b32_e32 v20, 12, v3
	v_lshrrev_b32_e32 v3, 1, v3
	s_addc_u32 s3, s1, -1
	s_mul_i32 s5, s4, 0x44000
	v_xor_b32_e32 v3, v3, v0
	s_add_u32 s12, s6, s5
	v_lshlrev_b32_e32 v3, 3, v3
	v_lshlrev_b32_e32 v106, 10, v2
	s_addc_u32 s13, s7, 0
	v_ashrrev_i32_e32 v97, 31, v96
	v_add_u32_e32 v98, 0x11000, v96
	v_and_or_b32 v100, v3, 56, v20
	v_lshl_add_u64 v[2:3], v[96:97], 1, s[12:13]
	s_mov_b64 s[14:15], 0xe00
	v_readfirstlane_b32 s11, v106
	s_lshl_b32 s5, s4, 7
	v_lshl_add_u64 v[2:3], v[2:3], 0, s[14:15]
	s_mov_b32 m0, s11
	v_ashrrev_i32_e32 v99, 31, v98
	v_add_u32_e32 v20, 0x1000, v106
	global_load_lds_dwordx4 v[2:3], off
	v_lshl_add_u64 v[2:3], v[98:99], 1, s[12:13]
	v_readfirstlane_b32 s11, v20
	s_add_u32 s12, s8, s5
	v_add_u32_e32 v20, 0x2000, v106
	v_add_u32_e32 v102, 0x20000, v100
	v_lshl_add_u64 v[2:3], v[2:3], 0, s[14:15]
	s_mov_b32 m0, s11
	s_addc_u32 s13, s9, 0
	v_ashrrev_i32_e32 v101, 31, v100
	v_readfirstlane_b32 s5, v20
	v_add_u32_e32 v20, 0x3000, v106
	global_load_lds_dwordx4 v[2:3], off
	v_lshl_add_u64 v[2:3], v[100:101], 1, s[12:13]
	s_mov_b32 m0, s5
	v_ashrrev_i32_e32 v103, 31, v102
	v_readfirstlane_b32 s5, v20
	global_load_lds_dwordx4 v[2:3], off
	v_lshl_add_u64 v[2:3], v[102:103], 1, s[12:13]
	s_mov_b32 m0, s5
	v_lshrrev_b32_e32 v20, 1, v0
	global_load_lds_dwordx4 v[2:3], off
	v_bfe_u32 v2, v0, 4, 2
	v_and_b32_e32 v3, 15, v0
	v_bfe_u32 v21, v0, 1, 3
	v_lshlrev_b32_e32 v22, 1, v0
	v_and_b32_e32 v0, 3, v0
	v_bitop3_b32 v20, v2, v20, 7 bitop3:0x78
	s_waitcnt vmcnt(0)
	v_and_or_b32 v0, v22, 24, v0
	v_lshlrev_b32_e32 v123, 4, v20
	v_bitop3_b32 v20, v2, v21, 4 bitop3:0x36
	v_lshlrev_b32_e32 v125, 3, v2
	v_lshlrev_b32_e32 v126, 7, v3
	v_mov_b32_e32 v2, v1
	v_mov_b32_e32 v3, v1
	v_lshlrev_b32_e32 v124, 4, v20
	v_lshlrev_b32_e32 v127, 7, v0
	v_mov_b32_e32 v0, v1
	v_mov_b64_e32 v[22:23], v[2:3]
	v_mov_b64_e32 v[26:27], v[2:3]
	v_mov_b64_e32 v[30:31], v[2:3]
	v_mov_b64_e32 v[34:35], v[2:3]
	v_mov_b64_e32 v[38:39], v[2:3]
	v_mov_b64_e32 v[42:43], v[2:3]
	v_mov_b64_e32 v[46:47], v[2:3]
	v_mov_b64_e32 v[50:51], v[2:3]
	v_add_u32_e32 v107, 0xfffffe00, v94
	v_add_u32_e32 v120, 0xfffffe10, v94
	s_and_b64 s[2:3], s[2:3], s[0:1]
	s_mov_b32 s11, 0
	v_mov_b32_e32 v128, 0xf149f2ca
	v_mov_b32_e32 v104, 0
	v_mov_b64_e32 v[20:21], v[0:1]
	v_mov_b64_e32 v[24:25], v[0:1]
	v_mov_b64_e32 v[28:29], v[0:1]
	v_mov_b64_e32 v[32:33], v[0:1]
	v_mov_b64_e32 v[36:37], v[0:1]
	v_mov_b64_e32 v[40:41], v[0:1]
	v_mov_b64_e32 v[44:45], v[0:1]
	v_mov_b64_e32 v[48:49], v[0:1]
	v_mov_b32_e32 v105, 0
	v_mov_b32_e32 v0, 0xf149f2ca
	v_lshlrev_b32_e32 v250, 1, v96
	v_lshlrev_b32_e32 v251, 1, v98
	v_lshlrev_b32_e32 v252, 1, v100
	v_lshlrev_b32_e32 v253, 1, v102
	s_waitcnt vmcnt(0) lgkmcnt(0)
	s_barrier
	s_cmp_lg_u64 s[2:3], 0
	s_cbranch_scc1 .LBB0_392
	s_branch .LBB0_391

; template <int KW, int VD, bool SEL> ...
;     ...
;     while (true) {
;         int jn = -1;
;         if (tiles) { jn = __ffsll((long long)tiles) - 1; tiles &= tiles - 1; FL_ISSUE(cur ^ 1, jn); }
.LBB0_392:
	s_add_u32 s0, s2, -1
	s_addc_u32 s1, s3, -1
	s_lshl_b32 s13, s11, 14
	s_ff1_i32_b64 s12, s[2:3]
	s_mov_b32 s16, 0xefa18f08
	s_and_b64 s[2:3], s[0:1], s[2:3]
	s_branch .LBB0_394

; __device__ __forceinline__ f32x4 mfma16(bf16x8 a, bf16x8 b, f32x4 c) { return __builtin_amdgcn_mfma_f32_16x16x32_bf16(a, b, c, 0, 0, 0); }
; template <int KW, int VD, bool SEL> ...
;     ...
;         if (tiles) { jn = __ffsll((long long)tiles) - 1; tiles &= tiles - 1; FL_ISSUE(cur ^ 1, jn); }
;         const char* sK = smem + cur * BUFB;
;         const char* sV = smem + cur * BUFB + KB;
;         f32x4 s[2][4];
;         const float mref0 = (mrow[0] < -1e29f) ? 0.f : mrow[0], mref1 = (mrow[1] < -1e29f) ? 0.f : mrow[1];
;         const float ci0 = (SEL && !((((const u64*)(smem + 69632))[fr] >> j) & 1ull)) ? -1e30f : -mref0;
;         const float ci1 = (SEL && !((((const u64*)(smem + 69632))[16 + fr] >> j) & 1ull)) ? -1e30f : -mref1;
;         const f32x4 cinit0 = (f32x4){ci0, ci0, ci0, ci0}, cinit1 = (f32x4){ci1, ci1, ci1, ci1};
; #pragma unroll
;         for (int tt = 0; tt < 4; ++tt) {
;             const int kr = 32 * (tt >> 1) + (fr >> 2) * 8 + (tt & 1) * 4 + (fr & 3);
;             const bf16x8 kf0 = *(const bf16x8*)(sK + kr * KROWB + (((kcol >> 3) + fq) ^ kswz) * 16);
;             const bf16x8 kf1 = *(const bf16x8*)(sK + kr * KROWB + (((kcol >> 3) + 4 + fq) ^ kswz) * 16);
;             s[0][tt] = mfma16(kf0, qf[0][0], cinit0);
;             s[1][tt] = mfma16(kf0, qf[1][0], cinit1);
;             s[0][tt] = mfma16(kf1, qf[0][1], s[0][tt]);
;             s[1][tt] = mfma16(kf1, qf[1][1], s[1][tt]);
;         }
.LBB0_394:
	v_add_u32_e32 v3, s13, v127
	v_add_u32_e32 v129, v3, v123
	ds_read_b128 v[52:55], v129
	ds_read_b128 v[60:63], v129 offset:512
	v_cmp_ngt_f32_e32 vcc, s16, v0
	v_add_u32_e32 v3, v3, v124
	ds_read_b128 v[68:71], v3
	ds_read_b128 v[72:75], v3 offset:512
	s_cmp_lt_i32 s12, 0
	s_cbranch_scc1 .Lfh_win_nodma
	v_readfirstlane_b32 s98, v106
	s_mul_i32 s14, s12, 0x44000
	s_add_u32 s14, s6, s14
	s_addc_u32 s15, s7, 0
	s_add_u32 s14, s14, 0xe00
	s_addc_u32 s15, s15, 0
	s_lshl_b32 s5, s12, 7
	s_add_u32 s22, s8, s5
	s_addc_u32 s23, s9, 0
	s_xor_b32 s5, s13, 0x4000
	s_add_i32 s5, s5, s98
	s_mov_b32 m0, s5
	s_nop 0
	global_load_lds_dwordx4 v250, s[14:15]
	s_add_i32 m0, s5, 0x1000
	s_nop 0
	global_load_lds_dwordx4 v251, s[14:15]
	s_add_i32 m0, s5, 0x2000
	s_nop 0
	global_load_lds_dwordx4 v252, s[22:23]
	s_add_i32 m0, s5, 0x3000
	s_nop 0
	global_load_lds_dwordx4 v253, s[22:23]
.Lfh_win_nodma:
	v_cndmask_b32_e32 v167, 0, v0, vcc
	v_cmp_ngt_f32_e32 vcc, s16, v128
	v_xor_b32_e32 v64, 0x80000000, v167
	v_mov_b32_e32 v65, v64
	v_cndmask_b32_e32 v2, 0, v128, vcc
	v_xor_b32_e32 v76, 0x80000000, v2
	v_mov_b32_e32 v66, v64
	v_mov_b32_e32 v67, v64
	v_mov_b32_e32 v77, v76
	v_mov_b32_e32 v78, v76
	v_mov_b32_e32 v79, v76
	s_waitcnt lgkmcnt(0)
	v_mfma_f32_16x16x32_bf16 v[56:59], v[52:55], v[4:7], v[64:67]
	s_lshl_b32 s14, s4, 6
	s_or_b32 s0, s14, 63
	s_cmp_gt_u32 s0, s21
	v_mfma_f32_16x16x32_bf16 v[52:55], v[52:55], v[12:15], v[76:79]
	s_cselect_b64 s[0:1], -1, 0
	s_cmp_le_i32 s14, s10
	s_cselect_b64 s[4:5], -1, 0
	v_mfma_f32_16x16x32_bf16 v[80:83], v[68:71], v[8:11], v[56:59]
	s_or_b64 s[4:5], s[4:5], s[0:1]
	s_mov_b64 s[0:1], -1
	s_and_b64 vcc, exec, s[4:5]
	v_mfma_f32_16x16x32_bf16 v[56:59], v[68:71], v[16:19], v[52:55]
	v_mfma_f32_16x16x32_bf16 v[52:55], v[60:63], v[4:7], v[64:67]
	v_mfma_f32_16x16x32_bf16 v[68:71], v[72:75], v[8:11], v[52:55]
	s_nop 6
	ds_read_b128 v[52:55], v129 offset:4096
	ds_read_b128 v[142:145], v129 offset:4608
	ds_read_b128 v[162:165], v3 offset:4096
	ds_read_b128 v[168:171], v3 offset:4608
	v_mfma_f32_16x16x32_bf16 v[60:63], v[60:63], v[12:15], v[76:79]
	v_mfma_f32_16x16x32_bf16 v[60:63], v[72:75], v[16:19], v[60:63]
	s_waitcnt lgkmcnt(3)
	v_mfma_f32_16x16x32_bf16 v[72:75], v[52:55], v[4:7], v[64:67]
	v_mfma_f32_16x16x32_bf16 v[52:55], v[52:55], v[12:15], v[76:79]
	s_waitcnt lgkmcnt(2)
	v_mfma_f32_16x16x32_bf16 v[64:67], v[142:145], v[4:7], v[64:67]
	v_mfma_f32_16x16x32_bf16 v[142:145], v[142:145], v[12:15], v[76:79]
	s_waitcnt lgkmcnt(1)
	v_mfma_f32_16x16x32_bf16 v[72:75], v[162:165], v[8:11], v[72:75]
	v_mfma_f32_16x16x32_bf16 v[52:55], v[162:165], v[16:19], v[52:55]
	s_waitcnt lgkmcnt(0)
	v_mfma_f32_16x16x32_bf16 v[76:79], v[168:171], v[8:11], v[64:67]
	v_mfma_f32_16x16x32_bf16 v[64:67], v[168:171], v[16:19], v[142:145]
	s_cbranch_vccnz .LBB0_396
	s_mov_b64 s[0:1], 0

; template <int KW, int VD, bool SEL> ...
;     ...
;             float mx = fmaxf(fmaxf(s[qt][0][0], s[qt][0][1]), fmaxf(s[qt][0][2], s[qt][0][3]));
; #pragma unroll
;             for (int tt = 1; tt < 4; ++tt) mx = fmaxf(mx, fmaxf(fmaxf(s[qt][tt][0], s[qt][tt][1]), fmaxf(s[qt][tt][2], s[qt][tt][3])));
;             const float mref = qt ? mref1 : mref0;
;             if (__builtin_amdgcn_ballot_w64(mx > (mrow[qt] - mref) + 8.0f) != 0ull) {
;                 mx = fmaxf(mx, __shfl_xor(mx, 16));
;                 mx = fmaxf(mx, __shfl_xor(mx, 32));
;                 const float mnew = fmaxf(mrow[qt], mx + mref);
;                 const float alpha = __builtin_amdgcn_exp2f(mrow[qt] - mnew);
;                 const float delta = ((mnew < -1e29f) ? 0.f : mnew) - mref;
;                 lrow[qt] *= alpha;
;                 mrow[qt] = mnew;
; #pragma unroll
;                 for (int dt = 0; dt < VD / 16; ++dt) O[qt][dt] = O[qt][dt] * alpha;
; #pragma unroll
;                 for (int tt = 0; tt < 4; ++tt)
; #pragma unroll
;                     for (int jj = 0; jj < 4; ++jj) s[qt][tt][jj] -= delta;
;             }
.LBB0_398:
	v_max3_f32 v168, v68, v69, v70
	v_max3_f32 v169, v71, v72, v73
	v_max3_f32 v168, v168, v74, v75
	v_max3_f32 v169, v169, v76, v77
	v_max3_f32 v168, v168, v78, v79
	v_max3_f32 v169, v169, v80, v81
	v_max3_f32 v168, v168, v82, v83
	v_max_f32_e32 v168, v168, v169
	v_sub_f32_e32 v169, v0, v167
	v_add_f32_e32 v169, 0x41000000, v169
	v_cmp_gt_f32_e32 vcc, v168, v169
	s_cbranch_vccz .LBB0_400
	ds_bpermute_b32 v169, v119, v168
	v_max_f32_e32 v168, v168, v168
	v_max_f32_e32 v170, v0, v0
	s_waitcnt lgkmcnt(0)
	v_max_f32_e32 v169, v169, v169
	v_max_f32_e32 v168, v168, v169
	ds_bpermute_b32 v169, v118, v168
	s_waitcnt lgkmcnt(0)
	v_max_f32_e32 v169, v169, v169
	v_max_f32_e32 v168, v168, v169
	v_add_f32_e32 v168, v167, v168
	v_max_f32_e32 v168, v170, v168
	v_sub_f32_e32 v0, v0, v168
	v_exp_f32_e32 v0, v0
	v_cmp_ngt_f32_e32 vcc, s16, v168
	v_mul_f32_e32 v105, v105, v0
	s_nop 0
	v_cndmask_b32_e32 v169, 0, v168, vcc
	v_pk_mul_f32 v[50:51], v[50:51], v[0:1] op_sel_hi:[1,0]
	v_pk_mul_f32 v[48:49], v[48:49], v[0:1] op_sel_hi:[1,0]
	v_pk_mul_f32 v[46:47], v[46:47], v[0:1] op_sel_hi:[1,0]
	v_pk_mul_f32 v[44:45], v[44:45], v[0:1] op_sel_hi:[1,0]
	v_pk_mul_f32 v[42:43], v[42:43], v[0:1] op_sel_hi:[1,0]
	v_pk_mul_f32 v[40:41], v[40:41], v[0:1] op_sel_hi:[1,0]
	v_pk_mul_f32 v[38:39], v[38:39], v[0:1] op_sel_hi:[1,0]
	v_pk_mul_f32 v[36:37], v[36:37], v[0:1] op_sel_hi:[1,0]
	v_sub_f32_e32 v0, v169, v167
	v_pk_add_f32 v[80:81], v[80:81], v[0:1] op_sel_hi:[1,0] neg_lo:[0,1] neg_hi:[0,1]
	v_pk_add_f32 v[82:83], v[82:83], v[0:1] op_sel_hi:[1,0] neg_lo:[0,1] neg_hi:[0,1]
	v_pk_add_f32 v[68:69], v[68:69], v[0:1] op_sel_hi:[1,0] neg_lo:[0,1] neg_hi:[0,1]
	v_pk_add_f32 v[70:71], v[70:71], v[0:1] op_sel_hi:[1,0] neg_lo:[0,1] neg_hi:[0,1]
	v_pk_add_f32 v[72:73], v[72:73], v[0:1] op_sel_hi:[1,0] neg_lo:[0,1] neg_hi:[0,1]
	v_pk_add_f32 v[74:75], v[74:75], v[0:1] op_sel_hi:[1,0] neg_lo:[0,1] neg_hi:[0,1]
	v_pk_add_f32 v[76:77], v[76:77], v[0:1] op_sel_hi:[1,0] neg_lo:[0,1] neg_hi:[0,1]
	v_pk_add_f32 v[78:79], v[78:79], v[0:1] op_sel_hi:[1,0] neg_lo:[0,1] neg_hi:[0,1]
	v_mov_b32_e32 v0, v168

; template <int KW, int VD, bool SEL> ...
;     ...
;             float mx = fmaxf(fmaxf(s[qt][0][0], s[qt][0][1]), fmaxf(s[qt][0][2], s[qt][0][3]));
; #pragma unroll
;             for (int tt = 1; tt < 4; ++tt) mx = fmaxf(mx, fmaxf(fmaxf(s[qt][tt][0], s[qt][tt][1]), fmaxf(s[qt][tt][2], s[qt][tt][3])));
;             const float mref = qt ? mref1 : mref0;
;             if (__builtin_amdgcn_ballot_w64(mx > (mrow[qt] - mref) + 8.0f) != 0ull) {
;                 mx = fmaxf(mx, __shfl_xor(mx, 16));
;                 mx = fmaxf(mx, __shfl_xor(mx, 32));
;                 const float mnew = fmaxf(mrow[qt], mx + mref);
;                 const float alpha = __builtin_amdgcn_exp2f(mrow[qt] - mnew);
;                 const float delta = ((mnew < -1e29f) ? 0.f : mnew) - mref;
;                 lrow[qt] *= alpha;
;                 mrow[qt] = mnew;
; #pragma unroll
;                 for (int dt = 0; dt < VD / 16; ++dt) O[qt][dt] = O[qt][dt] * alpha;
; #pragma unroll
;                 for (int tt = 0; tt < 4; ++tt)
; #pragma unroll
;                     for (int jj = 0; jj < 4; ++jj) s[qt][tt][jj] -= delta;
;             }
.LBB0_404:
	v_max3_f32 v3, v52, v53, v54
	v_max3_f32 v129, v55, v56, v57
	v_max3_f32 v3, v3, v58, v59
	v_max3_f32 v129, v129, v60, v61
	v_max3_f32 v3, v3, v62, v63
	v_max3_f32 v129, v129, v64, v65
	v_max3_f32 v3, v3, v66, v67
	v_max_f32_e32 v3, v3, v129
	v_sub_f32_e32 v129, v128, v2
	v_add_f32_e32 v129, 0x41000000, v129
	v_cmp_gt_f32_e32 vcc, v3, v129
	s_cbranch_vccz .LBB0_406
	ds_bpermute_b32 v129, v119, v3
	v_max_f32_e32 v3, v3, v3
	v_max_f32_e32 v130, v128, v128
	s_waitcnt lgkmcnt(0)
	v_max_f32_e32 v129, v129, v129
	v_max_f32_e32 v3, v3, v129
	ds_bpermute_b32 v129, v118, v3
	s_waitcnt lgkmcnt(0)
	v_max_f32_e32 v129, v129, v129
	v_max_f32_e32 v3, v3, v129
	v_add_f32_e32 v3, v2, v3
	v_max_f32_e32 v3, v130, v3
	v_sub_f32_e32 v128, v128, v3
	v_exp_f32_e32 v128, v128
	v_cmp_ngt_f32_e32 vcc, s16, v3
	v_mul_f32_e32 v104, v104, v128
	s_nop 0
	v_cndmask_b32_e32 v129, 0, v3, vcc
	v_sub_f32_e32 v2, v129, v2
	v_pk_mul_f32 v[34:35], v[34:35], v[128:129] op_sel_hi:[1,0]
	v_pk_mul_f32 v[32:33], v[32:33], v[128:129] op_sel_hi:[1,0]
	v_pk_mul_f32 v[30:31], v[30:31], v[128:129] op_sel_hi:[1,0]
	v_pk_mul_f32 v[28:29], v[28:29], v[128:129] op_sel_hi:[1,0]
	v_pk_mul_f32 v[26:27], v[26:27], v[128:129] op_sel_hi:[1,0]
	v_pk_mul_f32 v[24:25], v[24:25], v[128:129] op_sel_hi:[1,0]
	v_pk_mul_f32 v[22:23], v[22:23], v[128:129] op_sel_hi:[1,0]
	v_pk_mul_f32 v[20:21], v[20:21], v[128:129] op_sel_hi:[1,0]
	v_pk_add_f32 v[56:57], v[56:57], v[2:3] op_sel_hi:[1,0] neg_lo:[0,1] neg_hi:[0,1]
	v_pk_add_f32 v[58:59], v[58:59], v[2:3] op_sel_hi:[1,0] neg_lo:[0,1] neg_hi:[0,1]
	v_pk_add_f32 v[60:61], v[60:61], v[2:3] op_sel_hi:[1,0] neg_lo:[0,1] neg_hi:[0,1]
	v_pk_add_f32 v[62:63], v[62:63], v[2:3] op_sel_hi:[1,0] neg_lo:[0,1] neg_hi:[0,1]
	v_pk_add_f32 v[52:53], v[52:53], v[2:3] op_sel_hi:[1,0] neg_lo:[0,1] neg_hi:[0,1]
	v_pk_add_f32 v[54:55], v[54:55], v[2:3] op_sel_hi:[1,0] neg_lo:[0,1] neg_hi:[0,1]
	v_pk_add_f32 v[64:65], v[64:65], v[2:3] op_sel_hi:[1,0] neg_lo:[0,1] neg_hi:[0,1]
	v_pk_add_f32 v[66:67], v[66:67], v[2:3] op_sel_hi:[1,0] neg_lo:[0,1] neg_hi:[0,1]
	v_mov_b32_e32 v128, v3

; __device__ __forceinline__ f32x4 mfma16(bf16x8 a, bf16x8 b, f32x4 c) { return __builtin_amdgcn_mfma_f32_16x16x32_bf16(a, b, c, 0, 0, 0); }
; template <class Epi>
; __device__ __forceinline__ void gemm_tile(const bf16_t* __restrict__ A, const bf16_t* __restrict__ Bt, int K, int row0, int col0, const Epi& epi, char* smem,
;                                           bool prefetched, bool nvalid, int nrow0, int ncol0) {
;     ...
;     __syncthreads();
;     const int nk = K >> 6;
;     for (int kt = 0; kt < nk; ++kt) {
;         const int cur = kt & 1;
;         if (kt + 1 < nk) GLDS_STAGE(cur ^ 1, pA, pB, kt + 1);
;         const char* cb = smem + cur * 2 * TILE_B;
; #pragma unroll
;         for (int ks = 0; ks < 2; ++ks) {
;             bf16x8 a[4], b[4];
; #pragma unroll
;             for (int m = 0; m < 4; ++m) a[m] = *(const bf16x8*)(cb + offA[m][ks]);
; #pragma unroll
;             for (int n = 0; n < 4; ++n) b[n] = *(const bf16x8*)(cb + offB[n][ks]);
; #pragma unroll
;             for (int m = 0; m < 4; ++m)
; #pragma unroll
;                 for (int n = 0; n < 4; ++n) acc[m][n] = mfma16(b[n], a[m], acc[m][n]);
;         }
;         asm volatile("s_waitcnt vmcnt(0)" ::: "memory");
;         __syncthreads();
.LBB0_460:
	v_readfirstlane_b32 s98, v94
	v_readfirstlane_b32 s99, v95
	v_readfirstlane_b32 s8, v96
	v_readfirstlane_b32 s100, v102
	v_readfirstlane_b32 s101, v103
	v_readfirstlane_b32 s12, v149
	s_nop 3
	s_sub_u32 s13, s8, s98
	s_and_b32 s98, s98, 0xffffff80
	s_and_b32 s100, s100, 0xffffff80
	s_nop 1
	v_subrev_u32_e32 v254, s98, v94
	v_subrev_u32_e32 v255, s100, v102
	s_add_i32 s11, s12, 0x8000
	s_mov_b32 m0, s11
	s_nop 0
	global_load_lds_dwordx4 v254, s[98:99]
	s_add_i32 m0, s11, 0x1000
	s_add_u32 s8, s98, s13
	s_addc_u32 s9, s99, 0
	global_load_lds_dwordx4 v254, s[8:9]
	s_add_i32 m0, s11, 0x2000
	s_add_u32 s8, s8, s13
	s_addc_u32 s9, s9, 0
	global_load_lds_dwordx4 v254, s[8:9]
	ds_read_b128 v[174:177], v110
	ds_read_b128 v[94:97], v87 offset:16384
	ds_read_b128 v[98:101], v87 offset:16896
	ds_read_b128 v[102:105], v87 offset:20480
	ds_read_b128 v[106:109], v87 offset:20992
	ds_read_b128 v[178:181], v110 offset:2048
	ds_read_b128 v[246:249], v110 offset:4096
	ds_read_b128 v[250:253], v110 offset:6144
.Lgk_loop_460:
	s_and_b32 s5, s1, 0x8000
	s_xor_b32 s10, s5, 0x8000
	v_or_b32_e32 v130, s5, v118
	v_add_u32_e32 v131, s5, v111
	s_waitcnt lgkmcnt(6)
	v_mfma_f32_16x16x32_bf16 v[0:3], v[94:97], v[174:177], v[0:3]
	ds_read_b128 v[142:145], v130 offset:16384
	s_add_i32 m0, s11, 0x3000
	s_add_u32 s8, s8, s13
	s_addc_u32 s9, s9, 0
	s_waitcnt lgkmcnt(6)
	v_mfma_f32_16x16x32_bf16 v[4:7], v[98:101], v[174:177], v[4:7]
	global_load_lds_dwordx4 v254, s[8:9]
	s_add_u32 s98, s98, 0x80
	s_addc_u32 s99, s99, 0
	ds_read_b128 v[162:165], v130 offset:16896
	s_waitcnt lgkmcnt(6)
	v_mfma_f32_16x16x32_bf16 v[8:11], v[102:105], v[174:177], v[8:11]
	ds_read_b128 v[166:169], v130 offset:20480
	s_waitcnt lgkmcnt(6)
	v_mfma_f32_16x16x32_bf16 v[12:15], v[106:109], v[174:177], v[12:15]
	ds_read_b128 v[170:173], v130 offset:20992
	ds_read_b128 v[174:177], v131
	s_add_i32 m0, s11, 0x4000
	s_nop 0
	s_waitcnt lgkmcnt(7)
	v_mfma_f32_16x16x32_bf16 v[16:19], v[94:97], v[178:181], v[16:19]
	global_load_lds_dwordx4 v255, s[100:101]
	v_mfma_f32_16x16x32_bf16 v[20:23], v[98:101], v[178:181], v[20:23]
	v_mfma_f32_16x16x32_bf16 v[24:27], v[102:105], v[178:181], v[24:27]
	s_add_i32 m0, s11, 0x5000
	s_add_u32 s8, s100, s13
	s_addc_u32 s9, s101, 0
	v_mfma_f32_16x16x32_bf16 v[28:31], v[106:109], v[178:181], v[28:31]
	global_load_lds_dwordx4 v255, s[8:9]
	ds_read_b128 v[178:181], v131 offset:2048
	s_waitcnt lgkmcnt(7)
	v_mfma_f32_16x16x32_bf16 v[32:35], v[94:97], v[246:249], v[32:35]
	v_mfma_f32_16x16x32_bf16 v[36:39], v[98:101], v[246:249], v[36:39]
	s_add_i32 m0, s11, 0x6000
	s_add_u32 s8, s8, s13
	s_addc_u32 s9, s9, 0
	v_mfma_f32_16x16x32_bf16 v[40:43], v[102:105], v[246:249], v[40:43]
	global_load_lds_dwordx4 v255, s[8:9]
	v_mfma_f32_16x16x32_bf16 v[44:47], v[106:109], v[246:249], v[44:47]
	ds_read_b128 v[246:249], v131 offset:4096
	s_waitcnt lgkmcnt(7)
	v_mfma_f32_16x16x32_bf16 v[48:51], v[94:97], v[250:253], v[48:51]
	s_add_i32 m0, s11, 0x7000
	s_add_u32 s8, s8, s13
	s_addc_u32 s9, s9, 0
	v_mfma_f32_16x16x32_bf16 v[52:55], v[98:101], v[250:253], v[52:55]
	global_load_lds_dwordx4 v255, s[8:9]
	s_add_u32 s100, s100, 0x80
	s_addc_u32 s101, s101, 0
	v_mfma_f32_16x16x32_bf16 v[56:59], v[102:105], v[250:253], v[56:59]
	v_mfma_f32_16x16x32_bf16 v[60:63], v[106:109], v[250:253], v[60:63]
	ds_read_b128 v[250:253], v131 offset:6144
	s_waitcnt lgkmcnt(3)
	v_mfma_f32_16x16x32_bf16 v[0:3], v[142:145], v[174:177], v[0:3]
	v_mfma_f32_16x16x32_bf16 v[4:7], v[162:165], v[174:177], v[4:7]
	v_mfma_f32_16x16x32_bf16 v[8:11], v[166:169], v[174:177], v[8:11]
	v_mfma_f32_16x16x32_bf16 v[12:15], v[170:173], v[174:177], v[12:15]
	s_waitcnt lgkmcnt(2)
	v_mfma_f32_16x16x32_bf16 v[16:19], v[142:145], v[178:181], v[16:19]
	v_mfma_f32_16x16x32_bf16 v[20:23], v[162:165], v[178:181], v[20:23]
	v_mfma_f32_16x16x32_bf16 v[24:27], v[166:169], v[178:181], v[24:27]
	v_mfma_f32_16x16x32_bf16 v[28:31], v[170:173], v[178:181], v[28:31]
	s_waitcnt vmcnt(0)
	s_waitcnt lgkmcnt(0)
	s_barrier
	s_add_i32 s1, s1, 0x8000
	s_cmp_eq_u32 s1, 0x78000
	s_cbranch_scc1 .Lgk_tail_460
	v_or_b32_e32 v130, s10, v87
	v_add_u32_e32 v131, s10, v110
	s_add_i32 s11, s5, s12
	ds_read_b128 v[174:177], v131
	ds_read_b128 v[94:97], v130 offset:16384
	s_mov_b32 m0, s11
	s_nop 0
	v_mfma_f32_16x16x32_bf16 v[32:35], v[142:145], v[246:249], v[32:35]
	global_load_lds_dwordx4 v254, s[98:99]
	ds_read_b128 v[98:101], v130 offset:16896
	v_mfma_f32_16x16x32_bf16 v[36:39], v[162:165], v[246:249], v[36:39]
	ds_read_b128 v[102:105], v130 offset:20480
	v_mfma_f32_16x16x32_bf16 v[40:43], v[166:169], v[246:249], v[40:43]
	ds_read_b128 v[106:109], v130 offset:20992
	s_add_i32 m0, s11, 0x1000
	s_add_u32 s8, s98, s13
	s_addc_u32 s9, s99, 0
	v_mfma_f32_16x16x32_bf16 v[44:47], v[170:173], v[246:249], v[44:47]
	global_load_lds_dwordx4 v254, s[8:9]
	ds_read_b128 v[178:181], v131 offset:2048
	ds_read_b128 v[246:249], v131 offset:4096
	v_mfma_f32_16x16x32_bf16 v[48:51], v[142:145], v[250:253], v[48:51]
	v_mfma_f32_16x16x32_bf16 v[52:55], v[162:165], v[250:253], v[52:55]
	s_add_i32 m0, s11, 0x2000
	s_add_u32 s8, s8, s13
	s_addc_u32 s9, s9, 0
	v_mfma_f32_16x16x32_bf16 v[56:59], v[166:169], v[250:253], v[56:59]
	global_load_lds_dwordx4 v254, s[8:9]
	v_mfma_f32_16x16x32_bf16 v[60:63], v[170:173], v[250:253], v[60:63]
	ds_read_b128 v[250:253], v131 offset:6144
	s_branch .Lgk_loop_460

; __device__ __forceinline__ u32x4 pack8(f32x4 a, f32x4 b) { u32x4 r; r.x = cvt_pk_bf16(a[0], a[1]); r.y = cvt_pk_bf16(a[2], a[3]); r.z = cvt_pk_bf16(b[0], b[1]); r.w = cvt_pk_bf16(b[2], b[3]); return r; }
; template <class Epi>
; __device__ __forceinline__ void gemm_tile(const bf16_t* __restrict__ A, const bf16_t* __restrict__ Bt, int K, int row0, int col0, const Epi& epi, char* smem,
;                                           bool prefetched, bool nvalid, int nrow0, int ncol0) {
;     ...
;     if constexpr (Epi::STAGED) {
;         bf16_t* st = (bf16_t*)(smem + 2 * TILE_B);
;         epi.to_lds(acc, st, row0, col0, wr, wc, fr, fq);
;         __syncthreads();
;     __device__ __forceinline__ void to_lds(f32x4 (&acc)[4][4], bf16_t* st, int row0, int col0, int wr, int wc, int fr, int fq) const {
; #pragma unroll
;         for (int m = 0; m < 4; ++m)
; #pragma unroll
;             for (int pp = 0; pp < 2; ++pp) {
;                 f32x4 v0 = acc[m][2 * pp], v1 = acc[m][2 * pp + 1];
; #pragma unroll
;                 for (int j = 0; j < 4; ++j) { const float u0 = fmaxf(v0[j], 0.f), u1 = fmaxf(v1[j], 0.f); v0[j] = u0 * u0; v1[j] = u1 * u1; }
;                 *(u32x4*)(st + (wr * 64 + m * 16 + fr) * 136 + wc * 64 + pp * 32 + 8 * fq) = pack8(v0, v1);
;             }
;     }
.LBB0_557:
	v_max_f32_e32 v48, v48, v48
	v_max_f32_e32 v52, v52, v52
	v_max_f32_e32 v49, v49, v49
	v_max_f32_e32 v53, v53, v53
	v_max_f32_e32 v50, v50, v50
	v_max_f32_e32 v54, v54, v54
	v_max_f32_e32 v51, v51, v51
	v_max_f32_e32 v55, v55, v55
	v_max_f32_e32 v48, 0, v48
	v_max_f32_e32 v52, 0, v52
	v_max_f32_e32 v49, 0, v49
	v_max_f32_e32 v53, 0, v53
	v_max_f32_e32 v50, 0, v50
	v_max_f32_e32 v54, 0, v54
	v_max_f32_e32 v51, 0, v51
	v_max_f32_e32 v55, 0, v55
	v_pk_mul_f32 v[48:49], v[48:49], v[48:49]
	v_pk_mul_f32 v[52:53], v[52:53], v[52:53]
	v_pk_mul_f32 v[50:51], v[50:51], v[50:51]
	v_pk_mul_f32 v[54:55], v[54:55], v[54:55]
	v_max_f32_e32 v40, v40, v40
	v_max_f32_e32 v41, v41, v41
	v_cvt_pk_bf16_f32 v48, v48, v49
	v_cvt_pk_bf16_f32 v49, v50, v51
	v_cvt_pk_bf16_f32 v50, v52, v53
	v_cvt_pk_bf16_f32 v51, v54, v55
	v_max_f32_e32 v40, 0, v40
	v_max_f32_e32 v41, 0, v41
	ds_write_b128 v166, v[48:51] offset:32832
	v_pk_mul_f32 v[48:49], v[40:41], v[40:41]
	v_max_f32_e32 v41, v42, v42
	v_max_f32_e32 v44, v44, v44
	v_max_f32_e32 v45, v45, v45
	v_max_f32_e32 v40, v46, v46
	v_max_f32_e32 v42, 0, v41
	v_max_f32_e32 v41, v47, v47
	v_max_f32_e32 v43, v43, v43
	v_max_f32_e32 v44, 0, v44
	v_max_f32_e32 v45, 0, v45
	v_max_f32_e32 v40, 0, v40
	v_max_f32_e32 v41, 0, v41
	v_max_f32_e32 v43, 0, v43
	v_pk_mul_f32 v[44:45], v[44:45], v[44:45]
	v_pk_mul_f32 v[46:47], v[40:41], v[40:41]
	v_pk_mul_f32 v[50:51], v[42:43], v[42:43]
	v_max_f32_e32 v32, v32, v32
	v_max_f32_e32 v33, v33, v33
	v_cvt_pk_bf16_f32 v40, v44, v45
	v_cvt_pk_bf16_f32 v41, v46, v47
	v_cvt_pk_bf16_f32 v42, v48, v49
	v_cvt_pk_bf16_f32 v43, v50, v51
	v_max_f32_e32 v32, 0, v32
	v_max_f32_e32 v33, 0, v33
	ds_write_b128 v166, v[40:43] offset:37120
	v_pk_mul_f32 v[40:41], v[32:33], v[32:33]
	v_max_f32_e32 v33, v34, v34
	v_max_f32_e32 v36, v36, v36
	v_max_f32_e32 v37, v37, v37
	v_max_f32_e32 v32, v38, v38
	v_max_f32_e32 v34, 0, v33
	v_max_f32_e32 v33, v39, v39
	v_max_f32_e32 v35, v35, v35
	v_max_f32_e32 v36, 0, v36
	v_max_f32_e32 v37, 0, v37
	v_max_f32_e32 v32, 0, v32
	v_max_f32_e32 v33, 0, v33
	v_max_f32_e32 v35, 0, v35
	v_pk_mul_f32 v[36:37], v[36:37], v[36:37]
	v_pk_mul_f32 v[38:39], v[32:33], v[32:33]
	v_pk_mul_f32 v[42:43], v[34:35], v[34:35]
	v_max_f32_e32 v24, v24, v24
	v_max_f32_e32 v25, v25, v25
	v_cvt_pk_bf16_f32 v32, v36, v37
	v_cvt_pk_bf16_f32 v33, v38, v39
	v_cvt_pk_bf16_f32 v34, v40, v41
	v_cvt_pk_bf16_f32 v35, v42, v43
	v_max_f32_e32 v24, 0, v24
	v_max_f32_e32 v25, 0, v25
	ds_write_b128 v166, v[32:35] offset:37184
	v_pk_mul_f32 v[32:33], v[24:25], v[24:25]
	v_max_f32_e32 v25, v26, v26
	v_max_f32_e32 v28, v28, v28
	v_max_f32_e32 v29, v29, v29
	v_max_f32_e32 v24, v30, v30
	v_max_f32_e32 v26, 0, v25
	v_max_f32_e32 v25, v31, v31
	v_max_f32_e32 v27, v27, v27
	v_max_f32_e32 v28, 0, v28
	v_max_f32_e32 v29, 0, v29
	v_max_f32_e32 v24, 0, v24
	v_max_f32_e32 v25, 0, v25
	v_max_f32_e32 v27, 0, v27
	v_pk_mul_f32 v[28:29], v[28:29], v[28:29]
	v_pk_mul_f32 v[30:31], v[24:25], v[24:25]
	v_pk_mul_f32 v[34:35], v[26:27], v[26:27]
	v_max_f32_e32 v16, v16, v16
	v_max_f32_e32 v17, v17, v17
	v_cvt_pk_bf16_f32 v24, v28, v29
	v_cvt_pk_bf16_f32 v25, v30, v31
	v_cvt_pk_bf16_f32 v26, v32, v33
	v_cvt_pk_bf16_f32 v27, v34, v35
	v_max_f32_e32 v16, 0, v16
	v_max_f32_e32 v17, 0, v17
	ds_write_b128 v166, v[24:27] offset:41472
	v_pk_mul_f32 v[24:25], v[16:17], v[16:17]
	v_max_f32_e32 v17, v18, v18
	v_max_f32_e32 v56, v56, v56
	v_max_f32_e32 v60, v60, v60
	v_max_f32_e32 v57, v57, v57
	v_max_f32_e32 v61, v61, v61
	v_max_f32_e32 v58, v58, v58
	v_max_f32_e32 v62, v62, v62
	v_max_f32_e32 v59, v59, v59
	v_max_f32_e32 v63, v63, v63
	v_max_f32_e32 v20, v20, v20
	v_max_f32_e32 v21, v21, v21
	v_max_f32_e32 v16, v22, v22
	v_max_f32_e32 v18, 0, v17
	v_max_f32_e32 v17, v23, v23
	v_max_f32_e32 v19, v19, v19
	v_max_f32_e32 v8, v8, v8
	v_max_f32_e32 v12, v12, v12
	v_max_f32_e32 v9, v9, v9
	v_max_f32_e32 v13, v13, v13
	v_max_f32_e32 v10, v10, v10
	v_max_f32_e32 v14, v14, v14
	v_max_f32_e32 v11, v11, v11
	v_max_f32_e32 v15, v15, v15
	v_max_f32_e32 v0, v0, v0
	v_max_f32_e32 v4, v4, v4
	v_max_f32_e32 v1, v1, v1
	v_max_f32_e32 v5, v5, v5
	v_max_f32_e32 v2, v2, v2
	v_max_f32_e32 v6, v6, v6
	v_max_f32_e32 v3, v3, v3
	v_max_f32_e32 v7, v7, v7
	v_max_f32_e32 v56, 0, v56
	v_max_f32_e32 v60, 0, v60
	v_max_f32_e32 v57, 0, v57
	v_max_f32_e32 v61, 0, v61
	v_max_f32_e32 v58, 0, v58
	v_max_f32_e32 v62, 0, v62
	v_max_f32_e32 v59, 0, v59
	v_max_f32_e32 v63, 0, v63
	v_max_f32_e32 v20, 0, v20
	v_max_f32_e32 v21, 0, v21
	v_max_f32_e32 v16, 0, v16
	v_max_f32_e32 v17, 0, v17
	v_max_f32_e32 v19, 0, v19
	v_max_f32_e32 v8, 0, v8
	v_max_f32_e32 v12, 0, v12
	v_max_f32_e32 v9, 0, v9
	v_max_f32_e32 v13, 0, v13
	v_max_f32_e32 v10, 0, v10
	v_max_f32_e32 v14, 0, v14
	v_max_f32_e32 v11, 0, v11
	v_max_f32_e32 v15, 0, v15
	v_max_f32_e32 v0, 0, v0
	v_max_f32_e32 v4, 0, v4
	v_max_f32_e32 v1, 0, v1
	v_max_f32_e32 v5, 0, v5
	v_max_f32_e32 v2, 0, v2
	v_max_f32_e32 v6, 0, v6
	v_max_f32_e32 v3, 0, v3
	v_max_f32_e32 v7, 0, v7
	v_pk_mul_f32 v[56:57], v[56:57], v[56:57]
	v_pk_mul_f32 v[60:61], v[60:61], v[60:61]
	v_pk_mul_f32 v[58:59], v[58:59], v[58:59]
	v_pk_mul_f32 v[62:63], v[62:63], v[62:63]
	v_pk_mul_f32 v[20:21], v[20:21], v[20:21]
	v_pk_mul_f32 v[22:23], v[16:17], v[16:17]
	v_pk_mul_f32 v[26:27], v[18:19], v[18:19]
	v_pk_mul_f32 v[8:9], v[8:9], v[8:9]
	v_pk_mul_f32 v[12:13], v[12:13], v[12:13]
	v_pk_mul_f32 v[10:11], v[10:11], v[10:11]
	v_pk_mul_f32 v[14:15], v[14:15], v[14:15]
	v_pk_mul_f32 v[0:1], v[0:1], v[0:1]
	v_pk_mul_f32 v[4:5], v[4:5], v[4:5]
	v_pk_mul_f32 v[2:3], v[2:3], v[2:3]
	v_pk_mul_f32 v[6:7], v[6:7], v[6:7]
	s_lshl_b64 s[0:1], s[0:1], 13
	v_readlane_b32 s8, v245, 55
	v_cvt_pk_bf16_f32 v56, v56, v57
	v_cvt_pk_bf16_f32 v57, v58, v59
	v_cvt_pk_bf16_f32 v58, v60, v61
	v_cvt_pk_bf16_f32 v59, v62, v63
	v_cvt_pk_bf16_f32 v16, v20, v21
	v_cvt_pk_bf16_f32 v17, v22, v23
	v_cvt_pk_bf16_f32 v18, v24, v25
	v_cvt_pk_bf16_f32 v19, v26, v27
	v_cvt_pk_bf16_f32 v8, v8, v9
	v_cvt_pk_bf16_f32 v9, v10, v11
	v_cvt_pk_bf16_f32 v10, v12, v13
	v_cvt_pk_bf16_f32 v11, v14, v15
	v_cvt_pk_bf16_f32 v0, v0, v1
	v_cvt_pk_bf16_f32 v1, v2, v3
	v_cvt_pk_bf16_f32 v2, v4, v5
	v_cvt_pk_bf16_f32 v3, v6, v7
	v_readlane_b32 s9, v245, 56
	s_add_u32 s8, s8, s0
	ds_write_b128 v166, v[56:59] offset:32768
	ds_write_b128 v166, v[16:19] offset:41536
	ds_write_b128 v166, v[8:11] offset:45824
	ds_write_b128 v166, v[0:3] offset:45888
	s_waitcnt lgkmcnt(0)
	s_barrier
; template <class Epi>
; __device__ __forceinline__ void gemm_tile(const bf16_t* __restrict__ A, const bf16_t* __restrict__ Bt, int K, int row0, int col0, const Epi& epi, char* smem,
;                                           bool prefetched, bool nvalid, int nrow0, int ncol0) {
;     ...
;         bf16_t* gbase; size_t gstride;
;         epi.dest(row0, col0, gbase, gstride);
;         const int r0 = tid >> 4, ch = (tid & 15) * 8;
; #pragma unroll
;         for (int it = 0; it < 8; ++it) { const int r = it * 16 + r0; __builtin_nontemporal_store(*(const u32x4*)(st + r * 136 + ch), (u32x4*)(gbase + (size_t)r * gstride + ch)); }
	s_addc_u32 s9, s9, s1
	s_lshl_b64 s[0:1], s[4:5], 1
	ds_read_b128 v[0:3], v167 offset:32768
	ds_read_b128 v[4:7], v167 offset:37120
	s_add_u32 s0, s8, s0
	s_addc_u32 s1, s9, s1
	v_lshl_add_u64 v[12:13], s[0:1], 0, v[72:73]
	v_lshl_add_u64 v[8:9], v[74:75], 1, v[12:13]
	s_waitcnt lgkmcnt(1)
	global_store_dwordx4 v[8:9], v[0:3], off nt
	ds_read_b128 v[0:3], v167 offset:41472
	v_lshl_add_u64 v[8:9], v[76:77], 1, v[12:13]
	s_waitcnt lgkmcnt(1)
	global_store_dwordx4 v[8:9], v[4:7], off nt
	ds_read_b128 v[4:7], v167 offset:45824
	v_lshl_add_u64 v[8:9], v[78:79], 1, v[12:13]
	s_waitcnt lgkmcnt(1)
	global_store_dwordx4 v[8:9], v[0:3], off nt
	ds_read_b128 v[0:3], v167 offset:50176
	v_lshl_add_u64 v[8:9], v[80:81], 1, v[12:13]
	s_waitcnt lgkmcnt(1)
	global_store_dwordx4 v[8:9], v[4:7], off nt
	v_lshl_add_u64 v[8:9], v[82:83], 1, v[12:13]
	ds_read_b128 v[4:7], v167 offset:54528
	s_waitcnt lgkmcnt(1)
	global_store_dwordx4 v[8:9], v[0:3], off nt
	ds_read_b128 v[0:3], v167 offset:58880
	ds_read_b128 v[8:11], v167 offset:63232
	v_lshl_add_u64 v[14:15], v[88:89], 1, v[12:13]
	s_waitcnt lgkmcnt(2)
	global_store_dwordx4 v[14:15], v[4:7], off nt
	s_andn2_b64 vcc, exec, s[6:7]
	s_mov_b64 s[10:11], -1
	v_lshl_add_u64 v[4:5], v[90:91], 1, v[12:13]
	s_waitcnt lgkmcnt(1)
	global_store_dwordx4 v[4:5], v[0:3], off nt
	s_nop 1
	v_lshl_add_u64 v[0:1], v[92:93], 1, v[12:13]
	s_waitcnt lgkmcnt(0)
	global_store_dwordx4 v[0:1], v[8:11], off nt
	s_cbranch_vccz .LBB0_566

; __device__ __forceinline__ f32x4 zero4() { return (f32x4){0.f, 0.f, 0.f, 0.f}; }
; template <class Epi>
; __device__ __forceinline__ void gemm_tile(const bf16_t* __restrict__ A, const bf16_t* __restrict__ Bt, int K, int row0, int col0, const Epi& epi, char* smem,
;                                           bool prefetched, bool nvalid, int nrow0, int ncol0) {
;     ...
;     f32x4 acc[4][4];
; #pragma unroll
;     for (int m = 0; m < 4; ++m)
; #pragma unroll
;         for (int n = 0; n < 4; ++n) acc[m][n] = zero4();
;     ...
;     __syncthreads();
;     const int nk = K >> 6;
;     for (int kt = 0; kt < nk; ++kt) {
;         const int cur = kt & 1;
;         if (kt + 1 < nk) GLDS_STAGE(cur ^ 1, pA, pB, kt + 1);
;         const char* cb = smem + cur * 2 * TILE_B;
; #pragma unroll
;         for (int ks = 0; ks < 2; ++ks) {
;             bf16x8 a[4], b[4];
; #pragma unroll
;             for (int m = 0; m < 4; ++m) a[m] = *(const bf16x8*)(cb + offA[m][ks]);
; #pragma unroll
;             for (int n = 0; n < 4; ++n) b[n] = *(const bf16x8*)(cb + offB[n][ks]);
.LBB0_562:
	v_mov_b32_e32 v0, 0
	v_lshl_add_u64 v[110:111], v[94:95], 0, s[6:7]
	v_lshl_add_u64 v[118:119], v[96:97], 0, s[6:7]
	v_lshl_add_u64 v[120:121], v[98:99], 0, s[6:7]
	v_lshl_add_u64 v[122:123], v[100:101], 0, s[6:7]
	v_lshl_add_u64 v[124:125], v[102:103], 0, s[8:9]
	v_lshl_add_u64 v[126:127], v[104:105], 0, s[8:9]
	v_lshl_add_u64 v[128:129], v[106:107], 0, s[8:9]
	v_lshl_add_u64 v[130:131], v[108:109], 0, s[8:9]
	s_mov_b32 s8, 0
	s_mov_b64 s[6:7], 0
	v_mov_b32_e32 v1, v0
	v_mov_b32_e32 v2, v0
	v_mov_b32_e32 v3, v0
	v_mov_b32_e32 v4, v0
	v_mov_b32_e32 v5, v0
	v_mov_b32_e32 v6, v0
	v_mov_b32_e32 v7, v0
	v_mov_b32_e32 v8, v0
	v_mov_b32_e32 v9, v0
	v_mov_b32_e32 v10, v0
	v_mov_b32_e32 v11, v0
	v_mov_b32_e32 v12, v0
	v_mov_b32_e32 v13, v0
	v_mov_b32_e32 v14, v0
	v_mov_b32_e32 v15, v0
	v_mov_b32_e32 v16, v0
	v_mov_b32_e32 v17, v0
	v_mov_b32_e32 v18, v0
	v_mov_b32_e32 v19, v0
	v_mov_b32_e32 v20, v0
	v_mov_b32_e32 v21, v0
	v_mov_b32_e32 v22, v0
	v_mov_b32_e32 v23, v0
	v_mov_b32_e32 v24, v0
	v_mov_b32_e32 v25, v0
	v_mov_b32_e32 v26, v0
	v_mov_b32_e32 v27, v0
	v_mov_b32_e32 v28, v0
	v_mov_b32_e32 v29, v0
	v_mov_b32_e32 v30, v0
	v_mov_b32_e32 v31, v0
	v_mov_b32_e32 v32, v0
	v_mov_b32_e32 v33, v0
	v_mov_b32_e32 v34, v0
	v_mov_b32_e32 v35, v0
	v_mov_b32_e32 v36, v0
	v_mov_b32_e32 v37, v0
	v_mov_b32_e32 v38, v0
	v_mov_b32_e32 v39, v0
	v_mov_b32_e32 v40, v0
	v_mov_b32_e32 v41, v0
	v_mov_b32_e32 v42, v0
	v_mov_b32_e32 v43, v0
	v_mov_b32_e32 v44, v0
	v_mov_b32_e32 v45, v0
	v_mov_b32_e32 v46, v0
	v_mov_b32_e32 v47, v0
	v_mov_b32_e32 v48, v0
	v_mov_b32_e32 v49, v0
	v_mov_b32_e32 v50, v0
	v_mov_b32_e32 v51, v0
	v_mov_b32_e32 v52, v0
	v_mov_b32_e32 v53, v0
	v_mov_b32_e32 v54, v0
	v_mov_b32_e32 v55, v0
	v_mov_b32_e32 v56, v0
	v_mov_b32_e32 v57, v0
	v_mov_b32_e32 v58, v0
	v_mov_b32_e32 v59, v0
	v_mov_b32_e32 v60, v0
	v_mov_b32_e32 v61, v0
	v_mov_b32_e32 v62, v0
	v_mov_b32_e32 v63, v0
	s_waitcnt lgkmcnt(0)
	s_barrier
.LBB0_563:
	v_readfirstlane_b32 s98, v110
	v_readfirstlane_b32 s99, v111
	v_readfirstlane_b32 s10, v118
	v_readfirstlane_b32 s100, v124
	v_readfirstlane_b32 s101, v125
	v_readfirstlane_b32 s17, v149
	s_nop 3
	s_sub_u32 s18, s10, s98
	s_and_b32 s98, s98, 0xffffff80
	s_and_b32 s100, s100, 0xffffff80
	s_nop 1
	v_subrev_u32_e32 v254, s98, v110
	v_subrev_u32_e32 v255, s100, v124
	s_add_i32 s13, s17, 0x8000
	s_mov_b32 m0, s13
	s_nop 0
	global_load_lds_dwordx4 v254, s[98:99]
	s_add_i32 m0, s13, 0x1000
	s_add_u32 s10, s98, s18
	s_addc_u32 s11, s99, 0
	global_load_lds_dwordx4 v254, s[10:11]
	s_add_i32 m0, s13, 0x2000
	s_add_u32 s10, s10, s18
	s_addc_u32 s11, s11, 0
	global_load_lds_dwordx4 v254, s[10:11]
	ds_read_b128 v[192:195], v85
	ds_read_b128 v[118:121], v142 offset:16384
	ds_read_b128 v[122:125], v142 offset:16896
	ds_read_b128 v[126:129], v142 offset:20480
	ds_read_b128 v[172:175], v142 offset:20992
	ds_read_b128 v[196:199], v85 offset:2048
	ds_read_b128 v[246:249], v85 offset:4096
	ds_read_b128 v[250:253], v85 offset:6144
; __device__ __forceinline__ f32x4 mfma16(bf16x8 a, bf16x8 b, f32x4 c) { return __builtin_amdgcn_mfma_f32_16x16x32_bf16(a, b, c, 0, 0, 0); }
; template <class Epi>
; __device__ __forceinline__ void gemm_tile(const bf16_t* __restrict__ A, const bf16_t* __restrict__ Bt, int K, int row0, int col0, const Epi& epi, char* smem,
;                                           bool prefetched, bool nvalid, int nrow0, int ncol0) {
;     ...
;     for (int kt = 0; kt < nk; ++kt) {
;         const int cur = kt & 1;
;         if (kt + 1 < nk) GLDS_STAGE(cur ^ 1, pA, pB, kt + 1);
;         const char* cb = smem + cur * 2 * TILE_B;
; #pragma unroll
;         for (int ks = 0; ks < 2; ++ks) {
;             bf16x8 a[4], b[4];
; #pragma unroll
;             for (int m = 0; m < 4; ++m) a[m] = *(const bf16x8*)(cb + offA[m][ks]);
; #pragma unroll
;             for (int n = 0; n < 4; ++n) b[n] = *(const bf16x8*)(cb + offB[n][ks]);
; #pragma unroll
;             for (int m = 0; m < 4; ++m)
; #pragma unroll
;                 for (int n = 0; n < 4; ++n) acc[m][n] = mfma16(b[n], a[m], acc[m][n]);
;         }
;         asm volatile("s_waitcnt vmcnt(0)" ::: "memory");
;         __syncthreads();
.Lgk_loop_563:
	s_and_b32 s9, s8, 0x8000
	s_xor_b32 s12, s9, 0x8000
	v_or_b32_e32 v110, s9, v141
	v_add_u32_e32 v111, s9, v87
	s_waitcnt lgkmcnt(6)
	v_mfma_f32_16x16x32_bf16 v[0:3], v[118:121], v[192:195], v[0:3]
	ds_read_b128 v[176:179], v110 offset:16384
	s_add_i32 m0, s13, 0x3000
	s_add_u32 s10, s10, s18
	s_addc_u32 s11, s11, 0
	s_waitcnt lgkmcnt(6)
	v_mfma_f32_16x16x32_bf16 v[4:7], v[122:125], v[192:195], v[4:7]
	global_load_lds_dwordx4 v254, s[10:11]
	s_add_u32 s98, s98, 0x80
	s_addc_u32 s99, s99, 0
	ds_read_b128 v[180:183], v110 offset:16896
	s_waitcnt lgkmcnt(6)
	v_mfma_f32_16x16x32_bf16 v[8:11], v[126:129], v[192:195], v[8:11]
	ds_read_b128 v[184:187], v110 offset:20480
	s_waitcnt lgkmcnt(6)
	v_mfma_f32_16x16x32_bf16 v[12:15], v[172:175], v[192:195], v[12:15]
	ds_read_b128 v[188:191], v110 offset:20992
	ds_read_b128 v[192:195], v111
	s_add_i32 m0, s13, 0x4000
	s_nop 0
	s_waitcnt lgkmcnt(7)
	v_mfma_f32_16x16x32_bf16 v[16:19], v[118:121], v[196:199], v[16:19]
	global_load_lds_dwordx4 v255, s[100:101]
	v_mfma_f32_16x16x32_bf16 v[20:23], v[122:125], v[196:199], v[20:23]
	v_mfma_f32_16x16x32_bf16 v[24:27], v[126:129], v[196:199], v[24:27]
	s_add_i32 m0, s13, 0x5000
	s_add_u32 s10, s100, s18
	s_addc_u32 s11, s101, 0
	v_mfma_f32_16x16x32_bf16 v[28:31], v[172:175], v[196:199], v[28:31]
	global_load_lds_dwordx4 v255, s[10:11]
	ds_read_b128 v[196:199], v111 offset:2048
	s_waitcnt lgkmcnt(7)
	v_mfma_f32_16x16x32_bf16 v[32:35], v[118:121], v[246:249], v[32:35]
	v_mfma_f32_16x16x32_bf16 v[36:39], v[122:125], v[246:249], v[36:39]
	s_add_i32 m0, s13, 0x6000
	s_add_u32 s10, s10, s18
	s_addc_u32 s11, s11, 0
	v_mfma_f32_16x16x32_bf16 v[40:43], v[126:129], v[246:249], v[40:43]
	global_load_lds_dwordx4 v255, s[10:11]
	v_mfma_f32_16x16x32_bf16 v[44:47], v[172:175], v[246:249], v[44:47]
	ds_read_b128 v[246:249], v111 offset:4096
	s_waitcnt lgkmcnt(7)
	v_mfma_f32_16x16x32_bf16 v[48:51], v[118:121], v[250:253], v[48:51]
	s_add_i32 m0, s13, 0x7000
	s_add_u32 s10, s10, s18
	s_addc_u32 s11, s11, 0
	v_mfma_f32_16x16x32_bf16 v[52:55], v[122:125], v[250:253], v[52:55]
	global_load_lds_dwordx4 v255, s[10:11]
	s_add_u32 s100, s100, 0x80
	s_addc_u32 s101, s101, 0
	v_mfma_f32_16x16x32_bf16 v[56:59], v[126:129], v[250:253], v[56:59]
	v_mfma_f32_16x16x32_bf16 v[60:63], v[172:175], v[250:253], v[60:63]
	ds_read_b128 v[250:253], v111 offset:6144
	s_waitcnt lgkmcnt(3)
	v_mfma_f32_16x16x32_bf16 v[0:3], v[176:179], v[192:195], v[0:3]
	v_mfma_f32_16x16x32_bf16 v[4:7], v[180:183], v[192:195], v[4:7]
	v_mfma_f32_16x16x32_bf16 v[8:11], v[184:187], v[192:195], v[8:11]
	v_mfma_f32_16x16x32_bf16 v[12:15], v[188:191], v[192:195], v[12:15]
	s_waitcnt lgkmcnt(2)
	v_mfma_f32_16x16x32_bf16 v[16:19], v[176:179], v[196:199], v[16:19]
	v_mfma_f32_16x16x32_bf16 v[20:23], v[180:183], v[196:199], v[20:23]
	v_mfma_f32_16x16x32_bf16 v[24:27], v[184:187], v[196:199], v[24:27]
	v_mfma_f32_16x16x32_bf16 v[28:31], v[188:191], v[196:199], v[28:31]
	s_waitcnt vmcnt(0)
	s_waitcnt lgkmcnt(0)
	s_barrier
	s_add_i32 s8, s8, 0x8000
	s_cmp_eq_u32 s8, 0x78000
	s_cbranch_scc1 .Lgk_tail_563
	v_or_b32_e32 v110, s12, v142
	v_add_u32_e32 v111, s12, v85
	s_add_i32 s13, s9, s17
	ds_read_b128 v[192:195], v111
	ds_read_b128 v[118:121], v110 offset:16384
	s_mov_b32 m0, s13
	s_nop 0
	v_mfma_f32_16x16x32_bf16 v[32:35], v[176:179], v[246:249], v[32:35]
	global_load_lds_dwordx4 v254, s[98:99]
	ds_read_b128 v[122:125], v110 offset:16896
	v_mfma_f32_16x16x32_bf16 v[36:39], v[180:183], v[246:249], v[36:39]
	ds_read_b128 v[126:129], v110 offset:20480
	v_mfma_f32_16x16x32_bf16 v[40:43], v[184:187], v[246:249], v[40:43]
	ds_read_b128 v[172:175], v110 offset:20992
	s_add_i32 m0, s13, 0x1000
	s_add_u32 s10, s98, s18
	s_addc_u32 s11, s99, 0
	v_mfma_f32_16x16x32_bf16 v[44:47], v[188:191], v[246:249], v[44:47]
	global_load_lds_dwordx4 v254, s[10:11]
	ds_read_b128 v[196:199], v111 offset:2048
	ds_read_b128 v[246:249], v111 offset:4096
	v_mfma_f32_16x16x32_bf16 v[48:51], v[176:179], v[250:253], v[48:51]
	v_mfma_f32_16x16x32_bf16 v[52:55], v[180:183], v[250:253], v[52:55]
	s_add_i32 m0, s13, 0x2000
	s_add_u32 s10, s10, s18
	s_addc_u32 s11, s11, 0
	v_mfma_f32_16x16x32_bf16 v[56:59], v[184:187], v[250:253], v[56:59]
	global_load_lds_dwordx4 v254, s[10:11]
	v_mfma_f32_16x16x32_bf16 v[60:63], v[188:191], v[250:253], v[60:63]
	ds_read_b128 v[250:253], v111 offset:6144
	s_branch .Lgk_loop_563

; __device__ __forceinline__ f32x4 mfma16(bf16x8 a, bf16x8 b, f32x4 c) { return __builtin_amdgcn_mfma_f32_16x16x32_bf16(a, b, c, 0, 0, 0); }
; template <class Epi>
; __device__ __forceinline__ void gemm_tile(const bf16_t* __restrict__ A, const bf16_t* __restrict__ Bt, int K, int row0, int col0, const Epi& epi, char* smem,
;                                           bool prefetched, bool nvalid, int nrow0, int ncol0) {
;     ...
;     __syncthreads();
;     const int nk = K >> 6;
;     for (int kt = 0; kt < nk; ++kt) {
;         const int cur = kt & 1;
;         if (kt + 1 < nk) GLDS_STAGE(cur ^ 1, pA, pB, kt + 1);
;         const char* cb = smem + cur * 2 * TILE_B;
; #pragma unroll
;         for (int ks = 0; ks < 2; ++ks) {
;             bf16x8 a[4], b[4];
; #pragma unroll
;             for (int m = 0; m < 4; ++m) a[m] = *(const bf16x8*)(cb + offA[m][ks]);
; #pragma unroll
;             for (int n = 0; n < 4; ++n) b[n] = *(const bf16x8*)(cb + offB[n][ks]);
; #pragma unroll
;             for (int m = 0; m < 4; ++m)
; #pragma unroll
;                 for (int n = 0; n < 4; ++n) acc[m][n] = mfma16(b[n], a[m], acc[m][n]);
;         }
;         asm volatile("s_waitcnt vmcnt(0)" ::: "memory");
;         __syncthreads();
.LBB0_619:
	v_readfirstlane_b32 s98, v92
	v_readfirstlane_b32 s99, v93
	v_readfirstlane_b32 s8, v94
	v_readfirstlane_b32 s100, v100
	v_readfirstlane_b32 s101, v101
	v_readfirstlane_b32 s12, v149
	s_nop 3
	s_sub_u32 s13, s8, s98
	s_and_b32 s98, s98, 0xffffff80
	s_and_b32 s100, s100, 0xffffff80
	s_nop 1
	v_subrev_u32_e32 v254, s98, v92
	v_subrev_u32_e32 v255, s100, v100
	s_add_i32 s11, s12, 0x8000
	s_mov_b32 m0, s11
	s_nop 0
	global_load_lds_dwordx4 v254, s[98:99]
	s_add_i32 m0, s11, 0x1000
	s_add_u32 s8, s98, s13
	s_addc_u32 s9, s99, 0
	global_load_lds_dwordx4 v254, s[8:9]
	s_add_i32 m0, s11, 0x2000
	s_add_u32 s8, s8, s13
	s_addc_u32 s9, s9, 0
	global_load_lds_dwordx4 v254, s[8:9]
	ds_read_b128 v[174:177], v108
	ds_read_b128 v[92:95], v110 offset:16384
	ds_read_b128 v[96:99], v110 offset:16896
	ds_read_b128 v[100:103], v110 offset:20480
	ds_read_b128 v[104:107], v110 offset:20992
	ds_read_b128 v[178:181], v108 offset:2048
	ds_read_b128 v[246:249], v108 offset:4096
	ds_read_b128 v[250:253], v108 offset:6144
.Lgk_loop_619:
	s_and_b32 s3, s1, 0x8000
	s_xor_b32 s10, s3, 0x8000
	v_or_b32_e32 v129, s3, v111
	v_add_u32_e32 v130, s3, v109
	s_waitcnt lgkmcnt(6)
	v_mfma_f32_16x16x32_bf16 v[0:3], v[92:95], v[174:177], v[0:3]
	ds_read_b128 v[142:145], v129 offset:16384
	s_add_i32 m0, s11, 0x3000
	s_add_u32 s8, s8, s13
	s_addc_u32 s9, s9, 0
	s_waitcnt lgkmcnt(6)
	v_mfma_f32_16x16x32_bf16 v[4:7], v[96:99], v[174:177], v[4:7]
	global_load_lds_dwordx4 v254, s[8:9]
	s_add_u32 s98, s98, 0x80
	s_addc_u32 s99, s99, 0
	ds_read_b128 v[162:165], v129 offset:16896
	s_waitcnt lgkmcnt(6)
	v_mfma_f32_16x16x32_bf16 v[8:11], v[100:103], v[174:177], v[8:11]
	ds_read_b128 v[166:169], v129 offset:20480
	s_waitcnt lgkmcnt(6)
	v_mfma_f32_16x16x32_bf16 v[12:15], v[104:107], v[174:177], v[12:15]
	ds_read_b128 v[170:173], v129 offset:20992
	ds_read_b128 v[174:177], v130
	s_add_i32 m0, s11, 0x4000
	s_nop 0
	s_waitcnt lgkmcnt(7)
	v_mfma_f32_16x16x32_bf16 v[16:19], v[92:95], v[178:181], v[16:19]
	global_load_lds_dwordx4 v255, s[100:101]
	v_mfma_f32_16x16x32_bf16 v[20:23], v[96:99], v[178:181], v[20:23]
	v_mfma_f32_16x16x32_bf16 v[24:27], v[100:103], v[178:181], v[24:27]
	s_add_i32 m0, s11, 0x5000
	s_add_u32 s8, s100, s13
	s_addc_u32 s9, s101, 0
	v_mfma_f32_16x16x32_bf16 v[28:31], v[104:107], v[178:181], v[28:31]
	global_load_lds_dwordx4 v255, s[8:9]
	ds_read_b128 v[178:181], v130 offset:2048
	s_waitcnt lgkmcnt(7)
	v_mfma_f32_16x16x32_bf16 v[32:35], v[92:95], v[246:249], v[32:35]
	v_mfma_f32_16x16x32_bf16 v[36:39], v[96:99], v[246:249], v[36:39]
	s_add_i32 m0, s11, 0x6000
	s_add_u32 s8, s8, s13
	s_addc_u32 s9, s9, 0
	v_mfma_f32_16x16x32_bf16 v[40:43], v[100:103], v[246:249], v[40:43]
	global_load_lds_dwordx4 v255, s[8:9]
	v_mfma_f32_16x16x32_bf16 v[44:47], v[104:107], v[246:249], v[44:47]
	ds_read_b128 v[246:249], v130 offset:4096
	s_waitcnt lgkmcnt(7)
	v_mfma_f32_16x16x32_bf16 v[48:51], v[92:95], v[250:253], v[48:51]
	s_add_i32 m0, s11, 0x7000
	s_add_u32 s8, s8, s13
	s_addc_u32 s9, s9, 0
	v_mfma_f32_16x16x32_bf16 v[52:55], v[96:99], v[250:253], v[52:55]
	global_load_lds_dwordx4 v255, s[8:9]
	s_add_u32 s100, s100, 0x80
	s_addc_u32 s101, s101, 0
	v_mfma_f32_16x16x32_bf16 v[56:59], v[100:103], v[250:253], v[56:59]
	v_mfma_f32_16x16x32_bf16 v[60:63], v[104:107], v[250:253], v[60:63]
	ds_read_b128 v[250:253], v130 offset:6144
	s_waitcnt lgkmcnt(3)
	v_mfma_f32_16x16x32_bf16 v[0:3], v[142:145], v[174:177], v[0:3]
	v_mfma_f32_16x16x32_bf16 v[4:7], v[162:165], v[174:177], v[4:7]
	v_mfma_f32_16x16x32_bf16 v[8:11], v[166:169], v[174:177], v[8:11]
	v_mfma_f32_16x16x32_bf16 v[12:15], v[170:173], v[174:177], v[12:15]
	s_waitcnt lgkmcnt(2)
	v_mfma_f32_16x16x32_bf16 v[16:19], v[142:145], v[178:181], v[16:19]
	v_mfma_f32_16x16x32_bf16 v[20:23], v[162:165], v[178:181], v[20:23]
	v_mfma_f32_16x16x32_bf16 v[24:27], v[166:169], v[178:181], v[24:27]
	v_mfma_f32_16x16x32_bf16 v[28:31], v[170:173], v[178:181], v[28:31]
	s_waitcnt vmcnt(0)
	s_waitcnt lgkmcnt(0)
	s_barrier
	s_add_i32 s1, s1, 0x8000
	s_cmp_eq_u32 s1, 0x1f8000
	s_cbranch_scc1 .Lgk_tail_619
	v_or_b32_e32 v129, s10, v110
	v_add_u32_e32 v130, s10, v108
	s_add_i32 s11, s3, s12
	ds_read_b128 v[174:177], v130
	ds_read_b128 v[92:95], v129 offset:16384
	s_mov_b32 m0, s11
	s_nop 0
	v_mfma_f32_16x16x32_bf16 v[32:35], v[142:145], v[246:249], v[32:35]
	global_load_lds_dwordx4 v254, s[98:99]
	ds_read_b128 v[96:99], v129 offset:16896
	v_mfma_f32_16x16x32_bf16 v[36:39], v[162:165], v[246:249], v[36:39]
	ds_read_b128 v[100:103], v129 offset:20480
	v_mfma_f32_16x16x32_bf16 v[40:43], v[166:169], v[246:249], v[40:43]
	ds_read_b128 v[104:107], v129 offset:20992
	s_add_i32 m0, s11, 0x1000
	s_add_u32 s8, s98, s13
	s_addc_u32 s9, s99, 0
	v_mfma_f32_16x16x32_bf16 v[44:47], v[170:173], v[246:249], v[44:47]
	global_load_lds_dwordx4 v254, s[8:9]
	ds_read_b128 v[178:181], v130 offset:2048
	ds_read_b128 v[246:249], v130 offset:4096
	v_mfma_f32_16x16x32_bf16 v[48:51], v[142:145], v[250:253], v[48:51]
	v_mfma_f32_16x16x32_bf16 v[52:55], v[162:165], v[250:253], v[52:55]
	s_add_i32 m0, s11, 0x2000
	s_add_u32 s8, s8, s13
	s_addc_u32 s9, s9, 0
	v_mfma_f32_16x16x32_bf16 v[56:59], v[166:169], v[250:253], v[56:59]
	global_load_lds_dwordx4 v254, s[8:9]
	v_mfma_f32_16x16x32_bf16 v[60:63], v[170:173], v[250:253], v[60:63]
	ds_read_b128 v[250:253], v130 offset:6144
	s_branch .Lgk_loop_619

; __device__ __forceinline__ f32x4 mfma16(bf16x8 a, bf16x8 b, f32x4 c) { return __builtin_amdgcn_mfma_f32_16x16x32_bf16(a, b, c, 0, 0, 0); }
; template <class Epi>
; __device__ __forceinline__ void gemm_tile(const bf16_t* __restrict__ A, const bf16_t* __restrict__ Bt, int K, int row0, int col0, const Epi& epi, char* smem,
;                                           bool prefetched, bool nvalid, int nrow0, int ncol0) {
;     ...
;     __syncthreads();
;     const int nk = K >> 6;
;     for (int kt = 0; kt < nk; ++kt) {
;         const int cur = kt & 1;
;         if (kt + 1 < nk) GLDS_STAGE(cur ^ 1, pA, pB, kt + 1);
;         const char* cb = smem + cur * 2 * TILE_B;
; #pragma unroll
;         for (int ks = 0; ks < 2; ++ks) {
;             bf16x8 a[4], b[4];
; #pragma unroll
;             for (int m = 0; m < 4; ++m) a[m] = *(const bf16x8*)(cb + offA[m][ks]);
; #pragma unroll
;             for (int n = 0; n < 4; ++n) b[n] = *(const bf16x8*)(cb + offB[n][ks]);
; #pragma unroll
;             for (int m = 0; m < 4; ++m)
; #pragma unroll
;                 for (int n = 0; n < 4; ++n) acc[m][n] = mfma16(b[n], a[m], acc[m][n]);
;         }
;         asm volatile("s_waitcnt vmcnt(0)" ::: "memory");
;         __syncthreads();
.LBB0_723:
	v_readfirstlane_b32 s98, v64
	v_readfirstlane_b32 s99, v65
	v_readfirstlane_b32 s12, v66
	v_readfirstlane_b32 s100, v72
	v_readfirstlane_b32 s101, v73
	v_readfirstlane_b32 s15, v149
	s_nop 3
	s_sub_u32 s16, s12, s98
	s_and_b32 s98, s98, 0xffffff80
	s_and_b32 s100, s100, 0xffffff80
	s_nop 1
	v_subrev_u32_e32 v254, s98, v64
	v_subrev_u32_e32 v255, s100, v72
	s_add_i32 s14, s15, 0x8000
	s_mov_b32 m0, s14
	s_nop 0
	global_load_lds_dwordx4 v254, s[98:99]
	s_add_i32 m0, s14, 0x1000
	s_add_u32 s12, s98, s16
	s_addc_u32 s13, s99, 0
	global_load_lds_dwordx4 v254, s[12:13]
	s_add_i32 m0, s14, 0x2000
	s_add_u32 s12, s12, s16
	s_addc_u32 s13, s13, 0
	global_load_lds_dwordx4 v254, s[12:13]
	ds_read_b128 v[188:191], v137
	ds_read_b128 v[64:67], v143 offset:16384
	ds_read_b128 v[68:71], v143 offset:16896
	ds_read_b128 v[72:75], v143 offset:20480
	ds_read_b128 v[76:79], v143 offset:20992
	ds_read_b128 v[192:195], v137 offset:2048
	ds_read_b128 v[246:249], v137 offset:4096
	ds_read_b128 v[250:253], v137 offset:6144
.Lgk_loop_723:
	s_and_b32 s10, s7, 0x8000
	s_xor_b32 s11, s10, 0x8000
	v_or_b32_e32 v179, s10, v142
	v_add_u32_e32 v196, s10, v141
	s_waitcnt lgkmcnt(6)
	v_mfma_f32_16x16x32_bf16 v[0:3], v[64:67], v[188:191], v[0:3]
	ds_read_b128 v[80:83], v179 offset:16384
	s_add_i32 m0, s14, 0x3000
	s_add_u32 s12, s12, s16
	s_addc_u32 s13, s13, 0
	s_waitcnt lgkmcnt(6)
	v_mfma_f32_16x16x32_bf16 v[4:7], v[68:71], v[188:191], v[4:7]
	global_load_lds_dwordx4 v254, s[12:13]
	s_add_u32 s98, s98, 0x80
	s_addc_u32 s99, s99, 0
	ds_read_b128 v[128:131], v179 offset:16896
	s_waitcnt lgkmcnt(6)
	v_mfma_f32_16x16x32_bf16 v[8:11], v[72:75], v[188:191], v[8:11]
	ds_read_b128 v[180:183], v179 offset:20480
	s_waitcnt lgkmcnt(6)
	v_mfma_f32_16x16x32_bf16 v[12:15], v[76:79], v[188:191], v[12:15]
	ds_read_b128 v[184:187], v179 offset:20992
	ds_read_b128 v[188:191], v196
	s_add_i32 m0, s14, 0x4000
	s_nop 0
	s_waitcnt lgkmcnt(7)
	v_mfma_f32_16x16x32_bf16 v[16:19], v[64:67], v[192:195], v[16:19]
	global_load_lds_dwordx4 v255, s[100:101]
	v_mfma_f32_16x16x32_bf16 v[20:23], v[68:71], v[192:195], v[20:23]
	v_mfma_f32_16x16x32_bf16 v[24:27], v[72:75], v[192:195], v[24:27]
	s_add_i32 m0, s14, 0x5000
	s_add_u32 s12, s100, s16
	s_addc_u32 s13, s101, 0
	v_mfma_f32_16x16x32_bf16 v[28:31], v[76:79], v[192:195], v[28:31]
	global_load_lds_dwordx4 v255, s[12:13]
	ds_read_b128 v[192:195], v196 offset:2048
	s_waitcnt lgkmcnt(7)
	v_mfma_f32_16x16x32_bf16 v[32:35], v[64:67], v[246:249], v[32:35]
	v_mfma_f32_16x16x32_bf16 v[36:39], v[68:71], v[246:249], v[36:39]
	s_add_i32 m0, s14, 0x6000
	s_add_u32 s12, s12, s16
	s_addc_u32 s13, s13, 0
	v_mfma_f32_16x16x32_bf16 v[40:43], v[72:75], v[246:249], v[40:43]
	global_load_lds_dwordx4 v255, s[12:13]
	v_mfma_f32_16x16x32_bf16 v[44:47], v[76:79], v[246:249], v[44:47]
	ds_read_b128 v[246:249], v196 offset:4096
	s_waitcnt lgkmcnt(7)
	v_mfma_f32_16x16x32_bf16 v[48:51], v[64:67], v[250:253], v[48:51]
	s_add_i32 m0, s14, 0x7000
	s_add_u32 s12, s12, s16
	s_addc_u32 s13, s13, 0
	v_mfma_f32_16x16x32_bf16 v[52:55], v[68:71], v[250:253], v[52:55]
	global_load_lds_dwordx4 v255, s[12:13]
	s_add_u32 s100, s100, 0x80
	s_addc_u32 s101, s101, 0
	v_mfma_f32_16x16x32_bf16 v[56:59], v[72:75], v[250:253], v[56:59]
	v_mfma_f32_16x16x32_bf16 v[60:63], v[76:79], v[250:253], v[60:63]
	ds_read_b128 v[250:253], v196 offset:6144
	s_waitcnt lgkmcnt(3)
	v_mfma_f32_16x16x32_bf16 v[0:3], v[80:83], v[188:191], v[0:3]
	v_mfma_f32_16x16x32_bf16 v[4:7], v[128:131], v[188:191], v[4:7]
	v_mfma_f32_16x16x32_bf16 v[8:11], v[180:183], v[188:191], v[8:11]
	v_mfma_f32_16x16x32_bf16 v[12:15], v[184:187], v[188:191], v[12:15]
	s_waitcnt lgkmcnt(2)
	v_mfma_f32_16x16x32_bf16 v[16:19], v[80:83], v[192:195], v[16:19]
	v_mfma_f32_16x16x32_bf16 v[20:23], v[128:131], v[192:195], v[20:23]
	v_mfma_f32_16x16x32_bf16 v[24:27], v[180:183], v[192:195], v[24:27]
	v_mfma_f32_16x16x32_bf16 v[28:31], v[184:187], v[192:195], v[28:31]
	s_waitcnt vmcnt(0)
	s_waitcnt lgkmcnt(0)
	s_barrier
	s_add_i32 s7, s7, 0x8000
	s_cmp_eq_u32 s7, 0x78000
	s_cbranch_scc1 .Lgk_tail_723
	v_or_b32_e32 v179, s11, v143
	v_add_u32_e32 v196, s11, v137
	s_add_i32 s14, s10, s15
	ds_read_b128 v[188:191], v196
	ds_read_b128 v[64:67], v179 offset:16384
	s_mov_b32 m0, s14
	s_nop 0
	v_mfma_f32_16x16x32_bf16 v[32:35], v[80:83], v[246:249], v[32:35]
	global_load_lds_dwordx4 v254, s[98:99]
	ds_read_b128 v[68:71], v179 offset:16896
	v_mfma_f32_16x16x32_bf16 v[36:39], v[128:131], v[246:249], v[36:39]
	ds_read_b128 v[72:75], v179 offset:20480
	v_mfma_f32_16x16x32_bf16 v[40:43], v[180:183], v[246:249], v[40:43]
	ds_read_b128 v[76:79], v179 offset:20992
	s_add_i32 m0, s14, 0x1000
	s_add_u32 s12, s98, s16
	s_addc_u32 s13, s99, 0
	v_mfma_f32_16x16x32_bf16 v[44:47], v[184:187], v[246:249], v[44:47]
	global_load_lds_dwordx4 v254, s[12:13]
	ds_read_b128 v[192:195], v196 offset:2048
	ds_read_b128 v[246:249], v196 offset:4096
	v_mfma_f32_16x16x32_bf16 v[48:51], v[80:83], v[250:253], v[48:51]
	v_mfma_f32_16x16x32_bf16 v[52:55], v[128:131], v[250:253], v[52:55]
	s_add_i32 m0, s14, 0x2000
	s_add_u32 s12, s12, s16
	s_addc_u32 s13, s13, 0
	v_mfma_f32_16x16x32_bf16 v[56:59], v[180:183], v[250:253], v[56:59]
	global_load_lds_dwordx4 v254, s[12:13]
	v_mfma_f32_16x16x32_bf16 v[60:63], v[184:187], v[250:253], v[60:63]
	ds_read_b128 v[250:253], v196 offset:6144
	s_branch .Lgk_loop_723

; __device__ __forceinline__ u32x4 pack8(f32x4 a, f32x4 b) { u32x4 r; r.x = cvt_pk_bf16(a[0], a[1]); r.y = cvt_pk_bf16(a[2], a[3]); r.z = cvt_pk_bf16(b[0], b[1]); r.w = cvt_pk_bf16(b[2], b[3]); return r; }
; template <class Epi>
; __device__ __forceinline__ void gemm_tile(const bf16_t* __restrict__ A, const bf16_t* __restrict__ Bt, int K, int row0, int col0, const Epi& epi, char* smem,
;                                           bool prefetched, bool nvalid, int nrow0, int ncol0) {
;     ...
;     if constexpr (Epi::STAGED) {
;         bf16_t* st = (bf16_t*)(smem + 2 * TILE_B);
;         epi.to_lds(acc, st, row0, col0, wr, wc, fr, fq);
;         __syncthreads();
;         bf16_t* gbase; size_t gstride;
;         epi.dest(row0, col0, gbase, gstride);
;         const int r0 = tid >> 4, ch = (tid & 15) * 8;
; #pragma unroll
;         for (int it = 0; it < 8; ++it) { const int r = it * 16 + r0; __builtin_nontemporal_store(*(const u32x4*)(st + r * 136 + ch), (u32x4*)(gbase + (size_t)r * gstride + ch)); }
;     __device__ __forceinline__ void to_lds(f32x4 (&acc)[4][4], bf16_t* st, int row0, int col0, int wr, int wc, int fr, int fq) const {
; #pragma unroll
;         for (int m = 0; m < 4; ++m)
; #pragma unroll
;             for (int pp = 0; pp < 2; ++pp)
;                 *(u32x4*)(st + (wr * 64 + m * 16 + fr) * 136 + wc * 64 + pp * 32 + 8 * fq) = pack8(acc[m][2 * pp], acc[m][2 * pp + 1]);
;     }
.LBB0_760:
	s_ashr_i32 s8, s0, 12
	s_ashr_i32 s9, s8, 31
	s_lshl_b64 s[8:9], s[8:9], 23
	s_lshl_b64 s[2:3], s[2:3], 13
	v_readlane_b32 s1, v245, 57
	s_add_u32 s1, s1, s8
	v_readlane_b32 s8, v245, 58
	s_addc_u32 s8, s8, s9
	s_add_u32 s1, s1, s2
	v_cvt_pk_bf16_f32 v56, v56, v57
	v_cvt_pk_bf16_f32 v57, v58, v59
	v_cvt_pk_bf16_f32 v58, v60, v61
	v_cvt_pk_bf16_f32 v59, v62, v63
	v_cvt_pk_bf16_f32 v48, v48, v49
	v_cvt_pk_bf16_f32 v49, v50, v51
	v_cvt_pk_bf16_f32 v50, v52, v53
	v_cvt_pk_bf16_f32 v51, v54, v55
	v_cvt_pk_bf16_f32 v44, v44, v45
	v_cvt_pk_bf16_f32 v45, v46, v47
	v_cvt_pk_bf16_f32 v46, v40, v41
	v_cvt_pk_bf16_f32 v47, v42, v43
	v_cvt_pk_bf16_f32 v36, v36, v37
	v_cvt_pk_bf16_f32 v37, v38, v39
	v_cvt_pk_bf16_f32 v38, v32, v33
	v_cvt_pk_bf16_f32 v39, v34, v35
	v_cvt_pk_bf16_f32 v28, v28, v29
	v_cvt_pk_bf16_f32 v29, v30, v31
	v_cvt_pk_bf16_f32 v30, v24, v25
	v_cvt_pk_bf16_f32 v31, v26, v27
	v_cvt_pk_bf16_f32 v20, v20, v21
	v_cvt_pk_bf16_f32 v21, v22, v23
	v_cvt_pk_bf16_f32 v22, v16, v17
	v_cvt_pk_bf16_f32 v23, v18, v19
	v_cvt_pk_bf16_f32 v4, v4, v5
	v_cvt_pk_bf16_f32 v5, v6, v7
	v_cvt_pk_bf16_f32 v6, v8, v9
	v_cvt_pk_bf16_f32 v7, v10, v11
	v_cvt_pk_bf16_f32 v0, v0, v1
	v_cvt_pk_bf16_f32 v1, v2, v3
	v_cvt_pk_bf16_f32 v2, v12, v13
	v_cvt_pk_bf16_f32 v3, v14, v15
	s_addc_u32 s2, s8, s3
	s_and_b32 s0, s0, 0xf80
	ds_write_b128 v142, v[56:59] offset:32768
	ds_write_b128 v142, v[48:51] offset:32832
	ds_write_b128 v142, v[44:47] offset:37120
	ds_write_b128 v142, v[36:39] offset:37184
	ds_write_b128 v142, v[28:31] offset:41472
	ds_write_b128 v142, v[20:23] offset:41536
	ds_write_b128 v142, v[4:7] offset:45824
	ds_write_b128 v142, v[0:3] offset:45888
	s_waitcnt lgkmcnt(0)
	s_barrier
	s_lshl_b32 s0, s0, 1
	ds_read_b128 v[0:3], v143 offset:32768
	ds_read_b128 v[4:7], v143 offset:37120
	s_add_u32 s0, s1, s0
	s_addc_u32 s1, s2, 0
	v_lshl_add_u64 v[12:13], s[0:1], 0, v[72:73]
	v_lshl_add_u64 v[8:9], v[74:75], 1, v[12:13]
	s_waitcnt lgkmcnt(1)
	global_store_dwordx4 v[8:9], v[0:3], off nt
	ds_read_b128 v[0:3], v143 offset:41472
	v_lshl_add_u64 v[8:9], v[76:77], 1, v[12:13]
	s_waitcnt lgkmcnt(1)
	global_store_dwordx4 v[8:9], v[4:7], off nt
	ds_read_b128 v[4:7], v143 offset:45824
	v_lshl_add_u64 v[8:9], v[78:79], 1, v[12:13]
	s_waitcnt lgkmcnt(1)
	global_store_dwordx4 v[8:9], v[0:3], off nt
	ds_read_b128 v[0:3], v143 offset:50176
	v_lshl_add_u64 v[8:9], v[80:81], 1, v[12:13]
	s_waitcnt lgkmcnt(1)
	global_store_dwordx4 v[8:9], v[4:7], off nt
	v_lshl_add_u64 v[8:9], v[82:83], 1, v[12:13]
	ds_read_b128 v[4:7], v143 offset:54528
	s_waitcnt lgkmcnt(1)
	global_store_dwordx4 v[8:9], v[0:3], off nt
	ds_read_b128 v[0:3], v143 offset:58880
	ds_read_b128 v[8:11], v143 offset:63232
	v_lshl_add_u64 v[14:15], v[84:85], 1, v[12:13]
	s_waitcnt lgkmcnt(2)
	global_store_dwordx4 v[14:15], v[4:7], off nt
	s_andn2_b64 vcc, exec, s[6:7]
	s_mov_b64 s[10:11], -1
	v_lshl_add_u64 v[4:5], v[86:87], 1, v[12:13]
	s_waitcnt lgkmcnt(1)
	global_store_dwordx4 v[4:5], v[0:3], off nt
	s_nop 1
	v_lshl_add_u64 v[0:1], v[88:89], 1, v[12:13]
	s_waitcnt lgkmcnt(0)
	global_store_dwordx4 v[0:1], v[8:11], off nt
	s_cbranch_vccz .LBB0_769

; __device__ __forceinline__ f32x4 zero4() { return (f32x4){0.f, 0.f, 0.f, 0.f}; }
; template <class Epi>
; __device__ __forceinline__ void gemm_tile(const bf16_t* __restrict__ A, const bf16_t* __restrict__ Bt, int K, int row0, int col0, const Epi& epi, char* smem,
;                                           bool prefetched, bool nvalid, int nrow0, int ncol0) {
;     ...
;     f32x4 acc[4][4];
; #pragma unroll
;     for (int m = 0; m < 4; ++m)
; #pragma unroll
;         for (int n = 0; n < 4; ++n) acc[m][n] = zero4();
;     ...
;     __syncthreads();
;     const int nk = K >> 6;
;     for (int kt = 0; kt < nk; ++kt) {
;         const int cur = kt & 1;
;         if (kt + 1 < nk) GLDS_STAGE(cur ^ 1, pA, pB, kt + 1);
;         const char* cb = smem + cur * 2 * TILE_B;
; #pragma unroll
;         for (int ks = 0; ks < 2; ++ks) {
;             bf16x8 a[4], b[4];
; #pragma unroll
;             for (int m = 0; m < 4; ++m) a[m] = *(const bf16x8*)(cb + offA[m][ks]);
; #pragma unroll
;             for (int n = 0; n < 4; ++n) b[n] = *(const bf16x8*)(cb + offB[n][ks]);
.LBB0_765:
	v_mov_b32_e32 v0, 0
	v_lshl_add_u64 v[106:107], v[90:91], 0, s[6:7]
	v_lshl_add_u64 v[108:109], v[92:93], 0, s[6:7]
	v_lshl_add_u64 v[110:111], v[94:95], 0, s[6:7]
	v_lshl_add_u64 v[118:119], v[96:97], 0, s[6:7]
	v_lshl_add_u64 v[120:121], v[98:99], 0, s[8:9]
	v_lshl_add_u64 v[122:123], v[100:101], 0, s[8:9]
	v_lshl_add_u64 v[124:125], v[102:103], 0, s[8:9]
	v_lshl_add_u64 v[126:127], v[104:105], 0, s[8:9]
	s_mov_b32 s1, 0
	s_mov_b64 s[6:7], 0
	v_mov_b32_e32 v1, v0
	v_mov_b32_e32 v2, v0
	v_mov_b32_e32 v3, v0
	v_mov_b32_e32 v4, v0
	v_mov_b32_e32 v5, v0
	v_mov_b32_e32 v6, v0
	v_mov_b32_e32 v7, v0
	v_mov_b32_e32 v8, v0
	v_mov_b32_e32 v9, v0
	v_mov_b32_e32 v10, v0
	v_mov_b32_e32 v11, v0
	v_mov_b32_e32 v12, v0
	v_mov_b32_e32 v13, v0
	v_mov_b32_e32 v14, v0
	v_mov_b32_e32 v15, v0
	v_mov_b32_e32 v16, v0
	v_mov_b32_e32 v17, v0
	v_mov_b32_e32 v18, v0
	v_mov_b32_e32 v19, v0
	v_mov_b32_e32 v20, v0
	v_mov_b32_e32 v21, v0
	v_mov_b32_e32 v22, v0
	v_mov_b32_e32 v23, v0
	v_mov_b32_e32 v24, v0
	v_mov_b32_e32 v25, v0
	v_mov_b32_e32 v26, v0
	v_mov_b32_e32 v27, v0
	v_mov_b32_e32 v28, v0
	v_mov_b32_e32 v29, v0
	v_mov_b32_e32 v30, v0
	v_mov_b32_e32 v31, v0
	v_mov_b32_e32 v32, v0
	v_mov_b32_e32 v33, v0
	v_mov_b32_e32 v34, v0
	v_mov_b32_e32 v35, v0
	v_mov_b32_e32 v36, v0
	v_mov_b32_e32 v37, v0
	v_mov_b32_e32 v38, v0
	v_mov_b32_e32 v39, v0
	v_mov_b32_e32 v40, v0
	v_mov_b32_e32 v41, v0
	v_mov_b32_e32 v42, v0
	v_mov_b32_e32 v43, v0
	v_mov_b32_e32 v44, v0
	v_mov_b32_e32 v45, v0
	v_mov_b32_e32 v46, v0
	v_mov_b32_e32 v47, v0
	v_mov_b32_e32 v48, v0
	v_mov_b32_e32 v49, v0
	v_mov_b32_e32 v50, v0
	v_mov_b32_e32 v51, v0
	v_mov_b32_e32 v52, v0
	v_mov_b32_e32 v53, v0
	v_mov_b32_e32 v54, v0
	v_mov_b32_e32 v55, v0
	v_mov_b32_e32 v56, v0
	v_mov_b32_e32 v57, v0
	v_mov_b32_e32 v58, v0
	v_mov_b32_e32 v59, v0
	v_mov_b32_e32 v60, v0
	v_mov_b32_e32 v61, v0
	v_mov_b32_e32 v62, v0
	v_mov_b32_e32 v63, v0
	s_waitcnt lgkmcnt(0)
	s_barrier
.LBB0_766:
	v_readfirstlane_b32 s98, v106
	v_readfirstlane_b32 s99, v107
	v_readfirstlane_b32 s10, v108
	v_readfirstlane_b32 s100, v120
	v_readfirstlane_b32 s101, v121
	v_readfirstlane_b32 s13, v149
	s_nop 3
	s_sub_u32 s16, s10, s98
	s_and_b32 s98, s98, 0xffffff80
	s_and_b32 s100, s100, 0xffffff80
	s_nop 1
	v_subrev_u32_e32 v254, s98, v106
	v_subrev_u32_e32 v255, s100, v120
	s_add_i32 s12, s13, 0x8000
	s_mov_b32 m0, s12
	s_nop 0
	global_load_lds_dwordx4 v254, s[98:99]
	s_add_i32 m0, s12, 0x1000
	s_add_u32 s10, s98, s16
	s_addc_u32 s11, s99, 0
	global_load_lds_dwordx4 v254, s[10:11]
	s_add_i32 m0, s12, 0x2000
	s_add_u32 s10, s10, s16
	s_addc_u32 s11, s11, 0
	global_load_lds_dwordx4 v254, s[10:11]
	ds_read_b128 v[190:193], v128
	ds_read_b128 v[106:109], v131 offset:16384
	ds_read_b128 v[118:121], v131 offset:16896
	ds_read_b128 v[122:125], v131 offset:20480
	ds_read_b128 v[170:173], v131 offset:20992
	ds_read_b128 v[194:197], v128 offset:2048
	ds_read_b128 v[198:201], v128 offset:4096
	ds_read_b128 v[246:249], v128 offset:6144
; __device__ __forceinline__ f32x4 mfma16(bf16x8 a, bf16x8 b, f32x4 c) { return __builtin_amdgcn_mfma_f32_16x16x32_bf16(a, b, c, 0, 0, 0); }
; template <class Epi>
; __device__ __forceinline__ void gemm_tile(const bf16_t* __restrict__ A, const bf16_t* __restrict__ Bt, int K, int row0, int col0, const Epi& epi, char* smem,
;                                           bool prefetched, bool nvalid, int nrow0, int ncol0) {
;     ...
;     for (int kt = 0; kt < nk; ++kt) {
;         const int cur = kt & 1;
;         if (kt + 1 < nk) GLDS_STAGE(cur ^ 1, pA, pB, kt + 1);
;         const char* cb = smem + cur * 2 * TILE_B;
; #pragma unroll
;         for (int ks = 0; ks < 2; ++ks) {
;             bf16x8 a[4], b[4];
; #pragma unroll
;             for (int m = 0; m < 4; ++m) a[m] = *(const bf16x8*)(cb + offA[m][ks]);
; #pragma unroll
;             for (int n = 0; n < 4; ++n) b[n] = *(const bf16x8*)(cb + offB[n][ks]);
; #pragma unroll
;             for (int m = 0; m < 4; ++m)
; #pragma unroll
;                 for (int n = 0; n < 4; ++n) acc[m][n] = mfma16(b[n], a[m], acc[m][n]);
;         }
;         asm volatile("s_waitcnt vmcnt(0)" ::: "memory");
;         __syncthreads();
.Lgk_loop_766:
	s_and_b32 s8, s1, 0x8000
	s_xor_b32 s9, s8, 0x8000
	v_or_b32_e32 v164, s8, v130
	v_add_u32_e32 v165, s8, v129
	s_waitcnt lgkmcnt(6)
	v_mfma_f32_16x16x32_bf16 v[0:3], v[106:109], v[190:193], v[0:3]
	ds_read_b128 v[174:177], v164 offset:16384
	s_add_i32 m0, s12, 0x3000
	s_add_u32 s10, s10, s16
	s_addc_u32 s11, s11, 0
	s_waitcnt lgkmcnt(6)
	v_mfma_f32_16x16x32_bf16 v[4:7], v[118:121], v[190:193], v[4:7]
	global_load_lds_dwordx4 v254, s[10:11]
	s_add_u32 s98, s98, 0x80
	s_addc_u32 s99, s99, 0
	ds_read_b128 v[178:181], v164 offset:16896
	s_waitcnt lgkmcnt(6)
	v_mfma_f32_16x16x32_bf16 v[8:11], v[122:125], v[190:193], v[8:11]
	ds_read_b128 v[182:185], v164 offset:20480
	s_waitcnt lgkmcnt(6)
	v_mfma_f32_16x16x32_bf16 v[12:15], v[170:173], v[190:193], v[12:15]
	ds_read_b128 v[186:189], v164 offset:20992
	ds_read_b128 v[190:193], v165
	s_add_i32 m0, s12, 0x4000
	s_nop 0
	s_waitcnt lgkmcnt(7)
	v_mfma_f32_16x16x32_bf16 v[16:19], v[106:109], v[194:197], v[16:19]
	global_load_lds_dwordx4 v255, s[100:101]
	v_mfma_f32_16x16x32_bf16 v[20:23], v[118:121], v[194:197], v[20:23]
	v_mfma_f32_16x16x32_bf16 v[24:27], v[122:125], v[194:197], v[24:27]
	s_add_i32 m0, s12, 0x5000
	s_add_u32 s10, s100, s16
	s_addc_u32 s11, s101, 0
	v_mfma_f32_16x16x32_bf16 v[28:31], v[170:173], v[194:197], v[28:31]
	global_load_lds_dwordx4 v255, s[10:11]
	ds_read_b128 v[194:197], v165 offset:2048
	s_waitcnt lgkmcnt(7)
	v_mfma_f32_16x16x32_bf16 v[32:35], v[106:109], v[198:201], v[32:35]
	v_mfma_f32_16x16x32_bf16 v[36:39], v[118:121], v[198:201], v[36:39]
	s_add_i32 m0, s12, 0x6000
	s_add_u32 s10, s10, s16
	s_addc_u32 s11, s11, 0
	v_mfma_f32_16x16x32_bf16 v[40:43], v[122:125], v[198:201], v[40:43]
	global_load_lds_dwordx4 v255, s[10:11]
	v_mfma_f32_16x16x32_bf16 v[44:47], v[170:173], v[198:201], v[44:47]
	ds_read_b128 v[198:201], v165 offset:4096
	s_waitcnt lgkmcnt(7)
	v_mfma_f32_16x16x32_bf16 v[48:51], v[106:109], v[246:249], v[48:51]
	s_add_i32 m0, s12, 0x7000
	s_add_u32 s10, s10, s16
	s_addc_u32 s11, s11, 0
	v_mfma_f32_16x16x32_bf16 v[52:55], v[118:121], v[246:249], v[52:55]
	global_load_lds_dwordx4 v255, s[10:11]
	s_add_u32 s100, s100, 0x80
	s_addc_u32 s101, s101, 0
	v_mfma_f32_16x16x32_bf16 v[56:59], v[122:125], v[246:249], v[56:59]
	v_mfma_f32_16x16x32_bf16 v[60:63], v[170:173], v[246:249], v[60:63]
	ds_read_b128 v[246:249], v165 offset:6144
	s_waitcnt lgkmcnt(3)
	v_mfma_f32_16x16x32_bf16 v[0:3], v[174:177], v[190:193], v[0:3]
	v_mfma_f32_16x16x32_bf16 v[4:7], v[178:181], v[190:193], v[4:7]
	v_mfma_f32_16x16x32_bf16 v[8:11], v[182:185], v[190:193], v[8:11]
	v_mfma_f32_16x16x32_bf16 v[12:15], v[186:189], v[190:193], v[12:15]
	s_waitcnt lgkmcnt(2)
	v_mfma_f32_16x16x32_bf16 v[16:19], v[174:177], v[194:197], v[16:19]
	v_mfma_f32_16x16x32_bf16 v[20:23], v[178:181], v[194:197], v[20:23]
	v_mfma_f32_16x16x32_bf16 v[24:27], v[182:185], v[194:197], v[24:27]
	v_mfma_f32_16x16x32_bf16 v[28:31], v[186:189], v[194:197], v[28:31]
	s_waitcnt vmcnt(0)
	s_waitcnt lgkmcnt(0)
	s_barrier
	s_add_i32 s1, s1, 0x8000
	s_cmp_eq_u32 s1, 0x78000
	s_cbranch_scc1 .Lgk_tail_766
	v_or_b32_e32 v164, s9, v131
	v_add_u32_e32 v165, s9, v128
	s_add_i32 s12, s8, s13
	ds_read_b128 v[190:193], v165
	ds_read_b128 v[106:109], v164 offset:16384
	s_mov_b32 m0, s12
	s_nop 0
	v_mfma_f32_16x16x32_bf16 v[32:35], v[174:177], v[198:201], v[32:35]
	global_load_lds_dwordx4 v254, s[98:99]
	ds_read_b128 v[118:121], v164 offset:16896
	v_mfma_f32_16x16x32_bf16 v[36:39], v[178:181], v[198:201], v[36:39]
	ds_read_b128 v[122:125], v164 offset:20480
	v_mfma_f32_16x16x32_bf16 v[40:43], v[182:185], v[198:201], v[40:43]
	ds_read_b128 v[170:173], v164 offset:20992
	s_add_i32 m0, s12, 0x1000
	s_add_u32 s10, s98, s16
	s_addc_u32 s11, s99, 0
	v_mfma_f32_16x16x32_bf16 v[44:47], v[186:189], v[198:201], v[44:47]
	global_load_lds_dwordx4 v254, s[10:11]
	ds_read_b128 v[194:197], v165 offset:2048
	ds_read_b128 v[198:201], v165 offset:4096
	v_mfma_f32_16x16x32_bf16 v[48:51], v[174:177], v[246:249], v[48:51]
	v_mfma_f32_16x16x32_bf16 v[52:55], v[178:181], v[246:249], v[52:55]
	s_add_i32 m0, s12, 0x2000
	s_add_u32 s10, s10, s16
	s_addc_u32 s11, s11, 0
	v_mfma_f32_16x16x32_bf16 v[56:59], v[182:185], v[246:249], v[56:59]
	global_load_lds_dwordx4 v254, s[10:11]
	v_mfma_f32_16x16x32_bf16 v[60:63], v[186:189], v[246:249], v[60:63]
	ds_read_b128 v[246:249], v165 offset:6144
	s_branch .Lgk_loop_766

; __device__ __forceinline__ f32x4 zero4() { return (f32x4){0.f, 0.f, 0.f, 0.f}; }
; template <int KW, int VD, bool SEL> ...
;     ...
;     int koff[NKI], voff[NVI];
; #pragma unroll
;     for (int i = 0; i < NKI; ++i) {
;         const int row = (w + 4 * i) * KRPI + lane / KCPR, cp = lane % KCPR;
;         const int f = (KW == 64) ? (((row >> 1) & 1) | (((row >> 3) & 1) << 1) | (((row >> 4) & 1) << 2)) : ((row & 3) | (((row >> 3) & 3) << 2));
;         koff[i] = row * ldk + (cp ^ f) * 8;
;     }
; #pragma unroll
;     for (int i = 0; i < NVI; ++i) {
;         const int row = (w + 4 * i) * 8 + (lane >> 3), cp = lane & 7;
;         voff[i] = row * S + (cp ^ ((row >> 1) & 7)) * 8;
;     }
;     ...
;     int j = __ffsll((long long)tiles) - 1; tiles &= tiles - 1;
;     FL_ISSUE(0, j);
;     asm volatile("s_waitcnt vmcnt(0)" ::: "memory");
;     __syncthreads();
; __device__ __forceinline__ void diff_tile(const Params& p, int qb, int bh, float lam, char* smem) {
;     int tid = threadIdx.x; asm volatile("" : "+v"(tid));
;     const int lane = tid & 63, w = tid >> 6, fr = lane & 15, fq = lane >> 4;
;     const int b = bh >> 3, h = bh & 7, map = w >> 1, half = w & 1, tw0 = qb * 64 + half * 32;
;     const bf16_t* projA = (const bf16_t*)(p.ws + OFF_PROJA);
;     const bf16_t* projVT = (const bf16_t*)(p.ws + OFF_PROJVT);
;     bf16x8 qf[2][2];
;     int tpos[2];
; #pragma unroll
;     for (int qt = 0; qt < 2; ++qt) {
;         tpos[qt] = tw0 + qt * 16 + fr;
;         const bf16_t* qrow = projA + (size_t)(b * S + tpos[qt]) * LDA + (h * 2 + map) * 64;
; #pragma unroll
;         for (int ks = 0; ks < 2; ++ks) qf[qt][ks] = *(const bf16x8*)(qrow + ks * 32 + fq * 8);
;     }
;     f32x4 O[2][8];
; #pragma unroll
;     for (int qt = 0; qt < 2; ++qt)
; #pragma unroll
;         for (int dt = 0; dt < 8; ++dt) O[qt][dt] = zero4();
;     float mr[2] = {-1e30f, -1e30f}, lr[2] = {0.f, 0.f};
;     const int lo[2] = {-1, -1};
;     const u64 ones[2] = {~0ull, ~0ull};
;     const u64 tiles = (qb == 63) ? ~0ull : ((1ull << (qb + 1)) - 1ull);
;     flash_branch<128, 128, false>(tiles, projA + (size_t)b * S * LDA + 1024 + h * 128, LDA, projVT + ((size_t)b * 1024 + h * 128) * S, map * 64,
;                                   qf, O, mr, lr, tpos, ones, lo, qb * 64, -1, smem);
.LBB0_817:
	s_bitcmp0_b32 s17, 0
	v_readlane_b32 s7, v245, 0
	v_readlane_b32 s8, v245, 62
	s_cselect_b32 s7, s7, s8
	s_add_i32 s6, s7, s6
	s_cmpk_gt_i32 s6, 0xfff
	s_cbranch_scc1 .LBB0_816
	v_mov_b32_e32 v172, v114
	s_lshl_b32 s9, s6, 7
	s_and_b32 s18, s9, 0x380
	v_and_b32_e32 v0, 15, v172
	v_ashrrev_i32_e32 v173, 7, v172
	v_lshrrev_b32_e32 v1, 1, v172
	s_and_b32 s7, s6, 0xffffffc0
	v_and_or_b32 v171, v1, 32, v0
	v_lshl_add_u32 v0, v173, 6, s18
	v_readlane_b32 s20, v245, 55
	v_bfe_u32 v170, v172, 4, 2
	s_sub_i32 s19, 0xfc0, s7
	v_ashrrev_i32_e32 v1, 31, v0
	v_readlane_b32 s21, v245, 56
	s_bfe_u32 s8, s6, 0x30003
	v_or_b32_e32 v127, s19, v171
	v_lshl_add_u64 v[0:1], v[0:1], 1, s[20:21]
	v_lshlrev_b32_e32 v124, 4, v170
	v_mov_b32_e32 v125, v119
	s_lshl_b32 s7, s8, 12
	v_lshl_add_u64 v[0:1], v[0:1], 0, v[124:125]
	v_or_b32_e32 v125, 16, v127
	v_add_u32_e32 v118, s7, v127
	v_add_u32_e32 v126, s7, v125
	v_mad_u64_u32 v[2:3], s[10:11], v118, s3, v[0:1]
	v_mad_u64_u32 v[0:1], s[10:11], v126, s3, v[0:1]
	global_load_dwordx4 v[64:67], v[2:3], off
	global_load_dwordx4 v[68:71], v[2:3], off offset:64
	global_load_dwordx4 v[72:75], v[0:1], off
	global_load_dwordx4 v[76:79], v[0:1], off offset:64
	s_ashr_i32 s7, s6, 6
	s_sub_i32 s7, 64, s7
	s_lshl_b64 s[10:11], -1, s7
	s_not_b64 s[10:11], s[10:11]
	s_cmp_gt_u32 s6, 63
	s_cselect_b32 s7, s11, -1
	s_cselect_b32 s6, s10, -1
	v_mov_b32_e32 v0, v114
	s_cmp_eq_u64 s[6:7], 0
	s_cbranch_scc1 .LBB0_838
	v_ashrrev_i32_e32 v2, 6, v0
	v_bfe_u32 v1, v0, 4, 2
	v_lshlrev_b32_e32 v3, 2, v2
	v_lshlrev_b32_e32 v6, 1, v2
	v_and_b32_e32 v4, 15, v0
	v_or_b32_e32 v5, v3, v1
	v_and_b32_e32 v6, 12, v6
	s_mul_i32 s9, s8, 0x1100000
	v_mul_lo_u32 v5, v5, s12
	v_bitop3_b32 v6, v6, v4, v1 bitop3:0x36
	s_add_u32 s9, s20, s9
	v_lshl_or_b32 v128, v6, 3, v5
	v_add_u32_e32 v5, 16, v3
	s_addc_u32 s10, s21, 0
	s_lshl_b32 s11, s18, 1
	v_or_b32_e32 v6, v5, v1
	v_lshrrev_b32_e32 v5, 1, v5
	s_add_u32 s20, s9, s11
	v_and_b32_e32 v5, 12, v5
	s_addc_u32 s21, s10, 0
	s_lshl_b32 s8, s8, 23
	v_readlane_b32 s9, v245, 57
	v_mul_lo_u32 v6, v6, s12
	v_bitop3_b32 v5, v5, v4, v1 bitop3:0x36
	v_add_u32_e32 v3, 48, v3
	s_add_u32 s8, s9, s8
	v_readlane_b32 s9, v245, 58
	v_lshl_or_b32 v130, v5, 3, v6
	v_or_b32_e32 v5, v3, v1
	v_lshrrev_b32_e32 v3, 1, v3
	s_addc_u32 s9, s9, 0
	s_lshl_b32 s10, s18, 13
	v_and_b32_e32 v3, 12, v3
	s_add_u32 s22, s8, s10
	v_mul_lo_u32 v5, v5, s12
	v_bitop3_b32 v3, v3, v4, v1 bitop3:0x36
	s_addc_u32 s23, s9, 0
	v_lshl_or_b32 v134, v3, 3, v5
	v_bfe_u32 v3, v0, 3, 3
	v_lshl_or_b32 v3, v2, 3, v3
	s_ff1_i32_b64 s10, s[6:7]
	s_add_u32 s8, s6, -1
	v_lshlrev_b32_e32 v5, 12, v3
	v_lshrrev_b32_e32 v3, 1, v3
	s_addc_u32 s9, s7, -1
	s_mul_i32 s11, s10, 0x44000
	v_xor_b32_e32 v3, v3, v0
	s_add_u32 s24, s20, s11
	v_lshlrev_b32_e32 v3, 3, v3
	v_lshlrev_b32_e32 v174, 10, v2
	s_addc_u32 s25, s21, 0
	v_ashrrev_i32_e32 v129, 31, v128
	v_and_or_b32 v136, v3, 56, v5
	v_lshl_add_u64 v[2:3], v[128:129], 1, s[24:25]
	v_readfirstlane_b32 s26, v174
	v_lshl_add_u64 v[2:3], v[2:3], 0, s[0:1]
	s_mov_b32 m0, s26
	v_ashrrev_i32_e32 v131, 31, v130
	v_add_u32_e32 v5, 0x1000, v174
	v_add_u32_e32 v132, 0x11000, v128
	global_load_lds_dwordx4 v[2:3], off
	v_lshl_add_u64 v[2:3], v[130:131], 1, s[24:25]
	v_readfirstlane_b32 s26, v5
	v_lshl_add_u64 v[2:3], v[2:3], 0, s[0:1]
	s_mov_b32 m0, s26
	v_ashrrev_i32_e32 v133, 31, v132
	v_add_u32_e32 v5, 0x2000, v174
	global_load_lds_dwordx4 v[2:3], off
	v_lshl_add_u64 v[2:3], v[132:133], 1, s[24:25]
	v_readfirstlane_b32 s26, v5
	v_lshl_add_u64 v[2:3], v[2:3], 0, s[0:1]
	s_mov_b32 m0, s26
	v_ashrrev_i32_e32 v135, 31, v134
	v_add_u32_e32 v5, 0x3000, v174
	s_lshl_b32 s11, s10, 7
	global_load_lds_dwordx4 v[2:3], off
	v_lshl_add_u64 v[2:3], v[134:135], 1, s[24:25]
	v_readfirstlane_b32 s24, v5
	s_mov_b32 m0, s24
	s_add_u32 s24, s22, s11
	v_add_u32_e32 v5, 0x4000, v174
	v_add_u32_e32 v138, 0x20000, v136
	v_lshl_add_u64 v[2:3], v[2:3], 0, s[0:1]
	s_addc_u32 s25, s23, 0
	v_ashrrev_i32_e32 v137, 31, v136
	v_readfirstlane_b32 s11, v5
	v_add_u32_e32 v5, 0x5000, v174
	v_add_u32_e32 v140, 0x40000, v136
	global_load_lds_dwordx4 v[2:3], off
	v_lshl_add_u64 v[2:3], v[136:137], 1, s[24:25]
	s_mov_b32 m0, s11
	v_ashrrev_i32_e32 v139, 31, v138
	v_readfirstlane_b32 s11, v5
	v_add_u32_e32 v5, 0x6000, v174
	v_add_u32_e32 v142, 0x60000, v136
	global_load_lds_dwordx4 v[2:3], off
	v_lshl_add_u64 v[2:3], v[138:139], 1, s[24:25]
	s_mov_b32 m0, s11
	v_ashrrev_i32_e32 v141, 31, v140
	v_readfirstlane_b32 s11, v5
	v_add_u32_e32 v5, 0x7000, v174
	global_load_lds_dwordx4 v[2:3], off
	v_lshl_add_u64 v[2:3], v[140:141], 1, s[24:25]
	s_mov_b32 m0, s11
	v_ashrrev_i32_e32 v143, 31, v142
	v_readfirstlane_b32 s11, v5
	global_load_lds_dwordx4 v[2:3], off
	v_lshl_add_u64 v[2:3], v[142:143], 1, s[24:25]
	s_mov_b32 m0, s11
	v_lshlrev_b32_e32 v5, 1, v0
	global_load_lds_dwordx4 v[2:3], off
	v_lshrrev_b32_e32 v2, 1, v0
	v_bfe_u32 v3, v0, 1, 3
	v_and_b32_e32 v0, 3, v0
	v_and_or_b32 v0, v5, 24, v0
	v_lshlrev_b32_e32 v5, 3, v173
	v_or_b32_e32 v6, v1, v5
	v_bitop3_b32 v5, v1, v4, v5 bitop3:0x36
	v_lshlrev_b32_e32 v179, 8, v0
	v_bitop3_b32 v0, v1, v2, 7 bitop3:0x78
	s_waitcnt vmcnt(0)
	v_lshlrev_b32_e32 v175, 4, v5
	v_bitop3_b32 v5, v6, v4, 4 bitop3:0x36
	v_lshlrev_b32_e32 v180, 4, v0
	v_bitop3_b32 v0, v1, v3, 4 bitop3:0x36
	v_mov_b32_e32 v8, v119
	v_mov_b32_e32 v9, v119
	v_mov_b32_e32 v10, v119
	v_mov_b32_e32 v11, v119
	v_lshlrev_b32_e32 v176, 4, v5
	v_lshlrev_b32_e32 v177, 3, v1
	v_lshlrev_b32_e32 v178, 7, v4
	v_lshlrev_b32_e32 v181, 4, v0
	v_mov_b64_e32 v[14:15], v[10:11]
	v_mov_b64_e32 v[18:19], v[10:11]
	v_mov_b64_e32 v[22:23], v[10:11]
	v_mov_b64_e32 v[26:27], v[10:11]
	v_mov_b64_e32 v[30:31], v[10:11]
	v_mov_b64_e32 v[34:35], v[10:11]
	v_mov_b64_e32 v[38:39], v[10:11]
	v_mov_b64_e32 v[42:43], v[10:11]
	v_mov_b64_e32 v[46:47], v[10:11]
	v_mov_b64_e32 v[50:51], v[10:11]
	v_mov_b64_e32 v[54:55], v[10:11]
	v_mov_b64_e32 v[58:59], v[10:11]
	v_mov_b64_e32 v[62:63], v[10:11]
	v_mov_b64_e32 v[4:5], v[8:9]
	v_mov_b64_e32 v[0:1], v[8:9]
	s_and_b64 s[6:7], s[8:9], s[6:7]
	s_mov_b32 s24, 0
	v_mov_b32_e32 v182, 0xf149f2ca
	v_mov_b32_e32 v144, 0
	v_mov_b64_e32 v[12:13], v[8:9]
	v_mov_b64_e32 v[16:17], v[8:9]
	v_mov_b64_e32 v[20:21], v[8:9]
	v_mov_b64_e32 v[24:25], v[8:9]
	v_mov_b64_e32 v[28:29], v[8:9]
	v_mov_b64_e32 v[32:33], v[8:9]
	v_mov_b64_e32 v[36:37], v[8:9]
	v_mov_b64_e32 v[40:41], v[8:9]
	v_mov_b64_e32 v[44:45], v[8:9]
	v_mov_b64_e32 v[48:49], v[8:9]
	v_mov_b64_e32 v[52:53], v[8:9]
	v_mov_b64_e32 v[56:57], v[8:9]
	v_mov_b64_e32 v[60:61], v[8:9]
	v_mov_b64_e32 v[6:7], v[10:11]
	v_mov_b64_e32 v[2:3], v[10:11]
	v_mov_b32_e32 v145, 0
	v_mov_b32_e32 v183, 0xf149f2ca
	v_lshlrev_b32_e32 v246, 1, v128
	v_lshlrev_b32_e32 v247, 1, v130
	v_lshlrev_b32_e32 v248, 1, v132
	v_lshlrev_b32_e32 v249, 1, v134
	v_lshlrev_b32_e32 v250, 1, v136
	v_lshlrev_b32_e32 v251, 1, v138
	v_lshlrev_b32_e32 v252, 1, v140
	v_lshlrev_b32_e32 v253, 1, v142
	s_waitcnt vmcnt(0) lgkmcnt(0)
	s_barrier
	s_cmp_lg_u64 s[6:7], 0
	s_cbranch_scc1 .LBB0_822
	s_branch .LBB0_821

; template <int KW, int VD, bool SEL> ...
;     ...
;     while (true) {
;         int jn = -1;
;         if (tiles) { jn = __ffsll((long long)tiles) - 1; tiles &= tiles - 1; FL_ISSUE(cur ^ 1, jn); }
.LBB0_822:
	s_add_u32 s8, s6, -1
	s_addc_u32 s9, s7, -1
	s_lshl_b32 s26, s24, 15
	s_ff1_i32_b64 s25, s[6:7]
	s_and_b64 s[6:7], s[8:9], s[6:7]
	s_branch .LBB0_824

; __device__ __forceinline__ f32x4 mfma16(bf16x8 a, bf16x8 b, f32x4 c) { return __builtin_amdgcn_mfma_f32_16x16x32_bf16(a, b, c, 0, 0, 0); }
; template <int KW, int VD, bool SEL> ...
;     ...
;         if (tiles) { jn = __ffsll((long long)tiles) - 1; tiles &= tiles - 1; FL_ISSUE(cur ^ 1, jn); }
;         const char* sK = smem + cur * BUFB;
;         const char* sV = smem + cur * BUFB + KB;
;         f32x4 s[2][4];
;         const float mref0 = (mrow[0] < -1e29f) ? 0.f : mrow[0], mref1 = (mrow[1] < -1e29f) ? 0.f : mrow[1];
;         const float ci0 = (SEL && !((((const u64*)(smem + 69632))[fr] >> j) & 1ull)) ? -1e30f : -mref0;
;         const float ci1 = (SEL && !((((const u64*)(smem + 69632))[16 + fr] >> j) & 1ull)) ? -1e30f : -mref1;
;         const f32x4 cinit0 = (f32x4){ci0, ci0, ci0, ci0}, cinit1 = (f32x4){ci1, ci1, ci1, ci1};
; #pragma unroll
;         for (int tt = 0; tt < 4; ++tt) {
;             const int kr = 32 * (tt >> 1) + (fr >> 2) * 8 + (tt & 1) * 4 + (fr & 3);
;             const bf16x8 kf0 = *(const bf16x8*)(sK + kr * KROWB + (((kcol >> 3) + fq) ^ kswz) * 16);
;             const bf16x8 kf1 = *(const bf16x8*)(sK + kr * KROWB + (((kcol >> 3) + 4 + fq) ^ kswz) * 16);
;             s[0][tt] = mfma16(kf0, qf[0][0], cinit0);
;             s[1][tt] = mfma16(kf0, qf[1][0], cinit1);
;             s[0][tt] = mfma16(kf1, qf[0][1], s[0][tt]);
;             s[1][tt] = mfma16(kf1, qf[1][1], s[1][tt]);
;         }
.LBB0_824:
	v_add_u32_e32 v100, s26, v179
	v_add_u32_e32 v185, v100, v175
	ds_read_b128 v[80:83], v185
	ds_read_b128 v[92:95], v185 offset:1024
	v_cmp_ngt_f32_e32 vcc, s13, v182
	v_add_u32_e32 v194, v100, v176
	ds_read_b128 v[100:103], v194
	ds_read_b128 v[186:189], v194 offset:1024
	s_cmp_lt_i32 s25, 0
	s_cbranch_scc1 .Lfh_diff_nodma
	v_readfirstlane_b32 s27, v174
	s_mul_i32 s28, s25, 0x44000
	s_add_u32 s28, s20, s28
	s_addc_u32 s29, s21, 0
	s_add_u32 s28, s28, s0
	s_addc_u32 s29, s29, s1
	s_lshl_b32 s11, s25, 7
	s_add_u32 s98, s22, s11
	s_addc_u32 s99, s23, 0
	s_xor_b32 s11, s26, 0x8000
	s_add_i32 s11, s11, s27
	s_mov_b32 m0, s11
	s_nop 0
	global_load_lds_dwordx4 v246, s[28:29]
	s_add_i32 m0, s11, 0x1000
	s_nop 0
	global_load_lds_dwordx4 v247, s[28:29]
	s_add_i32 m0, s11, 0x2000
	s_nop 0
	global_load_lds_dwordx4 v248, s[28:29]
	s_add_i32 m0, s11, 0x3000
	s_nop 0
	global_load_lds_dwordx4 v249, s[28:29]
	s_add_i32 m0, s11, 0x4000
	s_nop 0
	global_load_lds_dwordx4 v250, s[98:99]
	s_add_i32 m0, s11, 0x5000
	s_nop 0
	global_load_lds_dwordx4 v251, s[98:99]
	s_add_i32 m0, s11, 0x6000
	s_nop 0
	global_load_lds_dwordx4 v252, s[98:99]
	s_add_i32 m0, s11, 0x7000
	s_nop 0
	global_load_lds_dwordx4 v253, s[98:99]
.Lfh_diff_nodma:
	v_cndmask_b32_e32 v199, 0, v182, vcc
	v_cmp_ngt_f32_e32 vcc, s13, v183
	v_xor_b32_e32 v84, 0x80000000, v199
	v_mov_b32_e32 v85, v84
	v_cndmask_b32_e32 v184, 0, v183, vcc
	v_xor_b32_e32 v88, 0x80000000, v184
	v_mov_b32_e32 v86, v84
	v_mov_b32_e32 v87, v84
	v_mov_b32_e32 v89, v88
	v_mov_b32_e32 v90, v88
	v_mov_b32_e32 v91, v88
	s_waitcnt lgkmcnt(0)
	v_mfma_f32_16x16x32_bf16 v[96:99], v[80:83], v[64:67], v[84:87]
	s_lshl_b32 s27, s10, 6
	s_or_b32 s10, s27, 63
	s_cmp_le_u32 s10, s19
	v_mfma_f32_16x16x32_bf16 v[80:83], v[80:83], v[72:75], v[88:91]
	s_cselect_b64 s[8:9], -1, 0
	s_cmp_gt_u32 s10, s19
	s_mov_b64 s[10:11], -1
	v_mfma_f32_16x16x32_bf16 v[108:111], v[100:103], v[68:71], v[96:99]
	v_mfma_f32_16x16x32_bf16 v[96:99], v[100:103], v[76:79], v[80:83]
	v_mfma_f32_16x16x32_bf16 v[80:83], v[92:95], v[64:67], v[84:87]
	v_mfma_f32_16x16x32_bf16 v[92:95], v[92:95], v[72:75], v[88:91]
	v_mfma_f32_16x16x32_bf16 v[104:107], v[186:189], v[68:71], v[80:83]
	v_mfma_f32_16x16x32_bf16 v[100:103], v[186:189], v[76:79], v[92:95]
	s_nop 4
	ds_read_b128 v[80:83], v185 offset:8192
	ds_read_b128 v[186:189], v185 offset:9216
	ds_read_b128 v[190:193], v194 offset:8192
	ds_read_b128 v[194:197], v194 offset:9216
	s_waitcnt lgkmcnt(3)
	v_mfma_f32_16x16x32_bf16 v[92:95], v[80:83], v[64:67], v[84:87]
	v_mfma_f32_16x16x32_bf16 v[80:83], v[80:83], v[72:75], v[88:91]
	s_waitcnt lgkmcnt(2)
	v_mfma_f32_16x16x32_bf16 v[84:87], v[186:189], v[64:67], v[84:87]
	v_mfma_f32_16x16x32_bf16 v[186:189], v[186:189], v[72:75], v[88:91]
	s_waitcnt lgkmcnt(1)
	v_mfma_f32_16x16x32_bf16 v[92:95], v[190:193], v[68:71], v[92:95]
	v_mfma_f32_16x16x32_bf16 v[80:83], v[190:193], v[76:79], v[80:83]
	s_waitcnt lgkmcnt(0)
	v_mfma_f32_16x16x32_bf16 v[88:91], v[194:197], v[68:71], v[84:87]
	v_mfma_f32_16x16x32_bf16 v[84:87], v[194:197], v[76:79], v[186:189]
	s_cbranch_scc1 .LBB0_826
	s_mov_b64 s[10:11], 0

; template <int KW, int VD, bool SEL> ...
;     ...
;             float mx = fmaxf(fmaxf(s[qt][0][0], s[qt][0][1]), fmaxf(s[qt][0][2], s[qt][0][3]));
; #pragma unroll
;             for (int tt = 1; tt < 4; ++tt) mx = fmaxf(mx, fmaxf(fmaxf(s[qt][tt][0], s[qt][tt][1]), fmaxf(s[qt][tt][2], s[qt][tt][3])));
;             const float mref = qt ? mref1 : mref0;
;             if (__builtin_amdgcn_ballot_w64(mx > (mrow[qt] - mref) + 8.0f) != 0ull) {
;                 mx = fmaxf(mx, __shfl_xor(mx, 16));
;                 mx = fmaxf(mx, __shfl_xor(mx, 32));
;                 const float mnew = fmaxf(mrow[qt], mx + mref);
;                 const float alpha = __builtin_amdgcn_exp2f(mrow[qt] - mnew);
;                 const float delta = ((mnew < -1e29f) ? 0.f : mnew) - mref;
;                 lrow[qt] *= alpha;
;                 mrow[qt] = mnew;
; #pragma unroll
;                 for (int dt = 0; dt < VD / 16; ++dt) O[qt][dt] = O[qt][dt] * alpha;
; #pragma unroll
;                 for (int tt = 0; tt < 4; ++tt)
; #pragma unroll
;                     for (int jj = 0; jj < 4; ++jj) s[qt][tt][jj] -= delta;
;             }
.LBB0_828:
	v_max3_f32 v200, v88, v89, v90
	v_max3_f32 v201, v91, v92, v93
	v_max3_f32 v200, v200, v94, v95
	v_max3_f32 v201, v201, v104, v105
	v_max3_f32 v200, v200, v106, v107
	v_max3_f32 v201, v201, v108, v109
	v_max3_f32 v200, v200, v110, v111
	v_max_f32_e32 v200, v200, v201
	v_sub_f32_e32 v201, v182, v199
	v_add_f32_e32 v201, 0x41000000, v201
	v_cmp_gt_f32_e32 vcc, v200, v201
	s_cbranch_vccz .LBB0_830
	ds_bpermute_b32 v201, v163, v200
	v_max_f32_e32 v200, v200, v200
	v_max_f32_e32 v202, v182, v182
	s_waitcnt lgkmcnt(0)
	v_max_f32_e32 v201, v201, v201
	v_max_f32_e32 v200, v200, v201
	ds_bpermute_b32 v201, v162, v200
	s_waitcnt lgkmcnt(0)
	v_max_f32_e32 v201, v201, v201
	v_max_f32_e32 v200, v200, v201
	v_add_f32_e32 v200, v199, v200
	v_max_f32_e32 v200, v202, v200
	v_sub_f32_e32 v182, v182, v200
	v_exp_f32_e32 v182, v182
	v_cmp_ngt_f32_e32 vcc, s13, v200
	v_mul_f32_e32 v145, v145, v182
	s_nop 0
	v_cndmask_b32_e32 v201, 0, v200, vcc
	v_pk_mul_f32 v[62:63], v[62:63], v[182:183] op_sel_hi:[1,0]
	v_pk_mul_f32 v[60:61], v[60:61], v[182:183] op_sel_hi:[1,0]
	v_pk_mul_f32 v[58:59], v[58:59], v[182:183] op_sel_hi:[1,0]
	v_pk_mul_f32 v[56:57], v[56:57], v[182:183] op_sel_hi:[1,0]
	v_pk_mul_f32 v[54:55], v[54:55], v[182:183] op_sel_hi:[1,0]
	v_pk_mul_f32 v[52:53], v[52:53], v[182:183] op_sel_hi:[1,0]
	v_pk_mul_f32 v[50:51], v[50:51], v[182:183] op_sel_hi:[1,0]
	v_pk_mul_f32 v[48:49], v[48:49], v[182:183] op_sel_hi:[1,0]
	v_pk_mul_f32 v[46:47], v[46:47], v[182:183] op_sel_hi:[1,0]
	v_pk_mul_f32 v[44:45], v[44:45], v[182:183] op_sel_hi:[1,0]
	v_pk_mul_f32 v[42:43], v[42:43], v[182:183] op_sel_hi:[1,0]
	v_pk_mul_f32 v[40:41], v[40:41], v[182:183] op_sel_hi:[1,0]
	v_pk_mul_f32 v[38:39], v[38:39], v[182:183] op_sel_hi:[1,0]
	v_pk_mul_f32 v[36:37], v[36:37], v[182:183] op_sel_hi:[1,0]
	v_pk_mul_f32 v[34:35], v[34:35], v[182:183] op_sel_hi:[1,0]
	v_pk_mul_f32 v[32:33], v[32:33], v[182:183] op_sel_hi:[1,0]
	v_sub_f32_e32 v182, v201, v199
	v_pk_add_f32 v[108:109], v[108:109], v[182:183] op_sel_hi:[1,0] neg_lo:[0,1] neg_hi:[0,1]
	v_pk_add_f32 v[110:111], v[110:111], v[182:183] op_sel_hi:[1,0] neg_lo:[0,1] neg_hi:[0,1]
	v_pk_add_f32 v[104:105], v[104:105], v[182:183] op_sel_hi:[1,0] neg_lo:[0,1] neg_hi:[0,1]
	v_pk_add_f32 v[106:107], v[106:107], v[182:183] op_sel_hi:[1,0] neg_lo:[0,1] neg_hi:[0,1]
	v_pk_add_f32 v[92:93], v[92:93], v[182:183] op_sel_hi:[1,0] neg_lo:[0,1] neg_hi:[0,1]
	v_pk_add_f32 v[94:95], v[94:95], v[182:183] op_sel_hi:[1,0] neg_lo:[0,1] neg_hi:[0,1]
	v_pk_add_f32 v[88:89], v[88:89], v[182:183] op_sel_hi:[1,0] neg_lo:[0,1] neg_hi:[0,1]
	v_pk_add_f32 v[90:91], v[90:91], v[182:183] op_sel_hi:[1,0] neg_lo:[0,1] neg_hi:[0,1]
	v_mov_b32_e32 v182, v200

; template <int KW, int VD, bool SEL> ...
;     ...
;             float mx = fmaxf(fmaxf(s[qt][0][0], s[qt][0][1]), fmaxf(s[qt][0][2], s[qt][0][3]));
; #pragma unroll
;             for (int tt = 1; tt < 4; ++tt) mx = fmaxf(mx, fmaxf(fmaxf(s[qt][tt][0], s[qt][tt][1]), fmaxf(s[qt][tt][2], s[qt][tt][3])));
;             const float mref = qt ? mref1 : mref0;
;             if (__builtin_amdgcn_ballot_w64(mx > (mrow[qt] - mref) + 8.0f) != 0ull) {
;                 mx = fmaxf(mx, __shfl_xor(mx, 16));
;                 mx = fmaxf(mx, __shfl_xor(mx, 32));
;                 const float mnew = fmaxf(mrow[qt], mx + mref);
;                 const float alpha = __builtin_amdgcn_exp2f(mrow[qt] - mnew);
;                 const float delta = ((mnew < -1e29f) ? 0.f : mnew) - mref;
;                 lrow[qt] *= alpha;
;                 mrow[qt] = mnew;
; #pragma unroll
;                 for (int dt = 0; dt < VD / 16; ++dt) O[qt][dt] = O[qt][dt] * alpha;
; #pragma unroll
;                 for (int tt = 0; tt < 4; ++tt)
; #pragma unroll
;                     for (int jj = 0; jj < 4; ++jj) s[qt][tt][jj] -= delta;
;             }
.LBB0_834:
	v_max3_f32 v185, v80, v81, v82
	v_max3_f32 v186, v83, v84, v85
	v_max3_f32 v185, v185, v86, v87
	v_max3_f32 v186, v186, v96, v97
	v_max3_f32 v185, v185, v98, v99
	v_max3_f32 v186, v186, v100, v101
	v_max3_f32 v185, v185, v102, v103
	v_max_f32_e32 v185, v185, v186
	v_sub_f32_e32 v186, v183, v184
	v_add_f32_e32 v186, 0x41000000, v186
	v_cmp_gt_f32_e32 vcc, v185, v186
	s_cbranch_vccz .LBB0_836
	ds_bpermute_b32 v186, v163, v185
	v_max_f32_e32 v185, v185, v185
	v_max_f32_e32 v187, v183, v183
	s_waitcnt lgkmcnt(0)
	v_max_f32_e32 v186, v186, v186
	v_max_f32_e32 v185, v185, v186
	ds_bpermute_b32 v186, v162, v185
	s_waitcnt lgkmcnt(0)
	v_max_f32_e32 v186, v186, v186
	v_max_f32_e32 v185, v185, v186
	v_add_f32_e32 v185, v184, v185
	v_max_f32_e32 v185, v187, v185
	v_sub_f32_e32 v183, v183, v185
	v_exp_f32_e32 v186, v183
	v_cmp_ngt_f32_e32 vcc, s13, v185
	v_mul_f32_e32 v144, v144, v186
	s_nop 0
	v_cndmask_b32_e32 v183, 0, v185, vcc
	v_sub_f32_e32 v184, v183, v184
	v_pk_mul_f32 v[30:31], v[30:31], v[186:187] op_sel_hi:[1,0]
	v_pk_mul_f32 v[28:29], v[28:29], v[186:187] op_sel_hi:[1,0]
	v_pk_mul_f32 v[26:27], v[26:27], v[186:187] op_sel_hi:[1,0]
	v_pk_mul_f32 v[24:25], v[24:25], v[186:187] op_sel_hi:[1,0]
	v_pk_mul_f32 v[22:23], v[22:23], v[186:187] op_sel_hi:[1,0]
	v_pk_mul_f32 v[20:21], v[20:21], v[186:187] op_sel_hi:[1,0]
	v_pk_mul_f32 v[18:19], v[18:19], v[186:187] op_sel_hi:[1,0]
	v_pk_mul_f32 v[16:17], v[16:17], v[186:187] op_sel_hi:[1,0]
	v_pk_mul_f32 v[14:15], v[14:15], v[186:187] op_sel_hi:[1,0]
	v_pk_mul_f32 v[12:13], v[12:13], v[186:187] op_sel_hi:[1,0]
	v_pk_mul_f32 v[10:11], v[10:11], v[186:187] op_sel_hi:[1,0]
	v_pk_mul_f32 v[8:9], v[8:9], v[186:187] op_sel_hi:[1,0]
	v_pk_mul_f32 v[6:7], v[6:7], v[186:187] op_sel_hi:[1,0]
	v_pk_mul_f32 v[4:5], v[4:5], v[186:187] op_sel_hi:[1,0]
	v_pk_mul_f32 v[2:3], v[2:3], v[186:187] op_sel_hi:[1,0]
	v_pk_mul_f32 v[0:1], v[0:1], v[186:187] op_sel_hi:[1,0]
	v_pk_add_f32 v[96:97], v[96:97], v[184:185] op_sel_hi:[1,0] neg_lo:[0,1] neg_hi:[0,1]
	v_pk_add_f32 v[98:99], v[98:99], v[184:185] op_sel_hi:[1,0] neg_lo:[0,1] neg_hi:[0,1]
	v_pk_add_f32 v[100:101], v[100:101], v[184:185] op_sel_hi:[1,0] neg_lo:[0,1] neg_hi:[0,1]
	v_pk_add_f32 v[102:103], v[102:103], v[184:185] op_sel_hi:[1,0] neg_lo:[0,1] neg_hi:[0,1]
	v_pk_add_f32 v[80:81], v[80:81], v[184:185] op_sel_hi:[1,0] neg_lo:[0,1] neg_hi:[0,1]
	v_pk_add_f32 v[82:83], v[82:83], v[184:185] op_sel_hi:[1,0] neg_lo:[0,1] neg_hi:[0,1]
	v_pk_add_f32 v[84:85], v[84:85], v[184:185] op_sel_hi:[1,0] neg_lo:[0,1] neg_hi:[0,1]
	v_pk_add_f32 v[86:87], v[86:87], v[184:185] op_sel_hi:[1,0] neg_lo:[0,1] neg_hi:[0,1]
	v_mov_b32_e32 v183, v185

; __device__ __forceinline__ f32x4 mfma16(bf16x8 a, bf16x8 b, f32x4 c) { return __builtin_amdgcn_mfma_f32_16x16x32_bf16(a, b, c, 0, 0, 0); }
; template <class Epi>
; __device__ __forceinline__ void gemm_tile(const bf16_t* __restrict__ A, const bf16_t* __restrict__ Bt, int K, int row0, int col0, const Epi& epi, char* smem,
;                                           bool prefetched, bool nvalid, int nrow0, int ncol0) {
;     ...
;     for (int kt = 0; kt < nk; ++kt) {
;         const int cur = kt & 1;
;         if (kt + 1 < nk) GLDS_STAGE(cur ^ 1, pA, pB, kt + 1);
;         const char* cb = smem + cur * 2 * TILE_B;
; #pragma unroll
;         for (int ks = 0; ks < 2; ++ks) {
;             bf16x8 a[4], b[4];
; #pragma unroll
;             for (int m = 0; m < 4; ++m) a[m] = *(const bf16x8*)(cb + offA[m][ks]);
; #pragma unroll
;             for (int n = 0; n < 4; ++n) b[n] = *(const bf16x8*)(cb + offB[n][ks]);
; #pragma unroll
;             for (int m = 0; m < 4; ++m)
; #pragma unroll
;                 for (int n = 0; n < 4; ++n) acc[m][n] = mfma16(b[n], a[m], acc[m][n]);
;         }
;         asm volatile("s_waitcnt vmcnt(0)" ::: "memory");
;         __syncthreads();
.Lgk_loop_895:
	s_and_b32 s3, s1, 0x8000
	s_xor_b32 s10, s3, 0x8000
	v_or_b32_e32 v131, s3, v111
	v_add_u32_e32 v144, s3, v109
	s_waitcnt lgkmcnt(6)
	v_mfma_f32_16x16x32_bf16 v[0:3], v[92:95], v[174:177], v[0:3]
	ds_read_b128 v[132:135], v131 offset:16384
	s_add_i32 m0, s11, 0x3000
	s_add_u32 s8, s8, s13
	s_addc_u32 s9, s9, 0
	s_waitcnt lgkmcnt(6)
	v_mfma_f32_16x16x32_bf16 v[4:7], v[96:99], v[174:177], v[4:7]
	global_load_lds_dwordx4 v254, s[8:9]
	s_add_u32 s98, s98, 0x80
	s_addc_u32 s99, s99, 0
	ds_read_b128 v[136:139], v131 offset:16896
	s_waitcnt lgkmcnt(6)
	v_mfma_f32_16x16x32_bf16 v[8:11], v[100:103], v[174:177], v[8:11]
	ds_read_b128 v[140:143], v131 offset:20480
	s_waitcnt lgkmcnt(6)
	v_mfma_f32_16x16x32_bf16 v[12:15], v[104:107], v[174:177], v[12:15]
	ds_read_b128 v[170:173], v131 offset:20992
	ds_read_b128 v[174:177], v144
	s_add_i32 m0, s11, 0x4000
	s_nop 0
	s_waitcnt lgkmcnt(7)
	v_mfma_f32_16x16x32_bf16 v[16:19], v[92:95], v[178:181], v[16:19]
	global_load_lds_dwordx4 v255, s[100:101]
	v_mfma_f32_16x16x32_bf16 v[20:23], v[96:99], v[178:181], v[20:23]
	v_mfma_f32_16x16x32_bf16 v[24:27], v[100:103], v[178:181], v[24:27]
	s_add_i32 m0, s11, 0x5000
	s_add_u32 s8, s100, s13
	s_addc_u32 s9, s101, 0
	v_mfma_f32_16x16x32_bf16 v[28:31], v[104:107], v[178:181], v[28:31]
	global_load_lds_dwordx4 v255, s[8:9]
	ds_read_b128 v[178:181], v144 offset:2048
	s_waitcnt lgkmcnt(7)
	v_mfma_f32_16x16x32_bf16 v[32:35], v[92:95], v[246:249], v[32:35]
	v_mfma_f32_16x16x32_bf16 v[36:39], v[96:99], v[246:249], v[36:39]
	s_add_i32 m0, s11, 0x6000
	s_add_u32 s8, s8, s13
	s_addc_u32 s9, s9, 0
	v_mfma_f32_16x16x32_bf16 v[40:43], v[100:103], v[246:249], v[40:43]
	global_load_lds_dwordx4 v255, s[8:9]
	v_mfma_f32_16x16x32_bf16 v[44:47], v[104:107], v[246:249], v[44:47]
	ds_read_b128 v[246:249], v144 offset:4096
	s_waitcnt lgkmcnt(7)
	v_mfma_f32_16x16x32_bf16 v[48:51], v[92:95], v[250:253], v[48:51]
	s_add_i32 m0, s11, 0x7000
	s_add_u32 s8, s8, s13
	s_addc_u32 s9, s9, 0
	v_mfma_f32_16x16x32_bf16 v[52:55], v[96:99], v[250:253], v[52:55]
	global_load_lds_dwordx4 v255, s[8:9]
	s_add_u32 s100, s100, 0x80
	s_addc_u32 s101, s101, 0
	v_mfma_f32_16x16x32_bf16 v[56:59], v[100:103], v[250:253], v[56:59]
	v_mfma_f32_16x16x32_bf16 v[60:63], v[104:107], v[250:253], v[60:63]
	ds_read_b128 v[250:253], v144 offset:6144
	s_waitcnt lgkmcnt(3)
	v_mfma_f32_16x16x32_bf16 v[0:3], v[132:135], v[174:177], v[0:3]
	v_mfma_f32_16x16x32_bf16 v[4:7], v[136:139], v[174:177], v[4:7]
	v_mfma_f32_16x16x32_bf16 v[8:11], v[140:143], v[174:177], v[8:11]
	v_mfma_f32_16x16x32_bf16 v[12:15], v[170:173], v[174:177], v[12:15]
	s_waitcnt lgkmcnt(2)
	v_mfma_f32_16x16x32_bf16 v[16:19], v[132:135], v[178:181], v[16:19]
	v_mfma_f32_16x16x32_bf16 v[20:23], v[136:139], v[178:181], v[20:23]
	v_mfma_f32_16x16x32_bf16 v[24:27], v[140:143], v[178:181], v[24:27]
	v_mfma_f32_16x16x32_bf16 v[28:31], v[170:173], v[178:181], v[28:31]
	s_waitcnt vmcnt(0)
	s_waitcnt lgkmcnt(0)
	s_barrier
	s_add_i32 s1, s1, 0x8000
	s_cmp_eq_u32 s1, 0x78000
	s_cbranch_scc1 .Lgk_tail_895
	v_or_b32_e32 v131, s10, v110
	v_add_u32_e32 v144, s10, v108
	s_add_i32 s11, s3, s12
	ds_read_b128 v[174:177], v144
	ds_read_b128 v[92:95], v131 offset:16384
	s_mov_b32 m0, s11
	s_nop 0
	v_mfma_f32_16x16x32_bf16 v[32:35], v[132:135], v[246:249], v[32:35]
	global_load_lds_dwordx4 v254, s[98:99]
	ds_read_b128 v[96:99], v131 offset:16896
	v_mfma_f32_16x16x32_bf16 v[36:39], v[136:139], v[246:249], v[36:39]
	ds_read_b128 v[100:103], v131 offset:20480
	v_mfma_f32_16x16x32_bf16 v[40:43], v[140:143], v[246:249], v[40:43]
	ds_read_b128 v[104:107], v131 offset:20992
	s_add_i32 m0, s11, 0x1000
	s_add_u32 s8, s98, s13
	s_addc_u32 s9, s99, 0
	v_mfma_f32_16x16x32_bf16 v[44:47], v[170:173], v[246:249], v[44:47]
	global_load_lds_dwordx4 v254, s[8:9]
	ds_read_b128 v[178:181], v144 offset:2048
	ds_read_b128 v[246:249], v144 offset:4096
	v_mfma_f32_16x16x32_bf16 v[48:51], v[132:135], v[250:253], v[48:51]
	v_mfma_f32_16x16x32_bf16 v[52:55], v[136:139], v[250:253], v[52:55]
	s_add_i32 m0, s11, 0x2000
	s_add_u32 s8, s8, s13
	s_addc_u32 s9, s9, 0
	v_mfma_f32_16x16x32_bf16 v[56:59], v[140:143], v[250:253], v[56:59]
	global_load_lds_dwordx4 v254, s[8:9]
	v_mfma_f32_16x16x32_bf16 v[60:63], v[170:173], v[250:253], v[60:63]
	ds_read_b128 v[250:253], v144 offset:6144
	s_branch .Lgk_loop_895

; __device__ __forceinline__ u32x4 pack8(f32x4 a, f32x4 b) { u32x4 r; r.x = cvt_pk_bf16(a[0], a[1]); r.y = cvt_pk_bf16(a[2], a[3]); r.z = cvt_pk_bf16(b[0], b[1]); r.w = cvt_pk_bf16(b[2], b[3]); return r; }
; template <class Epi>
; __device__ __forceinline__ void gemm_tile(const bf16_t* __restrict__ A, const bf16_t* __restrict__ Bt, int K, int row0, int col0, const Epi& epi, char* smem,
;                                           bool prefetched, bool nvalid, int nrow0, int ncol0) {
;     ...
;     if constexpr (Epi::STAGED) {
;         bf16_t* st = (bf16_t*)(smem + 2 * TILE_B);
;         epi.to_lds(acc, st, row0, col0, wr, wc, fr, fq);
;         __syncthreads();
;     __device__ __forceinline__ void to_lds(f32x4 (&acc)[4][4], bf16_t* st, int row0, int col0, int wr, int wc, int fr, int fq) const {
; #pragma unroll
;         for (int m = 0; m < 4; ++m)
; #pragma unroll
;             for (int pp = 0; pp < 2; ++pp) {
;                 f32x4 v0 = acc[m][2 * pp], v1 = acc[m][2 * pp + 1];
; #pragma unroll
;                 for (int j = 0; j < 4; ++j) { const float u0 = fmaxf(v0[j], 0.f), u1 = fmaxf(v1[j], 0.f); v0[j] = u0 * u0; v1[j] = u1 * u1; }
;                 *(u32x4*)(st + (wr * 64 + m * 16 + fr) * 136 + wc * 64 + pp * 32 + 8 * fq) = pack8(v0, v1);
;             }
;     }
.LBB0_992:
	v_max_f32_e32 v48, v48, v48
	v_max_f32_e32 v52, v52, v52
	v_max_f32_e32 v49, v49, v49
	v_max_f32_e32 v53, v53, v53
	v_max_f32_e32 v50, v50, v50
	v_max_f32_e32 v54, v54, v54
	v_max_f32_e32 v51, v51, v51
	v_max_f32_e32 v55, v55, v55
	v_max_f32_e32 v48, 0, v48
	v_max_f32_e32 v52, 0, v52
	v_max_f32_e32 v49, 0, v49
	v_max_f32_e32 v53, 0, v53
	v_max_f32_e32 v50, 0, v50
	v_max_f32_e32 v54, 0, v54
	v_max_f32_e32 v51, 0, v51
	v_max_f32_e32 v55, 0, v55
	v_pk_mul_f32 v[48:49], v[48:49], v[48:49]
	v_pk_mul_f32 v[52:53], v[52:53], v[52:53]
	v_pk_mul_f32 v[50:51], v[50:51], v[50:51]
	v_pk_mul_f32 v[54:55], v[54:55], v[54:55]
	v_max_f32_e32 v40, v40, v40
	v_max_f32_e32 v41, v41, v41
	v_cvt_pk_bf16_f32 v48, v48, v49
	v_cvt_pk_bf16_f32 v49, v50, v51
	v_cvt_pk_bf16_f32 v50, v52, v53
	v_cvt_pk_bf16_f32 v51, v54, v55
	v_max_f32_e32 v40, 0, v40
	v_max_f32_e32 v41, 0, v41
	ds_write_b128 v141, v[48:51] offset:32832
	v_pk_mul_f32 v[48:49], v[40:41], v[40:41]
	v_max_f32_e32 v41, v42, v42
	v_max_f32_e32 v44, v44, v44
	v_max_f32_e32 v45, v45, v45
	v_max_f32_e32 v40, v46, v46
	v_max_f32_e32 v42, 0, v41
	v_max_f32_e32 v41, v47, v47
	v_max_f32_e32 v43, v43, v43
	v_max_f32_e32 v44, 0, v44
	v_max_f32_e32 v45, 0, v45
	v_max_f32_e32 v40, 0, v40
	v_max_f32_e32 v41, 0, v41
	v_max_f32_e32 v43, 0, v43
	v_pk_mul_f32 v[44:45], v[44:45], v[44:45]
	v_pk_mul_f32 v[46:47], v[40:41], v[40:41]
	v_pk_mul_f32 v[50:51], v[42:43], v[42:43]
	v_max_f32_e32 v32, v32, v32
	v_max_f32_e32 v33, v33, v33
	v_cvt_pk_bf16_f32 v40, v44, v45
	v_cvt_pk_bf16_f32 v41, v46, v47
	v_cvt_pk_bf16_f32 v42, v48, v49
	v_cvt_pk_bf16_f32 v43, v50, v51
	v_max_f32_e32 v32, 0, v32
	v_max_f32_e32 v33, 0, v33
	ds_write_b128 v141, v[40:43] offset:37120
	v_pk_mul_f32 v[40:41], v[32:33], v[32:33]
	v_max_f32_e32 v33, v34, v34
	v_max_f32_e32 v36, v36, v36
	v_max_f32_e32 v37, v37, v37
	v_max_f32_e32 v32, v38, v38
	v_max_f32_e32 v34, 0, v33
	v_max_f32_e32 v33, v39, v39
	v_max_f32_e32 v35, v35, v35
	v_max_f32_e32 v36, 0, v36
	v_max_f32_e32 v37, 0, v37
	v_max_f32_e32 v32, 0, v32
	v_max_f32_e32 v33, 0, v33
	v_max_f32_e32 v35, 0, v35
	v_pk_mul_f32 v[36:37], v[36:37], v[36:37]
	v_pk_mul_f32 v[38:39], v[32:33], v[32:33]
	v_pk_mul_f32 v[42:43], v[34:35], v[34:35]
	v_max_f32_e32 v24, v24, v24
	v_max_f32_e32 v25, v25, v25
	v_cvt_pk_bf16_f32 v32, v36, v37
	v_cvt_pk_bf16_f32 v33, v38, v39
	v_cvt_pk_bf16_f32 v34, v40, v41
	v_cvt_pk_bf16_f32 v35, v42, v43
	v_max_f32_e32 v24, 0, v24
	v_max_f32_e32 v25, 0, v25
	ds_write_b128 v141, v[32:35] offset:37184
	v_pk_mul_f32 v[32:33], v[24:25], v[24:25]
	v_max_f32_e32 v25, v26, v26
	v_max_f32_e32 v28, v28, v28
	v_max_f32_e32 v29, v29, v29
	v_max_f32_e32 v24, v30, v30
	v_max_f32_e32 v26, 0, v25
	v_max_f32_e32 v25, v31, v31
	v_max_f32_e32 v27, v27, v27
	v_max_f32_e32 v28, 0, v28
	v_max_f32_e32 v29, 0, v29
	v_max_f32_e32 v24, 0, v24
	v_max_f32_e32 v25, 0, v25
	v_max_f32_e32 v27, 0, v27
	v_pk_mul_f32 v[28:29], v[28:29], v[28:29]
	v_pk_mul_f32 v[30:31], v[24:25], v[24:25]
	v_pk_mul_f32 v[34:35], v[26:27], v[26:27]
	v_max_f32_e32 v16, v16, v16
	v_max_f32_e32 v17, v17, v17
	v_cvt_pk_bf16_f32 v24, v28, v29
	v_cvt_pk_bf16_f32 v25, v30, v31
	v_cvt_pk_bf16_f32 v26, v32, v33
	v_cvt_pk_bf16_f32 v27, v34, v35
	v_max_f32_e32 v16, 0, v16
	v_max_f32_e32 v17, 0, v17
	ds_write_b128 v141, v[24:27] offset:41472
	v_pk_mul_f32 v[24:25], v[16:17], v[16:17]
	v_max_f32_e32 v17, v18, v18
	v_max_f32_e32 v56, v56, v56
	v_max_f32_e32 v60, v60, v60
	v_max_f32_e32 v57, v57, v57
	v_max_f32_e32 v61, v61, v61
	v_max_f32_e32 v58, v58, v58
	v_max_f32_e32 v62, v62, v62
	v_max_f32_e32 v59, v59, v59
	v_max_f32_e32 v63, v63, v63
	v_max_f32_e32 v20, v20, v20
	v_max_f32_e32 v21, v21, v21
	v_max_f32_e32 v16, v22, v22
	v_max_f32_e32 v18, 0, v17
	v_max_f32_e32 v17, v23, v23
	v_max_f32_e32 v19, v19, v19
	v_max_f32_e32 v8, v8, v8
	v_max_f32_e32 v12, v12, v12
	v_max_f32_e32 v9, v9, v9
	v_max_f32_e32 v13, v13, v13
	v_max_f32_e32 v10, v10, v10
	v_max_f32_e32 v14, v14, v14
	v_max_f32_e32 v11, v11, v11
	v_max_f32_e32 v15, v15, v15
	v_max_f32_e32 v0, v0, v0
	v_max_f32_e32 v4, v4, v4
	v_max_f32_e32 v1, v1, v1
	v_max_f32_e32 v5, v5, v5
	v_max_f32_e32 v2, v2, v2
	v_max_f32_e32 v6, v6, v6
	v_max_f32_e32 v3, v3, v3
	v_max_f32_e32 v7, v7, v7
	v_max_f32_e32 v56, 0, v56
	v_max_f32_e32 v60, 0, v60
	v_max_f32_e32 v57, 0, v57
	v_max_f32_e32 v61, 0, v61
	v_max_f32_e32 v58, 0, v58
	v_max_f32_e32 v62, 0, v62
	v_max_f32_e32 v59, 0, v59
	v_max_f32_e32 v63, 0, v63
	v_max_f32_e32 v20, 0, v20
	v_max_f32_e32 v21, 0, v21
	v_max_f32_e32 v16, 0, v16
	v_max_f32_e32 v17, 0, v17
	v_max_f32_e32 v19, 0, v19
	v_max_f32_e32 v8, 0, v8
	v_max_f32_e32 v12, 0, v12
	v_max_f32_e32 v9, 0, v9
	v_max_f32_e32 v13, 0, v13
	v_max_f32_e32 v10, 0, v10
	v_max_f32_e32 v14, 0, v14
	v_max_f32_e32 v11, 0, v11
	v_max_f32_e32 v15, 0, v15
	v_max_f32_e32 v0, 0, v0
	v_max_f32_e32 v4, 0, v4
	v_max_f32_e32 v1, 0, v1
	v_max_f32_e32 v5, 0, v5
	v_max_f32_e32 v2, 0, v2
	v_max_f32_e32 v6, 0, v6
	v_max_f32_e32 v3, 0, v3
	v_max_f32_e32 v7, 0, v7
	v_pk_mul_f32 v[56:57], v[56:57], v[56:57]
	v_pk_mul_f32 v[60:61], v[60:61], v[60:61]
	v_pk_mul_f32 v[58:59], v[58:59], v[58:59]
	v_pk_mul_f32 v[62:63], v[62:63], v[62:63]
	v_pk_mul_f32 v[20:21], v[20:21], v[20:21]
	v_pk_mul_f32 v[22:23], v[16:17], v[16:17]
	v_pk_mul_f32 v[26:27], v[18:19], v[18:19]
	v_pk_mul_f32 v[8:9], v[8:9], v[8:9]
	v_pk_mul_f32 v[12:13], v[12:13], v[12:13]
	v_pk_mul_f32 v[10:11], v[10:11], v[10:11]
	v_pk_mul_f32 v[14:15], v[14:15], v[14:15]
	v_pk_mul_f32 v[0:1], v[0:1], v[0:1]
	v_pk_mul_f32 v[4:5], v[4:5], v[4:5]
	v_pk_mul_f32 v[2:3], v[2:3], v[2:3]
	v_pk_mul_f32 v[6:7], v[6:7], v[6:7]
	s_lshl_b64 s[0:1], s[0:1], 13
	v_readlane_b32 s8, v245, 55
	v_cvt_pk_bf16_f32 v56, v56, v57
	v_cvt_pk_bf16_f32 v57, v58, v59
	v_cvt_pk_bf16_f32 v58, v60, v61
	v_cvt_pk_bf16_f32 v59, v62, v63
	v_cvt_pk_bf16_f32 v16, v20, v21
	v_cvt_pk_bf16_f32 v17, v22, v23
	v_cvt_pk_bf16_f32 v18, v24, v25
	v_cvt_pk_bf16_f32 v19, v26, v27
	v_cvt_pk_bf16_f32 v8, v8, v9
	v_cvt_pk_bf16_f32 v9, v10, v11
	v_cvt_pk_bf16_f32 v10, v12, v13
	v_cvt_pk_bf16_f32 v11, v14, v15
	v_cvt_pk_bf16_f32 v0, v0, v1
	v_cvt_pk_bf16_f32 v1, v2, v3
	v_cvt_pk_bf16_f32 v2, v4, v5
	v_cvt_pk_bf16_f32 v3, v6, v7
	v_readlane_b32 s9, v245, 56
	s_add_u32 s8, s8, s0
	ds_write_b128 v141, v[56:59] offset:32768
	ds_write_b128 v141, v[16:19] offset:41536
	ds_write_b128 v141, v[8:11] offset:45824
	ds_write_b128 v141, v[0:3] offset:45888
	s_waitcnt lgkmcnt(0)
	s_barrier
; template <class Epi>
; __device__ __forceinline__ void gemm_tile(const bf16_t* __restrict__ A, const bf16_t* __restrict__ Bt, int K, int row0, int col0, const Epi& epi, char* smem,
;                                           bool prefetched, bool nvalid, int nrow0, int ncol0) {
;     ...
;         bf16_t* gbase; size_t gstride;
;         epi.dest(row0, col0, gbase, gstride);
;         const int r0 = tid >> 4, ch = (tid & 15) * 8;
; #pragma unroll
;         for (int it = 0; it < 8; ++it) { const int r = it * 16 + r0; __builtin_nontemporal_store(*(const u32x4*)(st + r * 136 + ch), (u32x4*)(gbase + (size_t)r * gstride + ch)); }
	s_addc_u32 s9, s9, s1
	s_lshl_b64 s[0:1], s[2:3], 1
	ds_read_b128 v[0:3], v142 offset:32768
	ds_read_b128 v[4:7], v142 offset:37120
	s_add_u32 s0, s8, s0
	s_addc_u32 s1, s9, s1
	v_lshl_add_u64 v[12:13], s[0:1], 0, v[72:73]
	v_lshl_add_u64 v[8:9], v[74:75], 1, v[12:13]
	s_waitcnt lgkmcnt(1)
	global_store_dwordx4 v[8:9], v[0:3], off nt
	ds_read_b128 v[0:3], v142 offset:41472
	v_lshl_add_u64 v[8:9], v[76:77], 1, v[12:13]
	s_waitcnt lgkmcnt(1)
	global_store_dwordx4 v[8:9], v[4:7], off nt
	ds_read_b128 v[4:7], v142 offset:45824
	v_lshl_add_u64 v[8:9], v[78:79], 1, v[12:13]
	s_waitcnt lgkmcnt(1)
	global_store_dwordx4 v[8:9], v[0:3], off nt
	ds_read_b128 v[0:3], v142 offset:50176
	v_lshl_add_u64 v[8:9], v[80:81], 1, v[12:13]
	s_waitcnt lgkmcnt(1)
	global_store_dwordx4 v[8:9], v[4:7], off nt
	v_lshl_add_u64 v[8:9], v[82:83], 1, v[12:13]
	ds_read_b128 v[4:7], v142 offset:54528
	s_waitcnt lgkmcnt(1)
	global_store_dwordx4 v[8:9], v[0:3], off nt
	ds_read_b128 v[0:3], v142 offset:58880
	ds_read_b128 v[8:11], v142 offset:63232
	v_lshl_add_u64 v[14:15], v[84:85], 1, v[12:13]
	s_waitcnt lgkmcnt(2)
	global_store_dwordx4 v[14:15], v[4:7], off nt
	s_andn2_b64 vcc, exec, s[6:7]
	s_mov_b64 s[10:11], -1
	v_lshl_add_u64 v[4:5], v[86:87], 1, v[12:13]
	s_waitcnt lgkmcnt(1)
	global_store_dwordx4 v[4:5], v[0:3], off nt
	s_nop 1
	v_lshl_add_u64 v[0:1], v[88:89], 1, v[12:13]
	s_waitcnt lgkmcnt(0)
	global_store_dwordx4 v[0:1], v[8:11], off nt
	s_cbranch_vccz .LBB0_1001

; __device__ __forceinline__ f32x4 zero4() { return (f32x4){0.f, 0.f, 0.f, 0.f}; }
; template <class Epi>
; __device__ __forceinline__ void gemm_tile(const bf16_t* __restrict__ A, const bf16_t* __restrict__ Bt, int K, int row0, int col0, const Epi& epi, char* smem,
;                                           bool prefetched, bool nvalid, int nrow0, int ncol0) {
;     ...
;     f32x4 acc[4][4];
; #pragma unroll
;     for (int m = 0; m < 4; ++m)
; #pragma unroll
;         for (int n = 0; n < 4; ++n) acc[m][n] = zero4();
;     int soffA[4], soffB[4];
; #pragma unroll
;     for (int i = 0; i < 4; ++i) {
;         const int row = (w + 4 * i) * 8 + (lane >> 3), cp = lane & 7;
;         soffA[i] = row * K + (cp ^ ((row >> 1) & 7)) * 8;
;         soffB[i] = row * K + (cp ^ (((row >> 1) & 1) | (((row >> 3) & 1) << 1) | (((row >> 4) & 1) << 2))) * 8;
;     }
;     const bf16_t* pA = A + (size_t)row0 * K;
;     const bf16_t* pB = Bt + (size_t)col0 * K;
;     ...
;     int offA[4][2], offB[4][2];
; #pragma unroll
;     for (int m = 0; m < 4; ++m)
; #pragma unroll
;         for (int ks = 0; ks < 2; ++ks) { const int cx = ((ks * 4 + fq) ^ ((fr >> 1) & 7)) * 16;
;             offA[m][ks] = (wr * 64 + m * 16 + fr) * 128 + cx;
;             offB[m][ks] = TILE_B + (wc * 64 + (m >> 1) * 32 + 8 * (fr >> 2) + 4 * (m & 1) + (fr & 3)) * 128 + cx; }
;     if (prefetched) {
;         if (Epi::STAGED) asm volatile("s_waitcnt vmcnt(8)" ::: "memory");
;         else asm volatile("s_waitcnt vmcnt(0)" ::: "memory");
;     } else {
;         GLDS_STAGE(0, pA, pB, 0);
;         asm volatile("s_waitcnt vmcnt(0)" ::: "memory");
;     }
;     __syncthreads();
;     const int nk = K >> 6;
;     for (int kt = 0; kt < nk; ++kt) {
;         const int cur = kt & 1;
;         if (kt + 1 < nk) GLDS_STAGE(cur ^ 1, pA, pB, kt + 1);
;         const char* cb = smem + cur * 2 * TILE_B;
; #pragma unroll
;         for (int ks = 0; ks < 2; ++ks) {
;             bf16x8 a[4], b[4];
; #pragma unroll
;             for (int m = 0; m < 4; ++m) a[m] = *(const bf16x8*)(cb + offA[m][ks]);
; #pragma unroll
;             for (int n = 0; n < 4; ++n) b[n] = *(const bf16x8*)(cb + offB[n][ks]);
.LBB0_997:
	v_mov_b32_e32 v0, 0
	v_lshl_add_u64 v[106:107], v[90:91], 0, s[6:7]
	v_lshl_add_u64 v[108:109], v[92:93], 0, s[6:7]
	v_lshl_add_u64 v[110:111], v[94:95], 0, s[6:7]
	v_lshl_add_u64 v[118:119], v[96:97], 0, s[6:7]
	v_lshl_add_u64 v[120:121], v[98:99], 0, s[8:9]
	v_lshl_add_u64 v[122:123], v[100:101], 0, s[8:9]
	v_lshl_add_u64 v[124:125], v[102:103], 0, s[8:9]
	v_lshl_add_u64 v[126:127], v[104:105], 0, s[8:9]
	s_mov_b32 s8, 0
	s_mov_b64 s[6:7], 0
	v_mov_b32_e32 v1, v0
	v_mov_b32_e32 v2, v0
	v_mov_b32_e32 v3, v0
	v_mov_b32_e32 v4, v0
	v_mov_b32_e32 v5, v0
	v_mov_b32_e32 v6, v0
	v_mov_b32_e32 v7, v0
	v_mov_b32_e32 v8, v0
	v_mov_b32_e32 v9, v0
	v_mov_b32_e32 v10, v0
	v_mov_b32_e32 v11, v0
	v_mov_b32_e32 v12, v0
	v_mov_b32_e32 v13, v0
	v_mov_b32_e32 v14, v0
	v_mov_b32_e32 v15, v0
	v_mov_b32_e32 v16, v0
	v_mov_b32_e32 v17, v0
	v_mov_b32_e32 v18, v0
	v_mov_b32_e32 v19, v0
	v_mov_b32_e32 v20, v0
	v_mov_b32_e32 v21, v0
	v_mov_b32_e32 v22, v0
	v_mov_b32_e32 v23, v0
	v_mov_b32_e32 v24, v0
	v_mov_b32_e32 v25, v0
	v_mov_b32_e32 v26, v0
	v_mov_b32_e32 v27, v0
	v_mov_b32_e32 v28, v0
	v_mov_b32_e32 v29, v0
	v_mov_b32_e32 v30, v0
	v_mov_b32_e32 v31, v0
	v_mov_b32_e32 v32, v0
	v_mov_b32_e32 v33, v0
	v_mov_b32_e32 v34, v0
	v_mov_b32_e32 v35, v0
	v_mov_b32_e32 v36, v0
	v_mov_b32_e32 v37, v0
	v_mov_b32_e32 v38, v0
	v_mov_b32_e32 v39, v0
	v_mov_b32_e32 v40, v0
	v_mov_b32_e32 v41, v0
	v_mov_b32_e32 v42, v0
	v_mov_b32_e32 v43, v0
	v_mov_b32_e32 v44, v0
	v_mov_b32_e32 v45, v0
	v_mov_b32_e32 v46, v0
	v_mov_b32_e32 v47, v0
	v_mov_b32_e32 v48, v0
	v_mov_b32_e32 v49, v0
	v_mov_b32_e32 v50, v0
	v_mov_b32_e32 v51, v0
	v_mov_b32_e32 v52, v0
	v_mov_b32_e32 v53, v0
	v_mov_b32_e32 v54, v0
	v_mov_b32_e32 v55, v0
	v_mov_b32_e32 v56, v0
	v_mov_b32_e32 v57, v0
	v_mov_b32_e32 v58, v0
	v_mov_b32_e32 v59, v0
	v_mov_b32_e32 v60, v0
	v_mov_b32_e32 v61, v0
	v_mov_b32_e32 v62, v0
	v_mov_b32_e32 v63, v0
	s_waitcnt lgkmcnt(0)
	s_barrier
.LBB0_998:
	v_readfirstlane_b32 s98, v106
	v_readfirstlane_b32 s99, v107
	v_readfirstlane_b32 s10, v108
	v_readfirstlane_b32 s100, v120
	v_readfirstlane_b32 s101, v121
	v_readfirstlane_b32 s17, v149
	s_nop 3
	s_sub_u32 s18, s10, s98
	s_and_b32 s98, s98, 0xffffff80
	s_and_b32 s100, s100, 0xffffff80
	s_nop 1
	v_subrev_u32_e32 v254, s98, v106
	v_subrev_u32_e32 v255, s100, v120
	s_add_i32 s13, s17, 0x8000
	s_mov_b32 m0, s13
	s_nop 0
	global_load_lds_dwordx4 v254, s[98:99]
	s_add_i32 m0, s13, 0x1000
	s_add_u32 s10, s98, s18
	s_addc_u32 s11, s99, 0
	global_load_lds_dwordx4 v254, s[10:11]
	s_add_i32 m0, s13, 0x2000
	s_add_u32 s10, s10, s18
	s_addc_u32 s11, s11, 0
	global_load_lds_dwordx4 v254, s[10:11]
	ds_read_b128 v[184:187], v130
	ds_read_b128 v[106:109], v133 offset:16384
	ds_read_b128 v[118:121], v133 offset:16896
	ds_read_b128 v[122:125], v133 offset:20480
	ds_read_b128 v[158:161], v133 offset:20992
	ds_read_b128 v[188:191], v130 offset:2048
	ds_read_b128 v[246:249], v130 offset:4096
	ds_read_b128 v[250:253], v130 offset:6144
; __device__ __forceinline__ f32x4 mfma16(bf16x8 a, bf16x8 b, f32x4 c) { return __builtin_amdgcn_mfma_f32_16x16x32_bf16(a, b, c, 0, 0, 0); }
; template <class Epi>
; __device__ __forceinline__ void gemm_tile(const bf16_t* __restrict__ A, const bf16_t* __restrict__ Bt, int K, int row0, int col0, const Epi& epi, char* smem,
;                                           bool prefetched, bool nvalid, int nrow0, int ncol0) {
;     ...
;     for (int kt = 0; kt < nk; ++kt) {
;         const int cur = kt & 1;
;         if (kt + 1 < nk) GLDS_STAGE(cur ^ 1, pA, pB, kt + 1);
;         const char* cb = smem + cur * 2 * TILE_B;
; #pragma unroll
;         for (int ks = 0; ks < 2; ++ks) {
;             bf16x8 a[4], b[4];
; #pragma unroll
;             for (int m = 0; m < 4; ++m) a[m] = *(const bf16x8*)(cb + offA[m][ks]);
; #pragma unroll
;             for (int n = 0; n < 4; ++n) b[n] = *(const bf16x8*)(cb + offB[n][ks]);
; #pragma unroll
;             for (int m = 0; m < 4; ++m)
; #pragma unroll
;                 for (int n = 0; n < 4; ++n) acc[m][n] = mfma16(b[n], a[m], acc[m][n]);
;         }
;         asm volatile("s_waitcnt vmcnt(0)" ::: "memory");
;         __syncthreads();
.Lgk_loop_998:
	s_and_b32 s9, s8, 0x8000
	s_xor_b32 s12, s9, 0x8000
	v_or_b32_e32 v167, s9, v132
	v_add_u32_e32 v110, s9, v131
	s_waitcnt lgkmcnt(6)
	v_mfma_f32_16x16x32_bf16 v[0:3], v[106:109], v[184:187], v[0:3]
	ds_read_b128 v[168:171], v167 offset:16384
	s_add_i32 m0, s13, 0x3000
	s_add_u32 s10, s10, s18
	s_addc_u32 s11, s11, 0
	s_waitcnt lgkmcnt(6)
	v_mfma_f32_16x16x32_bf16 v[4:7], v[118:121], v[184:187], v[4:7]
	global_load_lds_dwordx4 v254, s[10:11]
	s_add_u32 s98, s98, 0x80
	s_addc_u32 s99, s99, 0
	ds_read_b128 v[172:175], v167 offset:16896
	s_waitcnt lgkmcnt(6)
	v_mfma_f32_16x16x32_bf16 v[8:11], v[122:125], v[184:187], v[8:11]
	ds_read_b128 v[176:179], v167 offset:20480
	s_waitcnt lgkmcnt(6)
	v_mfma_f32_16x16x32_bf16 v[12:15], v[158:161], v[184:187], v[12:15]
	ds_read_b128 v[180:183], v167 offset:20992
	ds_read_b128 v[184:187], v110
	s_add_i32 m0, s13, 0x4000
	s_nop 0
	s_waitcnt lgkmcnt(7)
	v_mfma_f32_16x16x32_bf16 v[16:19], v[106:109], v[188:191], v[16:19]
	global_load_lds_dwordx4 v255, s[100:101]
	v_mfma_f32_16x16x32_bf16 v[20:23], v[118:121], v[188:191], v[20:23]
	v_mfma_f32_16x16x32_bf16 v[24:27], v[122:125], v[188:191], v[24:27]
	s_add_i32 m0, s13, 0x5000
	s_add_u32 s10, s100, s18
	s_addc_u32 s11, s101, 0
	v_mfma_f32_16x16x32_bf16 v[28:31], v[158:161], v[188:191], v[28:31]
	global_load_lds_dwordx4 v255, s[10:11]
	ds_read_b128 v[188:191], v110 offset:2048
	s_waitcnt lgkmcnt(7)
	v_mfma_f32_16x16x32_bf16 v[32:35], v[106:109], v[246:249], v[32:35]
	v_mfma_f32_16x16x32_bf16 v[36:39], v[118:121], v[246:249], v[36:39]
	s_add_i32 m0, s13, 0x6000
	s_add_u32 s10, s10, s18
	s_addc_u32 s11, s11, 0
	v_mfma_f32_16x16x32_bf16 v[40:43], v[122:125], v[246:249], v[40:43]
	global_load_lds_dwordx4 v255, s[10:11]
	v_mfma_f32_16x16x32_bf16 v[44:47], v[158:161], v[246:249], v[44:47]
	ds_read_b128 v[246:249], v110 offset:4096
	s_waitcnt lgkmcnt(7)
	v_mfma_f32_16x16x32_bf16 v[48:51], v[106:109], v[250:253], v[48:51]
	s_add_i32 m0, s13, 0x7000
	s_add_u32 s10, s10, s18
	s_addc_u32 s11, s11, 0
	v_mfma_f32_16x16x32_bf16 v[52:55], v[118:121], v[250:253], v[52:55]
	global_load_lds_dwordx4 v255, s[10:11]
	s_add_u32 s100, s100, 0x80
	s_addc_u32 s101, s101, 0
	v_mfma_f32_16x16x32_bf16 v[56:59], v[122:125], v[250:253], v[56:59]
	v_mfma_f32_16x16x32_bf16 v[60:63], v[158:161], v[250:253], v[60:63]
	ds_read_b128 v[250:253], v110 offset:6144
	s_waitcnt lgkmcnt(3)
	v_mfma_f32_16x16x32_bf16 v[0:3], v[168:171], v[184:187], v[0:3]
	v_mfma_f32_16x16x32_bf16 v[4:7], v[172:175], v[184:187], v[4:7]
	v_mfma_f32_16x16x32_bf16 v[8:11], v[176:179], v[184:187], v[8:11]
	v_mfma_f32_16x16x32_bf16 v[12:15], v[180:183], v[184:187], v[12:15]
	s_waitcnt lgkmcnt(2)
	v_mfma_f32_16x16x32_bf16 v[16:19], v[168:171], v[188:191], v[16:19]
	v_mfma_f32_16x16x32_bf16 v[20:23], v[172:175], v[188:191], v[20:23]
	v_mfma_f32_16x16x32_bf16 v[24:27], v[176:179], v[188:191], v[24:27]
	v_mfma_f32_16x16x32_bf16 v[28:31], v[180:183], v[188:191], v[28:31]
	s_waitcnt vmcnt(0)
	s_waitcnt lgkmcnt(0)
	s_barrier
	s_add_i32 s8, s8, 0x8000
	s_cmp_eq_u32 s8, 0x78000
	s_cbranch_scc1 .Lgk_tail_998
	v_or_b32_e32 v167, s12, v133
	v_add_u32_e32 v110, s12, v130
	s_add_i32 s13, s9, s17
	ds_read_b128 v[184:187], v110
	ds_read_b128 v[106:109], v167 offset:16384
	s_mov_b32 m0, s13
	s_nop 0
	v_mfma_f32_16x16x32_bf16 v[32:35], v[168:171], v[246:249], v[32:35]
	global_load_lds_dwordx4 v254, s[98:99]
	ds_read_b128 v[118:121], v167 offset:16896
	v_mfma_f32_16x16x32_bf16 v[36:39], v[172:175], v[246:249], v[36:39]
	ds_read_b128 v[122:125], v167 offset:20480
	v_mfma_f32_16x16x32_bf16 v[40:43], v[176:179], v[246:249], v[40:43]
	ds_read_b128 v[158:161], v167 offset:20992
	s_add_i32 m0, s13, 0x1000
	s_add_u32 s10, s98, s18
	s_addc_u32 s11, s99, 0
	v_mfma_f32_16x16x32_bf16 v[44:47], v[180:183], v[246:249], v[44:47]
	global_load_lds_dwordx4 v254, s[10:11]
	ds_read_b128 v[188:191], v110 offset:2048
	ds_read_b128 v[246:249], v110 offset:4096
	v_mfma_f32_16x16x32_bf16 v[48:51], v[168:171], v[250:253], v[48:51]
	v_mfma_f32_16x16x32_bf16 v[52:55], v[172:175], v[250:253], v[52:55]
	s_add_i32 m0, s13, 0x2000
	s_add_u32 s10, s10, s18
	s_addc_u32 s11, s11, 0
	v_mfma_f32_16x16x32_bf16 v[56:59], v[176:179], v[250:253], v[56:59]
	global_load_lds_dwordx4 v254, s[10:11]
	v_mfma_f32_16x16x32_bf16 v[60:63], v[180:183], v[250:253], v[60:63]
	ds_read_b128 v[250:253], v110 offset:6144
	s_branch .Lgk_loop_998

; __device__ __forceinline__ f32x4 mfma16(bf16x8 a, bf16x8 b, f32x4 c) { return __builtin_amdgcn_mfma_f32_16x16x32_bf16(a, b, c, 0, 0, 0); }
; template <class Epi>
; __device__ __forceinline__ void gemm_tile(const bf16_t* __restrict__ A, const bf16_t* __restrict__ Bt, int K, int row0, int col0, const Epi& epi, char* smem,
;                                           bool prefetched, bool nvalid, int nrow0, int ncol0) {
;     ...
;     for (int kt = 0; kt < nk; ++kt) {
;         const int cur = kt & 1;
;         if (kt + 1 < nk) GLDS_STAGE(cur ^ 1, pA, pB, kt + 1);
;         const char* cb = smem + cur * 2 * TILE_B;
; #pragma unroll
;         for (int ks = 0; ks < 2; ++ks) {
;             bf16x8 a[4], b[4];
; #pragma unroll
;             for (int m = 0; m < 4; ++m) a[m] = *(const bf16x8*)(cb + offA[m][ks]);
; #pragma unroll
;             for (int n = 0; n < 4; ++n) b[n] = *(const bf16x8*)(cb + offB[n][ks]);
; #pragma unroll
;             for (int m = 0; m < 4; ++m)
; #pragma unroll
;                 for (int n = 0; n < 4; ++n) acc[m][n] = mfma16(b[n], a[m], acc[m][n]);
;         }
;         asm volatile("s_waitcnt vmcnt(0)" ::: "memory");
;         __syncthreads();
.LBB0_1054:
	v_readfirstlane_b32 s98, v92
	v_readfirstlane_b32 s99, v93
	v_readfirstlane_b32 s6, v94
	v_readfirstlane_b32 s100, v100
	v_readfirstlane_b32 s101, v101
	v_readfirstlane_b32 s10, v149
	s_nop 3
	s_sub_u32 s11, s6, s98
	s_and_b32 s98, s98, 0xffffff80
	s_and_b32 s100, s100, 0xffffff80
	s_nop 1
	v_subrev_u32_e32 v254, s98, v92
	v_subrev_u32_e32 v255, s100, v100
	s_add_i32 s9, s10, 0x8000
	s_mov_b32 m0, s9
	s_nop 0
	global_load_lds_dwordx4 v254, s[98:99]
	s_add_i32 m0, s9, 0x1000
	s_add_u32 s6, s98, s11
	s_addc_u32 s7, s99, 0
	global_load_lds_dwordx4 v254, s[6:7]
	s_add_i32 m0, s9, 0x2000
	s_add_u32 s6, s6, s11
	s_addc_u32 s7, s7, 0
	global_load_lds_dwordx4 v254, s[6:7]
	ds_read_b128 v[150:153], v108
	ds_read_b128 v[92:95], v110 offset:16384
	ds_read_b128 v[96:99], v110 offset:16896
	ds_read_b128 v[100:103], v110 offset:20480
	ds_read_b128 v[104:107], v110 offset:20992
	ds_read_b128 v[154:157], v108 offset:2048
	ds_read_b128 v[246:249], v108 offset:4096
	ds_read_b128 v[250:253], v108 offset:6144
.Lgk_loop_1054:
	s_and_b32 s3, s1, 0x8000
	s_xor_b32 s8, s3, 0x8000
	v_or_b32_e32 v127, s3, v111
	v_add_u32_e32 v144, s3, v109
	s_waitcnt lgkmcnt(6)
	v_mfma_f32_16x16x32_bf16 v[0:3], v[92:95], v[150:153], v[0:3]
	ds_read_b128 v[128:131], v127 offset:16384
	s_add_i32 m0, s9, 0x3000
	s_add_u32 s6, s6, s11
	s_addc_u32 s7, s7, 0
	s_waitcnt lgkmcnt(6)
	v_mfma_f32_16x16x32_bf16 v[4:7], v[96:99], v[150:153], v[4:7]
	global_load_lds_dwordx4 v254, s[6:7]
	s_add_u32 s98, s98, 0x80
	s_addc_u32 s99, s99, 0
	ds_read_b128 v[132:135], v127 offset:16896
	s_waitcnt lgkmcnt(6)
	v_mfma_f32_16x16x32_bf16 v[8:11], v[100:103], v[150:153], v[8:11]
	ds_read_b128 v[136:139], v127 offset:20480
	s_waitcnt lgkmcnt(6)
	v_mfma_f32_16x16x32_bf16 v[12:15], v[104:107], v[150:153], v[12:15]
	ds_read_b128 v[140:143], v127 offset:20992
	ds_read_b128 v[150:153], v144
	s_add_i32 m0, s9, 0x4000
	s_nop 0
	s_waitcnt lgkmcnt(7)
	v_mfma_f32_16x16x32_bf16 v[16:19], v[92:95], v[154:157], v[16:19]
	global_load_lds_dwordx4 v255, s[100:101]
	v_mfma_f32_16x16x32_bf16 v[20:23], v[96:99], v[154:157], v[20:23]
	v_mfma_f32_16x16x32_bf16 v[24:27], v[100:103], v[154:157], v[24:27]
	s_add_i32 m0, s9, 0x5000
	s_add_u32 s6, s100, s11
	s_addc_u32 s7, s101, 0
	v_mfma_f32_16x16x32_bf16 v[28:31], v[104:107], v[154:157], v[28:31]
	global_load_lds_dwordx4 v255, s[6:7]
	ds_read_b128 v[154:157], v144 offset:2048
	s_waitcnt lgkmcnt(7)
	v_mfma_f32_16x16x32_bf16 v[32:35], v[92:95], v[246:249], v[32:35]
	v_mfma_f32_16x16x32_bf16 v[36:39], v[96:99], v[246:249], v[36:39]
	s_add_i32 m0, s9, 0x6000
	s_add_u32 s6, s6, s11
	s_addc_u32 s7, s7, 0
	v_mfma_f32_16x16x32_bf16 v[40:43], v[100:103], v[246:249], v[40:43]
	global_load_lds_dwordx4 v255, s[6:7]
	v_mfma_f32_16x16x32_bf16 v[44:47], v[104:107], v[246:249], v[44:47]
	ds_read_b128 v[246:249], v144 offset:4096
	s_waitcnt lgkmcnt(7)
	v_mfma_f32_16x16x32_bf16 v[48:51], v[92:95], v[250:253], v[48:51]
	s_add_i32 m0, s9, 0x7000
	s_add_u32 s6, s6, s11
	s_addc_u32 s7, s7, 0
	v_mfma_f32_16x16x32_bf16 v[52:55], v[96:99], v[250:253], v[52:55]
	global_load_lds_dwordx4 v255, s[6:7]
	s_add_u32 s100, s100, 0x80
	s_addc_u32 s101, s101, 0
	v_mfma_f32_16x16x32_bf16 v[56:59], v[100:103], v[250:253], v[56:59]
	v_mfma_f32_16x16x32_bf16 v[60:63], v[104:107], v[250:253], v[60:63]
	ds_read_b128 v[250:253], v144 offset:6144
	s_waitcnt lgkmcnt(3)
	v_mfma_f32_16x16x32_bf16 v[0:3], v[128:131], v[150:153], v[0:3]
	v_mfma_f32_16x16x32_bf16 v[4:7], v[132:135], v[150:153], v[4:7]
	v_mfma_f32_16x16x32_bf16 v[8:11], v[136:139], v[150:153], v[8:11]
	v_mfma_f32_16x16x32_bf16 v[12:15], v[140:143], v[150:153], v[12:15]
	s_waitcnt lgkmcnt(2)
	v_mfma_f32_16x16x32_bf16 v[16:19], v[128:131], v[154:157], v[16:19]
	v_mfma_f32_16x16x32_bf16 v[20:23], v[132:135], v[154:157], v[20:23]
	v_mfma_f32_16x16x32_bf16 v[24:27], v[136:139], v[154:157], v[24:27]
	v_mfma_f32_16x16x32_bf16 v[28:31], v[140:143], v[154:157], v[28:31]
	s_waitcnt vmcnt(0)
	s_waitcnt lgkmcnt(0)
	s_barrier
	s_add_i32 s1, s1, 0x8000
	s_cmp_eq_u32 s1, 0x1f8000
	s_cbranch_scc1 .Lgk_tail_1054
	v_or_b32_e32 v127, s8, v110
	v_add_u32_e32 v144, s8, v108
	s_add_i32 s9, s3, s10
	ds_read_b128 v[150:153], v144
	ds_read_b128 v[92:95], v127 offset:16384
	s_mov_b32 m0, s9
	s_nop 0
	v_mfma_f32_16x16x32_bf16 v[32:35], v[128:131], v[246:249], v[32:35]
	global_load_lds_dwordx4 v254, s[98:99]
	ds_read_b128 v[96:99], v127 offset:16896
	v_mfma_f32_16x16x32_bf16 v[36:39], v[132:135], v[246:249], v[36:39]
	ds_read_b128 v[100:103], v127 offset:20480
	v_mfma_f32_16x16x32_bf16 v[40:43], v[136:139], v[246:249], v[40:43]
	ds_read_b128 v[104:107], v127 offset:20992
	s_add_i32 m0, s9, 0x1000
	s_add_u32 s6, s98, s11
	s_addc_u32 s7, s99, 0
	v_mfma_f32_16x16x32_bf16 v[44:47], v[140:143], v[246:249], v[44:47]
	global_load_lds_dwordx4 v254, s[6:7]
	ds_read_b128 v[154:157], v144 offset:2048
	ds_read_b128 v[246:249], v144 offset:4096
	v_mfma_f32_16x16x32_bf16 v[48:51], v[128:131], v[250:253], v[48:51]
	v_mfma_f32_16x16x32_bf16 v[52:55], v[132:135], v[250:253], v[52:55]
	s_add_i32 m0, s9, 0x2000
	s_add_u32 s6, s6, s11
	s_addc_u32 s7, s7, 0
	v_mfma_f32_16x16x32_bf16 v[56:59], v[136:139], v[250:253], v[56:59]
	global_load_lds_dwordx4 v254, s[6:7]
	v_mfma_f32_16x16x32_bf16 v[60:63], v[140:143], v[250:253], v[60:63]
	ds_read_b128 v[250:253], v144 offset:6144
	s_branch .Lgk_loop_1054
